# MLA-projection epilogue: the 8 row rstd pairs preloaded once per tile (8 dwordx2 in flight) instead of one load+wait per 16x32 block
# speedup vs baseline: 1.0033x; 1.0028x over previous
; #define PG8_STAGE(bufoff, gbase, voff) do { _Pragma("unroll") for (int _i = 0; _i < 2; ++_i) \
;         __builtin_amdgcn_global_load_lds((const unsigned*)((const char*)(gbase) + (voff)[_i]), (LAS unsigned*)(lds + (bufoff) + ldsw + _i * 8192), 16, 0, 0); } while (0)
; #define PG8_LDA(dst, b, h) do { _Pragma("unroll") for (int m = 0; m < 4; ++m) _Pragma("unroll") for (int k = 0; k < 2; ++k) dst[m][k] = *(const LAS bf16x8*)(lds + PG8_SA(b, h) + aoff + m * 2048 + k * 1024); } while (0)
; #define PG8_WAIT_V(n) asm volatile("s_waitcnt vmcnt(" #n ")" ::: "memory")
; #define PG8_WAIT_L(n) asm volatile("s_waitcnt lgkmcnt(" #n ")" ::: "memory")
; template <class Epi, class Sched>
; __device__ __forceinline__ void gemm_phase(LAS unsigned char* lds, const Gemm g, const Sched& S, const Epi& E) {
;     ...
;         for (int t = 0; t < nt; t += 2) {
;             const bool last = (t == nt - 2);
;             const char* a1 = cA + (size_t)(t + 1) * kstep;
;             const char* a2 = last ? nA : cA + (size_t)(t + 2) * kstep; const char* b2 = last ? nB : cB + (size_t)(t + 2) * kstep;
;             const char* a3 = a2 + kstep; const char* b3 = b2 + kstep;
;             PG8_LDB(B0, 0, 0); PG8_SCHED; PG8_LDA(At, 0, 0); PG8_STAGE(PG8_SA(1, 1), a1 + hstepA, voffA);
;             PG8_WAIT_L(8); PG8_BAR; PG8_WAIT_L(0); PG8_MMA(0, 0, At, B0); PG8_BAR; PG8_SCHED;
;             PG8_LDB(B1, 0, 1); PG8_STAGE(PG8_SB(0, 0), b2, voffB);
;             PG8_BAR; PG8_WAIT_L(0); PG8_MMA(0, 1, At, B1); PG8_BAR;
;             PG8_LDA(At, 0, 1); PG8_STAGE(PG8_SA(0, 0), a2, voffA);
;             PG8_BAR; PG8_WAIT_L(0); PG8_MMA(1, 0, At, B0); PG8_BAR; PG8_SCHED;
;             PG8_STAGE(PG8_SB(0, 1), b2 + hstepB, voffB);
;             PG8_WAIT_V(6); PG8_BAR; PG8_MMA(1, 1, At, B1); PG8_BAR;
;             PG8_LDB(B0, 1, 0); PG8_SCHED; PG8_LDA(At, 1, 0); PG8_STAGE(PG8_SA(0, 1), a2 + hstepA, voffA);
;             PG8_WAIT_L(8); PG8_BAR; PG8_WAIT_L(0); PG8_MMA(0, 0, At, B0); PG8_BAR; PG8_SCHED;
;             PG8_LDB(B1, 1, 1); PG8_STAGE(PG8_SB(1, 0), b3, voffB);
;             PG8_BAR; PG8_WAIT_L(0); PG8_MMA(0, 1, At, B1); PG8_BAR;
;             PG8_LDA(At, 1, 1); PG8_STAGE(PG8_SA(1, 0), a3, voffA);
;             PG8_BAR; PG8_WAIT_L(0); PG8_MMA(1, 0, At, B0); PG8_BAR; PG8_SCHED;
;             PG8_STAGE(PG8_SB(1, 1), b3 + hstepB, voffB);
;             PG8_WAIT_V(6); PG8_BAR; PG8_MMA(1, 1, At, B1); PG8_BAR;
.LBB0_304:
	s_add_i32 s7, 0, 0x10000
	v_add_u32_e32 v10, s7, v1
	ds_read_b128 v[12:15], v10
	ds_read_b128 v[16:19], v10 offset:1024
	ds_read_b128 v[20:23], v10 offset:2048
	ds_read_b128 v[24:27], v10 offset:3072
	s_add_u32 s0, s2, 0x90080
	s_addc_u32 s1, s3, 0
	s_add_i32 s14, s45, 0xc000
	v_lshl_add_u64 v[2:3], s[0:1], 0, v[134:135]
	s_mov_b32 m0, s14
	ds_read_b128 v[6:9], v152
	ds_read_b128 v[28:31], v152 offset:1024
	ds_read_b128 v[32:35], v152 offset:2048
	ds_read_b128 v[36:39], v152 offset:3072
	ds_read_b128 v[40:43], v152 offset:4096
	ds_read_b128 v[44:47], v152 offset:5120
	ds_read_b128 v[48:51], v152 offset:6144
	ds_read_b128 v[52:55], v152 offset:7168
	global_load_lds_dwordx4 v[2:3], off
	v_lshl_add_u64 v[2:3], s[0:1], 0, v[138:139]
	s_add_i32 s0, s45, 0xe000
	s_mov_b32 m0, s0
	s_nop 0
	global_load_lds_dwordx4 v[2:3], off
	s_waitcnt lgkmcnt(8)
	s_barrier
	s_waitcnt lgkmcnt(0)
	s_setprio 1
	s_waitcnt lgkmcnt(0)
	v_mfma_f32_16x16x32_bf16 v[2:5], v[12:15], v[6:9], 0
	v_mfma_f32_16x16x32_bf16 v[56:59], v[16:19], v[28:31], v[2:5]
	v_mfma_f32_16x16x32_bf16 v[2:5], v[20:23], v[6:9], 0
	v_mfma_f32_16x16x32_bf16 v[60:63], v[24:27], v[28:31], v[2:5]
	v_mfma_f32_16x16x32_bf16 v[2:5], v[12:15], v[32:35], 0
	v_mfma_f32_16x16x32_bf16 v[64:67], v[16:19], v[36:39], v[2:5]
	v_mfma_f32_16x16x32_bf16 v[2:5], v[20:23], v[32:35], 0
	v_mfma_f32_16x16x32_bf16 v[68:71], v[24:27], v[36:39], v[2:5]
	v_mfma_f32_16x16x32_bf16 v[2:5], v[12:15], v[40:43], 0
	v_mfma_f32_16x16x32_bf16 v[72:75], v[16:19], v[44:47], v[2:5]
	v_mfma_f32_16x16x32_bf16 v[2:5], v[20:23], v[40:43], 0
	v_mfma_f32_16x16x32_bf16 v[76:79], v[24:27], v[44:47], v[2:5]
	v_mfma_f32_16x16x32_bf16 v[2:5], v[12:15], v[48:51], 0
	v_mfma_f32_16x16x32_bf16 v[80:83], v[16:19], v[52:55], v[2:5]
	v_mfma_f32_16x16x32_bf16 v[2:5], v[20:23], v[48:51], 0
	v_mfma_f32_16x16x32_bf16 v[84:87], v[24:27], v[52:55], v[2:5]
	s_setprio 0
	s_barrier
	s_add_i32 s8, 0, 0x14000
	s_nop 3
	v_lshl_add_u64 v[2:3], s[10:11], 0, v[136:137]
	s_mov_b64 s[34:35], 0x100
	s_add_i32 s7, s7, s44
	v_add_u32_e32 v11, s8, v1
	v_lshl_add_u64 v[4:5], v[2:3], 0, s[34:35]
	s_mov_b32 m0, s7
	ds_read_b128 v[88:91], v11
	ds_read_b128 v[92:95], v11 offset:1024
	ds_read_b128 v[96:99], v11 offset:2048
	ds_read_b128 v[100:103], v11 offset:3072
	global_load_lds_dwordx4 v[4:5], off
	v_lshl_add_u64 v[4:5], s[10:11], 0, v[140:141]
	s_add_i32 s1, s7, 0x2000
	v_lshl_add_u64 v[104:105], v[4:5], 0, s[34:35]
	s_mov_b32 m0, s1
	s_nop 0
	global_load_lds_dwordx4 v[104:105], off
	s_barrier
	s_waitcnt lgkmcnt(0)
	s_setprio 1
	s_waitcnt lgkmcnt(0)
	v_mfma_f32_16x16x32_bf16 v[104:107], v[88:91], v[6:9], 0
	v_mfma_f32_16x16x32_bf16 v[6:9], v[96:99], v[6:9], 0
	v_mfma_f32_16x16x32_bf16 v[104:107], v[92:95], v[28:31], v[104:107]
	v_mfma_f32_16x16x32_bf16 v[28:31], v[100:103], v[28:31], v[6:9]
	v_mfma_f32_16x16x32_bf16 v[6:9], v[88:91], v[32:35], 0
	v_mfma_f32_16x16x32_bf16 v[108:111], v[92:95], v[36:39], v[6:9]
	v_mfma_f32_16x16x32_bf16 v[6:9], v[96:99], v[32:35], 0
	v_mfma_f32_16x16x32_bf16 v[32:35], v[100:103], v[36:39], v[6:9]
	v_mfma_f32_16x16x32_bf16 v[6:9], v[88:91], v[40:43], 0
	v_mfma_f32_16x16x32_bf16 v[36:39], v[92:95], v[44:47], v[6:9]
	v_mfma_f32_16x16x32_bf16 v[6:9], v[96:99], v[40:43], 0
	v_mfma_f32_16x16x32_bf16 v[40:43], v[100:103], v[44:47], v[6:9]
	v_mfma_f32_16x16x32_bf16 v[6:9], v[88:91], v[48:51], 0
	v_mfma_f32_16x16x32_bf16 v[44:47], v[92:95], v[52:55], v[6:9]
	v_mfma_f32_16x16x32_bf16 v[6:9], v[96:99], v[48:51], 0
	v_mfma_f32_16x16x32_bf16 v[48:51], v[100:103], v[52:55], v[6:9]
	s_setprio 0
	s_nop 5
	v_lshl_add_u64 v[6:7], s[2:3], 0, v[134:135]
	s_mov_b32 m0, s45
	v_lshl_add_u64 v[8:9], v[6:7], 0, s[34:35]
	s_barrier
	ds_read_b128 v[52:55], v152 offset:16384
	ds_read_b128 v[112:115], v152 offset:17408
	ds_read_b128 v[116:119], v152 offset:18432
	ds_read_b128 v[120:123], v152 offset:19456
	ds_read_b128 v[124:127], v152 offset:20480
	ds_read_b128 v[128:131], v152 offset:21504
	ds_read_b128 v[142:145], v152 offset:22528
	ds_read_b128 v[146:149], v152 offset:23552
	global_load_lds_dwordx4 v[8:9], off
	v_lshl_add_u64 v[8:9], s[2:3], 0, v[138:139]
	v_lshl_add_u64 v[132:133], v[8:9], 0, s[34:35]
	s_mov_b32 m0, s46
	s_nop 0
	global_load_lds_dwordx4 v[132:133], off
	s_barrier
	s_waitcnt lgkmcnt(0)
	s_setprio 1
	s_waitcnt lgkmcnt(0)
	v_mfma_f32_16x16x32_bf16 v[154:157], v[12:15], v[52:55], 0
	v_mfma_f32_16x16x32_bf16 v[162:165], v[12:15], v[116:119], 0
	v_mfma_f32_16x16x32_bf16 v[170:173], v[12:15], v[124:127], 0
	v_mfma_f32_16x16x32_bf16 v[12:15], v[12:15], v[142:145], 0
	v_mfma_f32_16x16x32_bf16 v[154:157], v[16:19], v[112:115], v[154:157]
	v_mfma_f32_16x16x32_bf16 v[158:161], v[20:23], v[52:55], 0
	v_mfma_f32_16x16x32_bf16 v[162:165], v[16:19], v[120:123], v[162:165]
	v_mfma_f32_16x16x32_bf16 v[166:169], v[20:23], v[116:119], 0
	v_mfma_f32_16x16x32_bf16 v[170:173], v[16:19], v[128:131], v[170:173]
	v_mfma_f32_16x16x32_bf16 v[174:177], v[20:23], v[124:127], 0
	v_mfma_f32_16x16x32_bf16 v[14:17], v[16:19], v[146:149], v[12:15]
	v_mfma_f32_16x16x32_bf16 v[18:21], v[20:23], v[142:145], 0
	v_mfma_f32_16x16x32_bf16 v[158:161], v[24:27], v[112:115], v[158:161]
	v_mfma_f32_16x16x32_bf16 v[18:21], v[24:27], v[146:149], v[18:21]
	v_mfma_f32_16x16x32_bf16 v[166:169], v[24:27], v[120:123], v[166:169]
	v_mfma_f32_16x16x32_bf16 v[174:177], v[24:27], v[128:131], v[174:177]
	s_setprio 0
	s_barrier
	s_add_u32 s34, s10, 0x18100
	s_addc_u32 s35, s11, 0
	s_add_i32 s8, s8, s44
	v_lshl_add_u64 v[12:13], s[34:35], 0, v[136:137]
	s_mov_b32 m0, s8
	s_add_i32 s6, s8, 0x2000
	global_load_lds_dwordx4 v[12:13], off
	v_lshl_add_u64 v[12:13], s[34:35], 0, v[140:141]
	s_mov_b32 m0, s6
	s_nop 0
	global_load_lds_dwordx4 v[12:13], off
	s_waitcnt vmcnt(6)
	s_barrier
; #define PG8_STAGE(bufoff, gbase, voff) do { _Pragma("unroll") for (int _i = 0; _i < 2; ++_i) \
;         __builtin_amdgcn_global_load_lds((const unsigned*)((const char*)(gbase) + (voff)[_i]), (LAS unsigned*)(lds + (bufoff) + ldsw + _i * 8192), 16, 0, 0); } while (0)
; #define PG8_LDA(dst, b, h) do { _Pragma("unroll") for (int m = 0; m < 4; ++m) _Pragma("unroll") for (int k = 0; k < 2; ++k) dst[m][k] = *(const LAS bf16x8*)(lds + PG8_SA(b, h) + aoff + m * 2048 + k * 1024); } while (0)
; #define PG8_WAIT_V(n) asm volatile("s_waitcnt vmcnt(" #n ")" ::: "memory")
; #define PG8_WAIT_L(n) asm volatile("s_waitcnt lgkmcnt(" #n ")" ::: "memory")
; template <class Epi, class Sched>
; __device__ __forceinline__ void gemm_phase(LAS unsigned char* lds, const Gemm g, const Sched& S, const Epi& E) {
;     ...
;         for (int t = 0; t < nt; t += 2) {
;             const bool last = (t == nt - 2);
;             const char* a1 = cA + (size_t)(t + 1) * kstep;
;             const char* a2 = last ? nA : cA + (size_t)(t + 2) * kstep; const char* b2 = last ? nB : cB + (size_t)(t + 2) * kstep;
;             const char* a3 = a2 + kstep; const char* b3 = b2 + kstep;
;             PG8_LDB(B0, 0, 0); PG8_SCHED; PG8_LDA(At, 0, 0); PG8_STAGE(PG8_SA(1, 1), a1 + hstepA, voffA);
;             PG8_WAIT_L(8); PG8_BAR; PG8_WAIT_L(0); PG8_MMA(0, 0, At, B0); PG8_BAR; PG8_SCHED;
;             PG8_LDB(B1, 0, 1); PG8_STAGE(PG8_SB(0, 0), b2, voffB);
;             PG8_BAR; PG8_WAIT_L(0); PG8_MMA(0, 1, At, B1); PG8_BAR;
;             PG8_LDA(At, 0, 1); PG8_STAGE(PG8_SA(0, 0), a2, voffA);
;             PG8_BAR; PG8_WAIT_L(0); PG8_MMA(1, 0, At, B0); PG8_BAR; PG8_SCHED;
;             PG8_STAGE(PG8_SB(0, 1), b2 + hstepB, voffB);
;             PG8_WAIT_V(6); PG8_BAR; PG8_MMA(1, 1, At, B1); PG8_BAR;
;             PG8_LDB(B0, 1, 0); PG8_SCHED; PG8_LDA(At, 1, 0); PG8_STAGE(PG8_SA(0, 1), a2 + hstepA, voffA);
;             PG8_WAIT_L(8); PG8_BAR; PG8_WAIT_L(0); PG8_MMA(0, 0, At, B0); PG8_BAR; PG8_SCHED;
;             PG8_LDB(B1, 1, 1); PG8_STAGE(PG8_SB(1, 0), b3, voffB);
;             PG8_BAR; PG8_WAIT_L(0); PG8_MMA(0, 1, At, B1); PG8_BAR;
;             PG8_LDA(At, 1, 1); PG8_STAGE(PG8_SA(1, 0), a3, voffA);
;             PG8_BAR; PG8_WAIT_L(0); PG8_MMA(1, 0, At, B0); PG8_BAR; PG8_SCHED;
;             PG8_STAGE(PG8_SB(1, 1), b3 + hstepB, voffB);
;             PG8_WAIT_V(6); PG8_BAR; PG8_MMA(1, 1, At, B1); PG8_BAR;
	s_setprio 1
	v_mfma_f32_16x16x32_bf16 v[22:25], v[88:91], v[52:55], 0
	v_mfma_f32_16x16x32_bf16 v[52:55], v[96:99], v[52:55], 0
	v_mfma_f32_16x16x32_bf16 v[22:25], v[92:95], v[112:115], v[22:25]
	v_mfma_f32_16x16x32_bf16 v[52:55], v[100:103], v[112:115], v[52:55]
	v_mfma_f32_16x16x32_bf16 v[112:115], v[88:91], v[116:119], 0
	v_mfma_f32_16x16x32_bf16 v[116:119], v[96:99], v[116:119], 0
	v_mfma_f32_16x16x32_bf16 v[112:115], v[92:95], v[120:123], v[112:115]
	v_mfma_f32_16x16x32_bf16 v[116:119], v[100:103], v[120:123], v[116:119]
	v_mfma_f32_16x16x32_bf16 v[120:123], v[88:91], v[124:127], 0
	v_mfma_f32_16x16x32_bf16 v[88:91], v[88:91], v[142:145], 0
	v_mfma_f32_16x16x32_bf16 v[120:123], v[92:95], v[128:131], v[120:123]
	v_mfma_f32_16x16x32_bf16 v[124:127], v[96:99], v[124:127], 0
	v_mfma_f32_16x16x32_bf16 v[88:91], v[92:95], v[146:149], v[88:91]
	v_mfma_f32_16x16x32_bf16 v[92:95], v[96:99], v[142:145], 0
	v_mfma_f32_16x16x32_bf16 v[124:127], v[100:103], v[128:131], v[124:127]
	v_mfma_f32_16x16x32_bf16 v[92:95], v[100:103], v[146:149], v[92:95]
	s_setprio 0
	s_add_i32 s9, 0, 0x18000
	v_add_u32_e32 v12, s9, v1
	s_barrier
	ds_read_b128 v[96:99], v12
	ds_read_b128 v[100:103], v12 offset:1024
	ds_read_b128 v[128:131], v12 offset:2048
	ds_read_b128 v[142:145], v12 offset:3072
	s_add_u32 s34, s2, 0x90100
	s_addc_u32 s35, s3, 0
	s_mov_b32 m0, s47
	v_lshl_add_u64 v[26:27], s[34:35], 0, v[134:135]
	ds_read_b128 v[146:149], v152 offset:32768
	ds_read_b128 v[178:181], v152 offset:33792
	ds_read_b128 v[182:185], v152 offset:34816
	ds_read_b128 v[200:203], v152 offset:35840
	ds_read_b128 v[204:207], v152 offset:36864
	ds_read_b128 v[208:211], v152 offset:37888
	ds_read_b128 v[212:215], v152 offset:38912
	ds_read_b128 v[230:233], v152 offset:39936
	global_load_lds_dwordx4 v[26:27], off
	v_lshl_add_u64 v[26:27], s[34:35], 0, v[138:139]
	s_mov_b32 m0, s48
	s_nop 0
	global_load_lds_dwordx4 v[26:27], off
	s_waitcnt lgkmcnt(8)
	s_barrier
	s_waitcnt lgkmcnt(0)
	s_setprio 1
	s_waitcnt lgkmcnt(0)
	v_mfma_f32_16x16x32_bf16 v[56:59], v[96:99], v[146:149], v[56:59]
	v_mfma_f32_16x16x32_bf16 v[60:63], v[128:131], v[146:149], v[60:63]
	v_mfma_f32_16x16x32_bf16 v[64:67], v[96:99], v[182:185], v[64:67]
	v_mfma_f32_16x16x32_bf16 v[68:71], v[128:131], v[182:185], v[68:71]
	v_mfma_f32_16x16x32_bf16 v[72:75], v[96:99], v[204:207], v[72:75]
	v_mfma_f32_16x16x32_bf16 v[76:79], v[128:131], v[204:207], v[76:79]
	v_mfma_f32_16x16x32_bf16 v[80:83], v[96:99], v[212:215], v[80:83]
	v_mfma_f32_16x16x32_bf16 v[84:87], v[128:131], v[212:215], v[84:87]
	v_mfma_f32_16x16x32_bf16 v[56:59], v[100:103], v[178:181], v[56:59]
	v_mfma_f32_16x16x32_bf16 v[60:63], v[142:145], v[178:181], v[60:63]
	v_mfma_f32_16x16x32_bf16 v[64:67], v[100:103], v[200:203], v[64:67]
	v_mfma_f32_16x16x32_bf16 v[68:71], v[142:145], v[200:203], v[68:71]
	v_mfma_f32_16x16x32_bf16 v[72:75], v[100:103], v[208:211], v[72:75]
	v_mfma_f32_16x16x32_bf16 v[76:79], v[142:145], v[208:211], v[76:79]
	v_mfma_f32_16x16x32_bf16 v[80:83], v[100:103], v[230:233], v[80:83]
	v_mfma_f32_16x16x32_bf16 v[84:87], v[142:145], v[230:233], v[84:87]
	s_setprio 0
	s_barrier
	s_add_i32 s35, 0, 0x1c000
	s_mov_b64 s[36:37], 0x180
	s_add_i32 s34, s9, s44
	v_add_u32_e32 v13, s35, v1
	v_lshl_add_u64 v[26:27], v[2:3], 0, s[36:37]
	s_mov_b32 m0, s34
	s_add_i32 s9, s34, 0x2000
	ds_read_b128 v[234:237], v13
	ds_read_b128 v[238:241], v13 offset:1024
	ds_read_b128 v[242:245], v13 offset:2048
	ds_read_b128 v[246:249], v13 offset:3072
	global_load_lds_dwordx4 v[26:27], off
	v_lshl_add_u64 v[26:27], v[4:5], 0, s[36:37]
	s_mov_b32 m0, s9
	s_nop 0
	global_load_lds_dwordx4 v[26:27], off
	s_barrier
	s_waitcnt lgkmcnt(0)
	s_setprio 1
	s_waitcnt lgkmcnt(0)
	v_mfma_f32_16x16x32_bf16 v[104:107], v[234:237], v[146:149], v[104:107]
	v_mfma_f32_16x16x32_bf16 v[26:29], v[242:245], v[146:149], v[28:31]
	v_mfma_f32_16x16x32_bf16 v[108:111], v[234:237], v[182:185], v[108:111]
	v_mfma_f32_16x16x32_bf16 v[30:33], v[242:245], v[182:185], v[32:35]
	v_mfma_f32_16x16x32_bf16 v[34:37], v[234:237], v[204:207], v[36:39]
	v_mfma_f32_16x16x32_bf16 v[38:41], v[242:245], v[204:207], v[40:43]
	v_mfma_f32_16x16x32_bf16 v[42:45], v[234:237], v[212:215], v[44:47]
	v_mfma_f32_16x16x32_bf16 v[46:49], v[242:245], v[212:215], v[48:51]
	v_mfma_f32_16x16x32_bf16 v[104:107], v[238:241], v[178:181], v[104:107]
	v_mfma_f32_16x16x32_bf16 v[26:29], v[246:249], v[178:181], v[26:29]
	v_mfma_f32_16x16x32_bf16 v[108:111], v[238:241], v[200:203], v[108:111]
	v_mfma_f32_16x16x32_bf16 v[30:33], v[246:249], v[200:203], v[30:33]
	v_mfma_f32_16x16x32_bf16 v[34:37], v[238:241], v[208:211], v[34:37]
	v_mfma_f32_16x16x32_bf16 v[38:41], v[246:249], v[208:211], v[38:41]
	v_mfma_f32_16x16x32_bf16 v[42:45], v[238:241], v[230:233], v[42:45]
	v_mfma_f32_16x16x32_bf16 v[46:49], v[246:249], v[230:233], v[46:49]
	s_setprio 0
	s_mov_b32 m0, s49
	v_lshl_add_u64 v[50:51], v[6:7], 0, s[36:37]
	s_barrier
	ds_read_b128 v[146:149], v152 offset:49152
	ds_read_b128 v[178:181], v152 offset:50176
	ds_read_b128 v[182:185], v152 offset:51200
	ds_read_b128 v[200:203], v152 offset:52224
	ds_read_b128 v[204:207], v152 offset:53248
	ds_read_b128 v[208:211], v152 offset:54272
	ds_read_b128 v[212:215], v152 offset:55296
	ds_read_b128 v[230:233], v152 offset:56320
	global_load_lds_dwordx4 v[50:51], off
	v_lshl_add_u64 v[50:51], v[8:9], 0, s[36:37]
	s_mov_b32 m0, s58
	s_nop 0
	global_load_lds_dwordx4 v[50:51], off
	s_barrier
; #define PG8_STAGE(bufoff, gbase, voff) do { _Pragma("unroll") for (int _i = 0; _i < 2; ++_i) \
;         __builtin_amdgcn_global_load_lds((const unsigned*)((const char*)(gbase) + (voff)[_i]), (LAS unsigned*)(lds + (bufoff) + ldsw + _i * 8192), 16, 0, 0); } while (0)
; #define PG8_LDA(dst, b, h) do { _Pragma("unroll") for (int m = 0; m < 4; ++m) _Pragma("unroll") for (int k = 0; k < 2; ++k) dst[m][k] = *(const LAS bf16x8*)(lds + PG8_SA(b, h) + aoff + m * 2048 + k * 1024); } while (0)
; #define PG8_WAIT_V(n) asm volatile("s_waitcnt vmcnt(" #n ")" ::: "memory")
; #define PG8_WAIT_L(n) asm volatile("s_waitcnt lgkmcnt(" #n ")" ::: "memory")
; template <class Epi, class Sched>
; __device__ __forceinline__ void gemm_phase(LAS unsigned char* lds, const Gemm g, const Sched& S, const Epi& E) {
;     ...
;         for (int t = 0; t < nt; t += 2) {
;             const bool last = (t == nt - 2);
;             const char* a1 = cA + (size_t)(t + 1) * kstep;
;             const char* a2 = last ? nA : cA + (size_t)(t + 2) * kstep; const char* b2 = last ? nB : cB + (size_t)(t + 2) * kstep;
;             const char* a3 = a2 + kstep; const char* b3 = b2 + kstep;
;             PG8_LDB(B0, 0, 0); PG8_SCHED; PG8_LDA(At, 0, 0); PG8_STAGE(PG8_SA(1, 1), a1 + hstepA, voffA);
;             PG8_WAIT_L(8); PG8_BAR; PG8_WAIT_L(0); PG8_MMA(0, 0, At, B0); PG8_BAR; PG8_SCHED;
;             PG8_LDB(B1, 0, 1); PG8_STAGE(PG8_SB(0, 0), b2, voffB);
;             PG8_BAR; PG8_WAIT_L(0); PG8_MMA(0, 1, At, B1); PG8_BAR;
;             PG8_LDA(At, 0, 1); PG8_STAGE(PG8_SA(0, 0), a2, voffA);
;             PG8_BAR; PG8_WAIT_L(0); PG8_MMA(1, 0, At, B0); PG8_BAR; PG8_SCHED;
;             PG8_STAGE(PG8_SB(0, 1), b2 + hstepB, voffB);
;             PG8_WAIT_V(6); PG8_BAR; PG8_MMA(1, 1, At, B1); PG8_BAR;
;             PG8_LDB(B0, 1, 0); PG8_SCHED; PG8_LDA(At, 1, 0); PG8_STAGE(PG8_SA(0, 1), a2 + hstepA, voffA);
;             PG8_WAIT_L(8); PG8_BAR; PG8_WAIT_L(0); PG8_MMA(0, 0, At, B0); PG8_BAR; PG8_SCHED;
;             PG8_LDB(B1, 1, 1); PG8_STAGE(PG8_SB(1, 0), b3, voffB);
;             PG8_BAR; PG8_WAIT_L(0); PG8_MMA(0, 1, At, B1); PG8_BAR;
;             PG8_LDA(At, 1, 1); PG8_STAGE(PG8_SA(1, 0), a3, voffA);
;             PG8_BAR; PG8_WAIT_L(0); PG8_MMA(1, 0, At, B0); PG8_BAR; PG8_SCHED;
;             PG8_STAGE(PG8_SB(1, 1), b3 + hstepB, voffB);
;             PG8_WAIT_V(6); PG8_BAR; PG8_MMA(1, 1, At, B1); PG8_BAR;
	s_waitcnt lgkmcnt(0)
	s_setprio 1
	s_waitcnt lgkmcnt(0)
	v_mfma_f32_16x16x32_bf16 v[154:157], v[96:99], v[146:149], v[154:157]
	v_mfma_f32_16x16x32_bf16 v[158:161], v[128:131], v[146:149], v[158:161]
	v_mfma_f32_16x16x32_bf16 v[14:17], v[96:99], v[212:215], v[14:17]
	v_mfma_f32_16x16x32_bf16 v[18:21], v[128:131], v[212:215], v[18:21]
	v_mfma_f32_16x16x32_bf16 v[154:157], v[100:103], v[178:181], v[154:157]
	v_mfma_f32_16x16x32_bf16 v[158:161], v[142:145], v[178:181], v[158:161]
	v_mfma_f32_16x16x32_bf16 v[162:165], v[96:99], v[182:185], v[162:165]
	v_mfma_f32_16x16x32_bf16 v[166:169], v[128:131], v[182:185], v[166:169]
	v_mfma_f32_16x16x32_bf16 v[170:173], v[96:99], v[204:207], v[170:173]
	v_mfma_f32_16x16x32_bf16 v[174:177], v[128:131], v[204:207], v[174:177]
	v_mfma_f32_16x16x32_bf16 v[14:17], v[100:103], v[230:233], v[14:17]
	v_mfma_f32_16x16x32_bf16 v[18:21], v[142:145], v[230:233], v[18:21]
	v_mfma_f32_16x16x32_bf16 v[162:165], v[100:103], v[200:203], v[162:165]
	v_mfma_f32_16x16x32_bf16 v[166:169], v[142:145], v[200:203], v[166:169]
	v_mfma_f32_16x16x32_bf16 v[170:173], v[100:103], v[208:211], v[170:173]
	v_mfma_f32_16x16x32_bf16 v[174:177], v[142:145], v[208:211], v[174:177]
	s_setprio 0
	s_barrier
	s_add_u32 s36, s10, 0x18180
	s_addc_u32 s37, s11, 0
	s_add_i32 s35, s35, s44
	v_lshl_add_u64 v[50:51], s[36:37], 0, v[136:137]
	s_mov_b32 m0, s35
	s_add_i32 s15, s35, 0x2000
	global_load_lds_dwordx4 v[50:51], off
	v_lshl_add_u64 v[50:51], s[36:37], 0, v[140:141]
	s_mov_b32 m0, s15
	s_nop 0
	global_load_lds_dwordx4 v[50:51], off
	s_waitcnt vmcnt(6)
	s_barrier
	s_setprio 1
	v_mfma_f32_16x16x32_bf16 v[22:25], v[234:237], v[146:149], v[22:25]
	v_mfma_f32_16x16x32_bf16 v[50:53], v[242:245], v[146:149], v[52:55]
	v_mfma_f32_16x16x32_bf16 v[96:99], v[234:237], v[182:185], v[112:115]
	v_mfma_f32_16x16x32_bf16 v[100:103], v[242:245], v[182:185], v[116:119]
	v_mfma_f32_16x16x32_bf16 v[112:115], v[234:237], v[204:207], v[120:123]
	v_mfma_f32_16x16x32_bf16 v[116:119], v[242:245], v[204:207], v[124:127]
	v_mfma_f32_16x16x32_bf16 v[88:91], v[234:237], v[212:215], v[88:91]
	v_mfma_f32_16x16x32_bf16 v[92:95], v[242:245], v[212:215], v[92:95]
	v_mfma_f32_16x16x32_bf16 v[22:25], v[238:241], v[178:181], v[22:25]
	v_mfma_f32_16x16x32_bf16 v[50:53], v[246:249], v[178:181], v[50:53]
	v_mfma_f32_16x16x32_bf16 v[96:99], v[238:241], v[200:203], v[96:99]
	v_mfma_f32_16x16x32_bf16 v[100:103], v[246:249], v[200:203], v[100:103]
	v_mfma_f32_16x16x32_bf16 v[112:115], v[238:241], v[208:211], v[112:115]
	v_mfma_f32_16x16x32_bf16 v[116:119], v[246:249], v[208:211], v[116:119]
	v_mfma_f32_16x16x32_bf16 v[88:91], v[238:241], v[230:233], v[88:91]
	v_mfma_f32_16x16x32_bf16 v[92:95], v[246:249], v[230:233], v[92:95]
	s_setprio 0
	s_barrier
	ds_read_b128 v[120:123], v10
	ds_read_b128 v[124:127], v10 offset:1024
	ds_read_b128 v[128:131], v10 offset:2048
	ds_read_b128 v[142:145], v10 offset:3072
	s_add_u32 s36, s2, 0x90180
	s_addc_u32 s37, s3, 0
	s_mov_b32 m0, s14
	v_lshl_add_u64 v[54:55], s[36:37], 0, v[134:135]
	ds_read_b128 v[146:149], v152
	ds_read_b128 v[178:181], v152 offset:1024
	ds_read_b128 v[182:185], v152 offset:2048
	ds_read_b128 v[200:203], v152 offset:3072
	ds_read_b128 v[204:207], v152 offset:4096
	ds_read_b128 v[208:211], v152 offset:5120
	ds_read_b128 v[212:215], v152 offset:6144
	ds_read_b128 v[230:233], v152 offset:7168
	global_load_lds_dwordx4 v[54:55], off
	v_lshl_add_u64 v[54:55], s[36:37], 0, v[138:139]
	s_mov_b32 m0, s0
	s_nop 0
	global_load_lds_dwordx4 v[54:55], off
	s_waitcnt lgkmcnt(8)
	s_barrier
	s_waitcnt lgkmcnt(0)
	s_setprio 1
	s_waitcnt lgkmcnt(0)
	v_mfma_f32_16x16x32_bf16 v[54:57], v[120:123], v[146:149], v[56:59]
	v_mfma_f32_16x16x32_bf16 v[58:61], v[128:131], v[146:149], v[60:63]
	v_mfma_f32_16x16x32_bf16 v[62:65], v[120:123], v[182:185], v[64:67]
	v_mfma_f32_16x16x32_bf16 v[66:69], v[128:131], v[182:185], v[68:71]
	v_mfma_f32_16x16x32_bf16 v[70:73], v[120:123], v[204:207], v[72:75]
	v_mfma_f32_16x16x32_bf16 v[74:77], v[128:131], v[204:207], v[76:79]
	v_mfma_f32_16x16x32_bf16 v[78:81], v[120:123], v[212:215], v[80:83]
	v_mfma_f32_16x16x32_bf16 v[82:85], v[128:131], v[212:215], v[84:87]
	v_mfma_f32_16x16x32_bf16 v[54:57], v[124:127], v[178:181], v[54:57]
	v_mfma_f32_16x16x32_bf16 v[58:61], v[142:145], v[178:181], v[58:61]
	v_mfma_f32_16x16x32_bf16 v[62:65], v[124:127], v[200:203], v[62:65]
	v_mfma_f32_16x16x32_bf16 v[66:69], v[142:145], v[200:203], v[66:69]
	v_mfma_f32_16x16x32_bf16 v[70:73], v[124:127], v[208:211], v[70:73]
	v_mfma_f32_16x16x32_bf16 v[74:77], v[142:145], v[208:211], v[74:77]
	v_mfma_f32_16x16x32_bf16 v[78:81], v[124:127], v[230:233], v[78:81]
	v_mfma_f32_16x16x32_bf16 v[82:85], v[142:145], v[230:233], v[82:85]
	s_setprio 0
	s_barrier
	s_mov_b64 s[36:37], 0x200
	s_mov_b32 m0, s7
	v_lshl_add_u64 v[86:87], v[2:3], 0, s[36:37]
	ds_read_b128 v[234:237], v11
	ds_read_b128 v[238:241], v11 offset:1024
	ds_read_b128 v[242:245], v11 offset:2048
	ds_read_b128 v[246:249], v11 offset:3072
	global_load_lds_dwordx4 v[86:87], off
	v_lshl_add_u64 v[86:87], v[4:5], 0, s[36:37]
	s_mov_b32 m0, s1
	s_nop 0
	global_load_lds_dwordx4 v[86:87], off
	s_barrier
; #define PG8_STAGE(bufoff, gbase, voff) do { _Pragma("unroll") for (int _i = 0; _i < 2; ++_i) \
;         __builtin_amdgcn_global_load_lds((const unsigned*)((const char*)(gbase) + (voff)[_i]), (LAS unsigned*)(lds + (bufoff) + ldsw + _i * 8192), 16, 0, 0); } while (0)
; #define PG8_LDA(dst, b, h) do { _Pragma("unroll") for (int m = 0; m < 4; ++m) _Pragma("unroll") for (int k = 0; k < 2; ++k) dst[m][k] = *(const LAS bf16x8*)(lds + PG8_SA(b, h) + aoff + m * 2048 + k * 1024); } while (0)
; #define PG8_WAIT_V(n) asm volatile("s_waitcnt vmcnt(" #n ")" ::: "memory")
; #define PG8_WAIT_L(n) asm volatile("s_waitcnt lgkmcnt(" #n ")" ::: "memory")
; template <class Epi, class Sched>
; __device__ __forceinline__ void gemm_phase(LAS unsigned char* lds, const Gemm g, const Sched& S, const Epi& E) {
;     ...
;         for (int t = 0; t < nt; t += 2) {
;             const bool last = (t == nt - 2);
;             const char* a1 = cA + (size_t)(t + 1) * kstep;
;             const char* a2 = last ? nA : cA + (size_t)(t + 2) * kstep; const char* b2 = last ? nB : cB + (size_t)(t + 2) * kstep;
;             const char* a3 = a2 + kstep; const char* b3 = b2 + kstep;
;             PG8_LDB(B0, 0, 0); PG8_SCHED; PG8_LDA(At, 0, 0); PG8_STAGE(PG8_SA(1, 1), a1 + hstepA, voffA);
;             PG8_WAIT_L(8); PG8_BAR; PG8_WAIT_L(0); PG8_MMA(0, 0, At, B0); PG8_BAR; PG8_SCHED;
;             PG8_LDB(B1, 0, 1); PG8_STAGE(PG8_SB(0, 0), b2, voffB);
;             PG8_BAR; PG8_WAIT_L(0); PG8_MMA(0, 1, At, B1); PG8_BAR;
;             PG8_LDA(At, 0, 1); PG8_STAGE(PG8_SA(0, 0), a2, voffA);
;             PG8_BAR; PG8_WAIT_L(0); PG8_MMA(1, 0, At, B0); PG8_BAR; PG8_SCHED;
;             PG8_STAGE(PG8_SB(0, 1), b2 + hstepB, voffB);
;             PG8_WAIT_V(6); PG8_BAR; PG8_MMA(1, 1, At, B1); PG8_BAR;
;             PG8_LDB(B0, 1, 0); PG8_SCHED; PG8_LDA(At, 1, 0); PG8_STAGE(PG8_SA(0, 1), a2 + hstepA, voffA);
;             PG8_WAIT_L(8); PG8_BAR; PG8_WAIT_L(0); PG8_MMA(0, 0, At, B0); PG8_BAR; PG8_SCHED;
;             PG8_LDB(B1, 1, 1); PG8_STAGE(PG8_SB(1, 0), b3, voffB);
;             PG8_BAR; PG8_WAIT_L(0); PG8_MMA(0, 1, At, B1); PG8_BAR;
;             PG8_LDA(At, 1, 1); PG8_STAGE(PG8_SA(1, 0), a3, voffA);
;             PG8_BAR; PG8_WAIT_L(0); PG8_MMA(1, 0, At, B0); PG8_BAR; PG8_SCHED;
;             PG8_STAGE(PG8_SB(1, 1), b3 + hstepB, voffB);
;             PG8_WAIT_V(6); PG8_BAR; PG8_MMA(1, 1, At, B1); PG8_BAR;
	s_waitcnt lgkmcnt(0)
	s_setprio 1
	s_waitcnt lgkmcnt(0)
	v_mfma_f32_16x16x32_bf16 v[104:107], v[234:237], v[146:149], v[104:107]
	v_mfma_f32_16x16x32_bf16 v[26:29], v[242:245], v[146:149], v[26:29]
	v_mfma_f32_16x16x32_bf16 v[108:111], v[234:237], v[182:185], v[108:111]
	v_mfma_f32_16x16x32_bf16 v[30:33], v[242:245], v[182:185], v[30:33]
	v_mfma_f32_16x16x32_bf16 v[34:37], v[234:237], v[204:207], v[34:37]
	v_mfma_f32_16x16x32_bf16 v[38:41], v[242:245], v[204:207], v[38:41]
	v_mfma_f32_16x16x32_bf16 v[42:45], v[234:237], v[212:215], v[42:45]
	v_mfma_f32_16x16x32_bf16 v[46:49], v[242:245], v[212:215], v[46:49]
	v_mfma_f32_16x16x32_bf16 v[104:107], v[238:241], v[178:181], v[104:107]
	v_mfma_f32_16x16x32_bf16 v[26:29], v[246:249], v[178:181], v[26:29]
	v_mfma_f32_16x16x32_bf16 v[108:111], v[238:241], v[200:203], v[108:111]
	v_mfma_f32_16x16x32_bf16 v[30:33], v[246:249], v[200:203], v[30:33]
	v_mfma_f32_16x16x32_bf16 v[34:37], v[238:241], v[208:211], v[34:37]
	v_mfma_f32_16x16x32_bf16 v[38:41], v[246:249], v[208:211], v[38:41]
	v_mfma_f32_16x16x32_bf16 v[42:45], v[238:241], v[230:233], v[42:45]
	v_mfma_f32_16x16x32_bf16 v[46:49], v[246:249], v[230:233], v[46:49]
	s_setprio 0
	s_mov_b32 m0, s45
	v_lshl_add_u64 v[86:87], v[6:7], 0, s[36:37]
	s_barrier
	ds_read_b128 v[146:149], v152 offset:16384
	ds_read_b128 v[178:181], v152 offset:17408
	ds_read_b128 v[182:185], v152 offset:18432
	ds_read_b128 v[200:203], v152 offset:19456
	ds_read_b128 v[204:207], v152 offset:20480
	ds_read_b128 v[208:211], v152 offset:21504
	ds_read_b128 v[212:215], v152 offset:22528
	ds_read_b128 v[230:233], v152 offset:23552
	global_load_lds_dwordx4 v[86:87], off
	v_lshl_add_u64 v[86:87], v[8:9], 0, s[36:37]
	s_mov_b32 m0, s46
	s_nop 0
	global_load_lds_dwordx4 v[86:87], off
	s_barrier
	s_waitcnt lgkmcnt(0)
	s_setprio 1
	s_waitcnt lgkmcnt(0)
	v_mfma_f32_16x16x32_bf16 v[154:157], v[120:123], v[146:149], v[154:157]
	v_mfma_f32_16x16x32_bf16 v[158:161], v[128:131], v[146:149], v[158:161]
	v_mfma_f32_16x16x32_bf16 v[14:17], v[120:123], v[212:215], v[14:17]
	v_mfma_f32_16x16x32_bf16 v[18:21], v[128:131], v[212:215], v[18:21]
	v_mfma_f32_16x16x32_bf16 v[154:157], v[124:127], v[178:181], v[154:157]
	v_mfma_f32_16x16x32_bf16 v[158:161], v[142:145], v[178:181], v[158:161]
	v_mfma_f32_16x16x32_bf16 v[162:165], v[120:123], v[182:185], v[162:165]
	v_mfma_f32_16x16x32_bf16 v[166:169], v[128:131], v[182:185], v[166:169]
	v_mfma_f32_16x16x32_bf16 v[170:173], v[120:123], v[204:207], v[170:173]
	v_mfma_f32_16x16x32_bf16 v[174:177], v[128:131], v[204:207], v[174:177]
	v_mfma_f32_16x16x32_bf16 v[14:17], v[124:127], v[230:233], v[14:17]
	v_mfma_f32_16x16x32_bf16 v[18:21], v[142:145], v[230:233], v[18:21]
	v_mfma_f32_16x16x32_bf16 v[162:165], v[124:127], v[200:203], v[162:165]
	v_mfma_f32_16x16x32_bf16 v[166:169], v[142:145], v[200:203], v[166:169]
	v_mfma_f32_16x16x32_bf16 v[170:173], v[124:127], v[208:211], v[170:173]
	v_mfma_f32_16x16x32_bf16 v[174:177], v[142:145], v[208:211], v[174:177]
	s_setprio 0
	s_barrier
	s_add_u32 s36, s10, 0x18200
	s_addc_u32 s37, s11, 0
	s_mov_b32 m0, s8
	v_lshl_add_u64 v[86:87], s[36:37], 0, v[136:137]
	global_load_lds_dwordx4 v[86:87], off
	v_lshl_add_u64 v[86:87], s[36:37], 0, v[140:141]
	s_mov_b32 m0, s6
	s_nop 0
	global_load_lds_dwordx4 v[86:87], off
	s_waitcnt vmcnt(6)
	s_barrier
	s_setprio 1
	v_mfma_f32_16x16x32_bf16 v[22:25], v[234:237], v[146:149], v[22:25]
	v_mfma_f32_16x16x32_bf16 v[50:53], v[242:245], v[146:149], v[50:53]
	v_mfma_f32_16x16x32_bf16 v[96:99], v[234:237], v[182:185], v[96:99]
	v_mfma_f32_16x16x32_bf16 v[100:103], v[242:245], v[182:185], v[100:103]
	v_mfma_f32_16x16x32_bf16 v[112:115], v[234:237], v[204:207], v[112:115]
	v_mfma_f32_16x16x32_bf16 v[116:119], v[242:245], v[204:207], v[116:119]
	v_mfma_f32_16x16x32_bf16 v[86:89], v[234:237], v[212:215], v[88:91]
	v_mfma_f32_16x16x32_bf16 v[90:93], v[242:245], v[212:215], v[92:95]
	v_mfma_f32_16x16x32_bf16 v[22:25], v[238:241], v[178:181], v[22:25]
	v_mfma_f32_16x16x32_bf16 v[50:53], v[246:249], v[178:181], v[50:53]
	v_mfma_f32_16x16x32_bf16 v[96:99], v[238:241], v[200:203], v[96:99]
	v_mfma_f32_16x16x32_bf16 v[100:103], v[246:249], v[200:203], v[100:103]
	v_mfma_f32_16x16x32_bf16 v[112:115], v[238:241], v[208:211], v[112:115]
	v_mfma_f32_16x16x32_bf16 v[116:119], v[246:249], v[208:211], v[116:119]
	v_mfma_f32_16x16x32_bf16 v[86:89], v[238:241], v[230:233], v[86:89]
	v_mfma_f32_16x16x32_bf16 v[90:93], v[246:249], v[230:233], v[90:93]
	s_setprio 0
	s_barrier
	ds_read_b128 v[120:123], v12
	ds_read_b128 v[124:127], v12 offset:1024
	ds_read_b128 v[128:131], v12 offset:2048
	ds_read_b128 v[142:145], v12 offset:3072
	s_add_u32 s36, s2, 0x90200
	s_addc_u32 s37, s3, 0
	s_mov_b32 m0, s47
	v_lshl_add_u64 v[94:95], s[36:37], 0, v[134:135]
	ds_read_b128 v[146:149], v152 offset:32768
	ds_read_b128 v[178:181], v152 offset:33792
	ds_read_b128 v[182:185], v152 offset:34816
	ds_read_b128 v[200:203], v152 offset:35840
	ds_read_b128 v[204:207], v152 offset:36864
	ds_read_b128 v[208:211], v152 offset:37888
	ds_read_b128 v[212:215], v152 offset:38912
	ds_read_b128 v[230:233], v152 offset:39936
	global_load_lds_dwordx4 v[94:95], off
	v_lshl_add_u64 v[94:95], s[36:37], 0, v[138:139]
	s_mov_b32 m0, s48
	s_nop 0
	global_load_lds_dwordx4 v[94:95], off
	s_waitcnt lgkmcnt(8)
	s_barrier
; #define PG8_STAGE(bufoff, gbase, voff) do { _Pragma("unroll") for (int _i = 0; _i < 2; ++_i) \
;         __builtin_amdgcn_global_load_lds((const unsigned*)((const char*)(gbase) + (voff)[_i]), (LAS unsigned*)(lds + (bufoff) + ldsw + _i * 8192), 16, 0, 0); } while (0)
; #define PG8_LDA(dst, b, h) do { _Pragma("unroll") for (int m = 0; m < 4; ++m) _Pragma("unroll") for (int k = 0; k < 2; ++k) dst[m][k] = *(const LAS bf16x8*)(lds + PG8_SA(b, h) + aoff + m * 2048 + k * 1024); } while (0)
; #define PG8_WAIT_V(n) asm volatile("s_waitcnt vmcnt(" #n ")" ::: "memory")
; #define PG8_WAIT_L(n) asm volatile("s_waitcnt lgkmcnt(" #n ")" ::: "memory")
; template <class Epi, class Sched>
; __device__ __forceinline__ void gemm_phase(LAS unsigned char* lds, const Gemm g, const Sched& S, const Epi& E) {
;     ...
;         for (int t = 0; t < nt; t += 2) {
;             const bool last = (t == nt - 2);
;             const char* a1 = cA + (size_t)(t + 1) * kstep;
;             const char* a2 = last ? nA : cA + (size_t)(t + 2) * kstep; const char* b2 = last ? nB : cB + (size_t)(t + 2) * kstep;
;             const char* a3 = a2 + kstep; const char* b3 = b2 + kstep;
;             PG8_LDB(B0, 0, 0); PG8_SCHED; PG8_LDA(At, 0, 0); PG8_STAGE(PG8_SA(1, 1), a1 + hstepA, voffA);
;             PG8_WAIT_L(8); PG8_BAR; PG8_WAIT_L(0); PG8_MMA(0, 0, At, B0); PG8_BAR; PG8_SCHED;
;             PG8_LDB(B1, 0, 1); PG8_STAGE(PG8_SB(0, 0), b2, voffB);
;             PG8_BAR; PG8_WAIT_L(0); PG8_MMA(0, 1, At, B1); PG8_BAR;
;             PG8_LDA(At, 0, 1); PG8_STAGE(PG8_SA(0, 0), a2, voffA);
;             PG8_BAR; PG8_WAIT_L(0); PG8_MMA(1, 0, At, B0); PG8_BAR; PG8_SCHED;
;             PG8_STAGE(PG8_SB(0, 1), b2 + hstepB, voffB);
;             PG8_WAIT_V(6); PG8_BAR; PG8_MMA(1, 1, At, B1); PG8_BAR;
;             PG8_LDB(B0, 1, 0); PG8_SCHED; PG8_LDA(At, 1, 0); PG8_STAGE(PG8_SA(0, 1), a2 + hstepA, voffA);
;             PG8_WAIT_L(8); PG8_BAR; PG8_WAIT_L(0); PG8_MMA(0, 0, At, B0); PG8_BAR; PG8_SCHED;
;             PG8_LDB(B1, 1, 1); PG8_STAGE(PG8_SB(1, 0), b3, voffB);
;             PG8_BAR; PG8_WAIT_L(0); PG8_MMA(0, 1, At, B1); PG8_BAR;
;             PG8_LDA(At, 1, 1); PG8_STAGE(PG8_SA(1, 0), a3, voffA);
;             PG8_BAR; PG8_WAIT_L(0); PG8_MMA(1, 0, At, B0); PG8_BAR; PG8_SCHED;
;             PG8_STAGE(PG8_SB(1, 1), b3 + hstepB, voffB);
;             PG8_WAIT_V(6); PG8_BAR; PG8_MMA(1, 1, At, B1); PG8_BAR;
	s_waitcnt lgkmcnt(0)
	s_setprio 1
	s_waitcnt lgkmcnt(0)
	v_mfma_f32_16x16x32_bf16 v[54:57], v[120:123], v[146:149], v[54:57]
	v_mfma_f32_16x16x32_bf16 v[58:61], v[128:131], v[146:149], v[58:61]
	v_mfma_f32_16x16x32_bf16 v[62:65], v[120:123], v[182:185], v[62:65]
	v_mfma_f32_16x16x32_bf16 v[66:69], v[128:131], v[182:185], v[66:69]
	v_mfma_f32_16x16x32_bf16 v[70:73], v[120:123], v[204:207], v[70:73]
	v_mfma_f32_16x16x32_bf16 v[74:77], v[128:131], v[204:207], v[74:77]
	v_mfma_f32_16x16x32_bf16 v[78:81], v[120:123], v[212:215], v[78:81]
	v_mfma_f32_16x16x32_bf16 v[82:85], v[128:131], v[212:215], v[82:85]
	v_mfma_f32_16x16x32_bf16 v[54:57], v[124:127], v[178:181], v[54:57]
	v_mfma_f32_16x16x32_bf16 v[58:61], v[142:145], v[178:181], v[58:61]
	v_mfma_f32_16x16x32_bf16 v[62:65], v[124:127], v[200:203], v[62:65]
	v_mfma_f32_16x16x32_bf16 v[66:69], v[142:145], v[200:203], v[66:69]
	v_mfma_f32_16x16x32_bf16 v[70:73], v[124:127], v[208:211], v[70:73]
	v_mfma_f32_16x16x32_bf16 v[74:77], v[142:145], v[208:211], v[74:77]
	v_mfma_f32_16x16x32_bf16 v[78:81], v[124:127], v[230:233], v[78:81]
	v_mfma_f32_16x16x32_bf16 v[82:85], v[142:145], v[230:233], v[82:85]
	s_setprio 0
	s_barrier
	s_mov_b64 s[36:37], 0x280
	s_mov_b32 m0, s34
	v_lshl_add_u64 v[2:3], v[2:3], 0, s[36:37]
	ds_read_b128 v[234:237], v13
	ds_read_b128 v[238:241], v13 offset:1024
	ds_read_b128 v[242:245], v13 offset:2048
	ds_read_b128 v[246:249], v13 offset:3072
	global_load_lds_dwordx4 v[2:3], off
	v_lshl_add_u64 v[2:3], v[4:5], 0, s[36:37]
	s_mov_b32 m0, s9
	s_nop 0
	global_load_lds_dwordx4 v[2:3], off
	s_barrier
	s_waitcnt lgkmcnt(0)
	s_setprio 1
	s_waitcnt lgkmcnt(0)
	v_mfma_f32_16x16x32_bf16 v[2:5], v[234:237], v[146:149], v[104:107]
	v_mfma_f32_16x16x32_bf16 v[26:29], v[242:245], v[146:149], v[26:29]
	v_mfma_f32_16x16x32_bf16 v[104:107], v[234:237], v[182:185], v[108:111]
	v_mfma_f32_16x16x32_bf16 v[30:33], v[242:245], v[182:185], v[30:33]
	v_mfma_f32_16x16x32_bf16 v[34:37], v[234:237], v[204:207], v[34:37]
	v_mfma_f32_16x16x32_bf16 v[38:41], v[242:245], v[204:207], v[38:41]
	v_mfma_f32_16x16x32_bf16 v[42:45], v[234:237], v[212:215], v[42:45]
	v_mfma_f32_16x16x32_bf16 v[46:49], v[242:245], v[212:215], v[46:49]
	v_mfma_f32_16x16x32_bf16 v[2:5], v[238:241], v[178:181], v[2:5]
	v_mfma_f32_16x16x32_bf16 v[26:29], v[246:249], v[178:181], v[26:29]
	v_mfma_f32_16x16x32_bf16 v[104:107], v[238:241], v[200:203], v[104:107]
	v_mfma_f32_16x16x32_bf16 v[30:33], v[246:249], v[200:203], v[30:33]
	v_mfma_f32_16x16x32_bf16 v[34:37], v[238:241], v[208:211], v[34:37]
	v_mfma_f32_16x16x32_bf16 v[38:41], v[246:249], v[208:211], v[38:41]
	v_mfma_f32_16x16x32_bf16 v[42:45], v[238:241], v[230:233], v[42:45]
	v_mfma_f32_16x16x32_bf16 v[46:49], v[246:249], v[230:233], v[46:49]
	s_setprio 0
	s_mov_b32 m0, s49
	v_lshl_add_u64 v[6:7], v[6:7], 0, s[36:37]
	s_barrier
	ds_read_b128 v[108:111], v152 offset:49152
	ds_read_b128 v[146:149], v152 offset:50176
	ds_read_b128 v[178:181], v152 offset:51200
	ds_read_b128 v[182:185], v152 offset:52224
	ds_read_b128 v[200:203], v152 offset:53248
	ds_read_b128 v[204:207], v152 offset:54272
	ds_read_b128 v[208:211], v152 offset:55296
	ds_read_b128 v[212:215], v152 offset:56320
	global_load_lds_dwordx4 v[6:7], off
	v_lshl_add_u64 v[6:7], v[8:9], 0, s[36:37]
	s_mov_b32 m0, s58
	s_nop 0
	global_load_lds_dwordx4 v[6:7], off
	s_barrier
	s_waitcnt lgkmcnt(0)
	s_setprio 1
	s_waitcnt lgkmcnt(0)
	v_mfma_f32_16x16x32_bf16 v[6:9], v[120:123], v[108:111], v[154:157]
	v_mfma_f32_16x16x32_bf16 v[154:157], v[128:131], v[108:111], v[158:161]
	v_mfma_f32_16x16x32_bf16 v[158:161], v[120:123], v[178:181], v[162:165]
	v_mfma_f32_16x16x32_bf16 v[14:17], v[120:123], v[208:211], v[14:17]
	v_mfma_f32_16x16x32_bf16 v[18:21], v[128:131], v[208:211], v[18:21]
	v_mfma_f32_16x16x32_bf16 v[6:9], v[124:127], v[146:149], v[6:9]
	v_mfma_f32_16x16x32_bf16 v[154:157], v[142:145], v[146:149], v[154:157]
	v_mfma_f32_16x16x32_bf16 v[158:161], v[124:127], v[182:185], v[158:161]
	v_mfma_f32_16x16x32_bf16 v[162:165], v[128:131], v[178:181], v[166:169]
	v_mfma_f32_16x16x32_bf16 v[166:169], v[120:123], v[200:203], v[170:173]
	v_mfma_f32_16x16x32_bf16 v[170:173], v[128:131], v[200:203], v[174:177]
	v_mfma_f32_16x16x32_bf16 v[14:17], v[124:127], v[212:215], v[14:17]
	v_mfma_f32_16x16x32_bf16 v[18:21], v[142:145], v[212:215], v[18:21]
	v_mfma_f32_16x16x32_bf16 v[162:165], v[142:145], v[182:185], v[162:165]
	v_mfma_f32_16x16x32_bf16 v[166:169], v[124:127], v[204:207], v[166:169]
	v_mfma_f32_16x16x32_bf16 v[170:173], v[142:145], v[204:207], v[170:173]
	s_setprio 0
	s_barrier
	s_add_u32 s10, s10, 0x18280
	s_addc_u32 s11, s11, 0
	s_mov_b32 m0, s35
	v_lshl_add_u64 v[94:95], s[10:11], 0, v[136:137]
	global_load_lds_dwordx4 v[94:95], off
	v_lshl_add_u64 v[94:95], s[10:11], 0, v[140:141]
	s_mov_b32 m0, s15
	s_nop 0
	global_load_lds_dwordx4 v[94:95], off
	s_waitcnt vmcnt(6)
	s_barrier
	s_setprio 1
	v_mfma_f32_16x16x32_bf16 v[22:25], v[234:237], v[108:111], v[22:25]
	v_mfma_f32_16x16x32_bf16 v[50:53], v[242:245], v[108:111], v[50:53]
	v_mfma_f32_16x16x32_bf16 v[94:97], v[234:237], v[178:181], v[96:99]
	v_mfma_f32_16x16x32_bf16 v[98:101], v[242:245], v[178:181], v[100:103]
	v_mfma_f32_16x16x32_bf16 v[108:111], v[234:237], v[200:203], v[112:115]
	v_mfma_f32_16x16x32_bf16 v[112:115], v[242:245], v[200:203], v[116:119]
	v_mfma_f32_16x16x32_bf16 v[86:89], v[234:237], v[208:211], v[86:89]
	v_mfma_f32_16x16x32_bf16 v[90:93], v[242:245], v[208:211], v[90:93]
	v_mfma_f32_16x16x32_bf16 v[22:25], v[238:241], v[146:149], v[22:25]
	v_mfma_f32_16x16x32_bf16 v[50:53], v[246:249], v[146:149], v[50:53]
	v_mfma_f32_16x16x32_bf16 v[94:97], v[238:241], v[182:185], v[94:97]
	v_mfma_f32_16x16x32_bf16 v[98:101], v[246:249], v[182:185], v[98:101]
	v_mfma_f32_16x16x32_bf16 v[108:111], v[238:241], v[204:207], v[108:111]
	v_mfma_f32_16x16x32_bf16 v[112:115], v[246:249], v[204:207], v[112:115]
	v_mfma_f32_16x16x32_bf16 v[86:89], v[238:241], v[212:215], v[86:89]
	v_mfma_f32_16x16x32_bf16 v[90:93], v[246:249], v[212:215], v[90:93]
	s_setprio 0
	s_barrier
; #define PG8_STAGE(bufoff, gbase, voff) do { _Pragma("unroll") for (int _i = 0; _i < 2; ++_i) \
;         __builtin_amdgcn_global_load_lds((const unsigned*)((const char*)(gbase) + (voff)[_i]), (LAS unsigned*)(lds + (bufoff) + ldsw + _i * 8192), 16, 0, 0); } while (0)
; #define PG8_LDA(dst, b, h) do { _Pragma("unroll") for (int m = 0; m < 4; ++m) _Pragma("unroll") for (int k = 0; k < 2; ++k) dst[m][k] = *(const LAS bf16x8*)(lds + PG8_SA(b, h) + aoff + m * 2048 + k * 1024); } while (0)
; #define PG8_WAIT_V(n) asm volatile("s_waitcnt vmcnt(" #n ")" ::: "memory")
; #define PG8_WAIT_L(n) asm volatile("s_waitcnt lgkmcnt(" #n ")" ::: "memory")
; template <class Epi, class Sched>
; __device__ __forceinline__ void gemm_phase(LAS unsigned char* lds, const Gemm g, const Sched& S, const Epi& E) {
;     ...
;         for (int t = 0; t < nt; t += 2) {
;             const bool last = (t == nt - 2);
;             const char* a1 = cA + (size_t)(t + 1) * kstep;
;             const char* a2 = last ? nA : cA + (size_t)(t + 2) * kstep; const char* b2 = last ? nB : cB + (size_t)(t + 2) * kstep;
;             const char* a3 = a2 + kstep; const char* b3 = b2 + kstep;
;             PG8_LDB(B0, 0, 0); PG8_SCHED; PG8_LDA(At, 0, 0); PG8_STAGE(PG8_SA(1, 1), a1 + hstepA, voffA);
;             PG8_WAIT_L(8); PG8_BAR; PG8_WAIT_L(0); PG8_MMA(0, 0, At, B0); PG8_BAR; PG8_SCHED;
;             PG8_LDB(B1, 0, 1); PG8_STAGE(PG8_SB(0, 0), b2, voffB);
;             PG8_BAR; PG8_WAIT_L(0); PG8_MMA(0, 1, At, B1); PG8_BAR;
;             PG8_LDA(At, 0, 1); PG8_STAGE(PG8_SA(0, 0), a2, voffA);
;             PG8_BAR; PG8_WAIT_L(0); PG8_MMA(1, 0, At, B0); PG8_BAR; PG8_SCHED;
;             PG8_STAGE(PG8_SB(0, 1), b2 + hstepB, voffB);
;             PG8_WAIT_V(6); PG8_BAR; PG8_MMA(1, 1, At, B1); PG8_BAR;
;             PG8_LDB(B0, 1, 0); PG8_SCHED; PG8_LDA(At, 1, 0); PG8_STAGE(PG8_SA(0, 1), a2 + hstepA, voffA);
;             PG8_WAIT_L(8); PG8_BAR; PG8_WAIT_L(0); PG8_MMA(0, 0, At, B0); PG8_BAR; PG8_SCHED;
;             PG8_LDB(B1, 1, 1); PG8_STAGE(PG8_SB(1, 0), b3, voffB);
;             PG8_BAR; PG8_WAIT_L(0); PG8_MMA(0, 1, At, B1); PG8_BAR;
;             PG8_LDA(At, 1, 1); PG8_STAGE(PG8_SA(1, 0), a3, voffA);
;             PG8_BAR; PG8_WAIT_L(0); PG8_MMA(1, 0, At, B0); PG8_BAR; PG8_SCHED;
;             PG8_STAGE(PG8_SB(1, 1), b3 + hstepB, voffB);
;             PG8_WAIT_V(6); PG8_BAR; PG8_MMA(1, 1, At, B1); PG8_BAR;
	ds_read_b128 v[116:119], v10
	ds_read_b128 v[120:123], v10 offset:1024
	ds_read_b128 v[124:127], v10 offset:2048
	ds_read_b128 v[128:131], v10 offset:3072
	s_add_u32 s2, s2, 0x90280
	s_addc_u32 s3, s3, 0
	s_mov_b32 m0, s14
	v_lshl_add_u64 v[102:103], s[2:3], 0, v[134:135]
	ds_read_b128 v[142:145], v152
	ds_read_b128 v[146:149], v152 offset:1024
	ds_read_b128 v[174:177], v152 offset:2048
	ds_read_b128 v[178:181], v152 offset:3072
	ds_read_b128 v[182:185], v152 offset:4096
	ds_read_b128 v[200:203], v152 offset:5120
	ds_read_b128 v[204:207], v152 offset:6144
	ds_read_b128 v[208:211], v152 offset:7168
	global_load_lds_dwordx4 v[102:103], off
	v_lshl_add_u64 v[102:103], s[2:3], 0, v[138:139]
	s_mov_b32 m0, s0
	s_nop 0
	global_load_lds_dwordx4 v[102:103], off
	s_waitcnt lgkmcnt(8)
	s_barrier
	s_waitcnt lgkmcnt(0)
	s_setprio 1
	s_waitcnt lgkmcnt(0)
	v_mfma_f32_16x16x32_bf16 v[54:57], v[116:119], v[142:145], v[54:57]
	v_mfma_f32_16x16x32_bf16 v[58:61], v[124:127], v[142:145], v[58:61]
	v_mfma_f32_16x16x32_bf16 v[62:65], v[116:119], v[174:177], v[62:65]
	v_mfma_f32_16x16x32_bf16 v[66:69], v[124:127], v[174:177], v[66:69]
	v_mfma_f32_16x16x32_bf16 v[70:73], v[116:119], v[182:185], v[70:73]
	v_mfma_f32_16x16x32_bf16 v[74:77], v[124:127], v[182:185], v[74:77]
	v_mfma_f32_16x16x32_bf16 v[78:81], v[116:119], v[204:207], v[78:81]
	v_mfma_f32_16x16x32_bf16 v[82:85], v[124:127], v[204:207], v[82:85]
	v_mfma_f32_16x16x32_bf16 v[54:57], v[120:123], v[146:149], v[54:57]
	v_mfma_f32_16x16x32_bf16 v[58:61], v[128:131], v[146:149], v[58:61]
	v_mfma_f32_16x16x32_bf16 v[62:65], v[120:123], v[178:181], v[62:65]
	v_mfma_f32_16x16x32_bf16 v[66:69], v[128:131], v[178:181], v[66:69]
	v_mfma_f32_16x16x32_bf16 v[70:73], v[120:123], v[200:203], v[70:73]
	v_mfma_f32_16x16x32_bf16 v[74:77], v[128:131], v[200:203], v[74:77]
	v_mfma_f32_16x16x32_bf16 v[78:81], v[120:123], v[208:211], v[78:81]
	v_mfma_f32_16x16x32_bf16 v[82:85], v[128:131], v[208:211], v[82:85]
	s_setprio 0
	s_barrier
	s_mov_b32 m0, s7
	ds_read_b128 v[212:215], v11
	ds_read_b128 v[230:233], v11 offset:1024
	ds_read_b128 v[234:237], v11 offset:2048
	ds_read_b128 v[238:241], v11 offset:3072
	v_lshl_add_u64 v[10:11], s[30:31], 0, v[136:137]
	global_load_lds_dwordx4 v[10:11], off
	v_lshl_add_u64 v[150:151], s[30:31], 0, v[140:141]
	s_mov_b32 m0, s1
	s_nop 0
	global_load_lds_dwordx4 v[150:151], off
	s_barrier
	s_waitcnt lgkmcnt(0)
	s_setprio 1
	s_waitcnt lgkmcnt(0)
	v_mfma_f32_16x16x32_bf16 v[2:5], v[212:215], v[142:145], v[2:5]
	v_mfma_f32_16x16x32_bf16 v[26:29], v[234:237], v[142:145], v[26:29]
	v_mfma_f32_16x16x32_bf16 v[102:105], v[212:215], v[174:177], v[104:107]
	v_mfma_f32_16x16x32_bf16 v[30:33], v[234:237], v[174:177], v[30:33]
	v_mfma_f32_16x16x32_bf16 v[34:37], v[212:215], v[182:185], v[34:37]
	v_mfma_f32_16x16x32_bf16 v[38:41], v[234:237], v[182:185], v[38:41]
	v_mfma_f32_16x16x32_bf16 v[42:45], v[212:215], v[204:207], v[42:45]
	v_mfma_f32_16x16x32_bf16 v[2:5], v[230:233], v[146:149], v[2:5]
	v_mfma_f32_16x16x32_bf16 v[26:29], v[238:241], v[146:149], v[26:29]
	v_mfma_f32_16x16x32_bf16 v[142:145], v[230:233], v[178:181], v[102:105]
	v_mfma_f32_16x16x32_bf16 v[30:33], v[238:241], v[178:181], v[30:33]
	v_mfma_f32_16x16x32_bf16 v[34:37], v[230:233], v[200:203], v[34:37]
	v_mfma_f32_16x16x32_bf16 v[38:41], v[238:241], v[200:203], v[38:41]
	v_mfma_f32_16x16x32_bf16 v[146:149], v[230:233], v[208:211], v[42:45]
	v_mfma_f32_16x16x32_bf16 v[42:45], v[234:237], v[204:207], v[46:49]
	v_mfma_f32_16x16x32_bf16 v[174:177], v[238:241], v[208:211], v[42:45]
	s_setprio 0
	s_mov_b32 m0, s45
	v_lshl_add_u64 v[186:187], s[28:29], 0, v[134:135]
	s_barrier
	s_nop 2
	ds_read_b128 v[42:45], v152 offset:16384
	ds_read_b128 v[46:49], v152 offset:17408
	ds_read_b128 v[102:105], v152 offset:18432
	ds_read_b128 v[178:181], v152 offset:19456
	ds_read_b128 v[182:185], v152 offset:20480
	ds_read_b128 v[200:203], v152 offset:21504
	ds_read_b128 v[204:207], v152 offset:22528
	ds_read_b128 v[208:211], v152 offset:23552
	global_load_lds_dwordx4 v[186:187], off
	v_lshl_add_u64 v[198:199], s[28:29], 0, v[138:139]
	s_mov_b32 m0, s46
	s_nop 0
	global_load_lds_dwordx4 v[198:199], off
	s_barrier
	s_waitcnt lgkmcnt(0)
	s_setprio 1
	s_waitcnt lgkmcnt(0)
	v_mfma_f32_16x16x32_bf16 v[6:9], v[116:119], v[42:45], v[6:9]
	v_mfma_f32_16x16x32_bf16 v[154:157], v[124:127], v[42:45], v[154:157]
	v_mfma_f32_16x16x32_bf16 v[158:161], v[116:119], v[102:105], v[158:161]
	v_mfma_f32_16x16x32_bf16 v[14:17], v[116:119], v[204:207], v[14:17]
	v_mfma_f32_16x16x32_bf16 v[18:21], v[124:127], v[204:207], v[18:21]
	v_mfma_f32_16x16x32_bf16 v[6:9], v[120:123], v[46:49], v[6:9]
	v_mfma_f32_16x16x32_bf16 v[154:157], v[128:131], v[46:49], v[154:157]
	v_mfma_f32_16x16x32_bf16 v[158:161], v[120:123], v[178:181], v[158:161]
	v_mfma_f32_16x16x32_bf16 v[162:165], v[124:127], v[102:105], v[162:165]
	v_mfma_f32_16x16x32_bf16 v[166:169], v[116:119], v[182:185], v[166:169]
	v_mfma_f32_16x16x32_bf16 v[170:173], v[124:127], v[182:185], v[170:173]
	v_mfma_f32_16x16x32_bf16 v[14:17], v[120:123], v[208:211], v[14:17]
	v_mfma_f32_16x16x32_bf16 v[18:21], v[128:131], v[208:211], v[18:21]
	v_mfma_f32_16x16x32_bf16 v[162:165], v[128:131], v[178:181], v[162:165]
	v_mfma_f32_16x16x32_bf16 v[166:169], v[120:123], v[200:203], v[166:169]
	v_mfma_f32_16x16x32_bf16 v[170:173], v[128:131], v[200:203], v[170:173]
	s_setprio 0
	s_barrier
	s_add_u32 s0, s30, 0x18000
	s_addc_u32 s1, s31, 0
	s_mov_b32 m0, s8
	v_lshl_add_u64 v[106:107], s[0:1], 0, v[136:137]
	global_load_lds_dwordx4 v[106:107], off
	v_lshl_add_u64 v[106:107], s[0:1], 0, v[140:141]
	s_mov_b32 m0, s6
	s_nop 0
	global_load_lds_dwordx4 v[106:107], off
	s_waitcnt vmcnt(6)
	s_barrier
; #define PG8_STAGE(bufoff, gbase, voff) do { _Pragma("unroll") for (int _i = 0; _i < 2; ++_i) \
;         __builtin_amdgcn_global_load_lds((const unsigned*)((const char*)(gbase) + (voff)[_i]), (LAS unsigned*)(lds + (bufoff) + ldsw + _i * 8192), 16, 0, 0); } while (0)
; #define PG8_LDA(dst, b, h) do { _Pragma("unroll") for (int m = 0; m < 4; ++m) _Pragma("unroll") for (int k = 0; k < 2; ++k) dst[m][k] = *(const LAS bf16x8*)(lds + PG8_SA(b, h) + aoff + m * 2048 + k * 1024); } while (0)
; #define PG8_LDB(dst, b, h) do { _Pragma("unroll") for (int n = 0; n < 2; ++n) _Pragma("unroll") for (int k = 0; k < 2; ++k) dst[n][k] = *(const LAS bf16x8*)(lds + PG8_SB(b, h) + boff + n * 2048 + k * 1024); } while (0)
; #define PG8_MMA(ai, bj, At, Bt) do { __builtin_amdgcn_s_setprio(1); _Pragma("unroll") for (int m = 0; m < 4; ++m) _Pragma("unroll") for (int n = 0; n < 2; ++n) _Pragma("unroll") for (int k = 0; k < 2; ++k) \
;         acc[ai][bj][m][n] = __builtin_amdgcn_mfma_f32_16x16x32_bf16(Bt[n][k], At[m][k], acc[ai][bj][m][n], 0, 0, 0); __builtin_amdgcn_s_setprio(0); } while (0)
; #define PG8_WAIT_V(n) asm volatile("s_waitcnt vmcnt(" #n ")" ::: "memory")
; #define PG8_WAIT_L(n) asm volatile("s_waitcnt lgkmcnt(" #n ")" ::: "memory")
; #define PG8_BAR __builtin_amdgcn_s_barrier()
; #define PG8_SCHED __builtin_amdgcn_sched_barrier(0)
; template <class Epi, class Sched>
; __device__ __forceinline__ void gemm_phase(LAS unsigned char* lds, const Gemm g, const Sched& S, const Epi& E) {
;     ...
;             PG8_BAR; PG8_WAIT_L(0); PG8_MMA(1, 0, At, B0); PG8_BAR; PG8_SCHED;
;             PG8_STAGE(PG8_SB(0, 1), b2 + hstepB, voffB);
;             PG8_WAIT_V(6); PG8_BAR; PG8_MMA(1, 1, At, B1); PG8_BAR;
;             PG8_LDB(B0, 1, 0); PG8_SCHED; PG8_LDA(At, 1, 0); PG8_STAGE(PG8_SA(0, 1), a2 + hstepA, voffA);
;             PG8_WAIT_L(8); PG8_BAR; PG8_WAIT_L(0); PG8_MMA(0, 0, At, B0); PG8_BAR; PG8_SCHED;
;             PG8_LDB(B1, 1, 1); PG8_STAGE(PG8_SB(1, 0), b3, voffB);
;             PG8_BAR; PG8_WAIT_L(0); PG8_MMA(0, 1, At, B1); PG8_BAR;
;             PG8_LDA(At, 1, 1); PG8_STAGE(PG8_SA(1, 0), a3, voffA);
;             PG8_BAR; PG8_WAIT_L(0); PG8_MMA(1, 0, At, B0); PG8_BAR; PG8_SCHED;
;             PG8_STAGE(PG8_SB(1, 1), b3 + hstepB, voffB);
;             PG8_WAIT_V(6); PG8_BAR; PG8_MMA(1, 1, At, B1); PG8_BAR;
	s_setprio 1
	v_mfma_f32_16x16x32_bf16 v[22:25], v[212:215], v[42:45], v[22:25]
	v_mfma_f32_16x16x32_bf16 v[42:45], v[234:237], v[42:45], v[50:53]
	v_mfma_f32_16x16x32_bf16 v[130:133], v[238:241], v[46:49], v[42:45]
	v_mfma_f32_16x16x32_bf16 v[42:45], v[212:215], v[102:105], v[94:97]
	v_mfma_f32_16x16x32_bf16 v[242:245], v[230:233], v[178:181], v[42:45]
	v_mfma_f32_16x16x32_bf16 v[42:45], v[234:237], v[102:105], v[98:101]
	v_mfma_f32_16x16x32_bf16 v[178:181], v[238:241], v[178:181], v[42:45]
	v_mfma_f32_16x16x32_bf16 v[42:45], v[212:215], v[182:185], v[108:111]
	v_mfma_f32_16x16x32_bf16 v[246:249], v[230:233], v[200:203], v[42:45]
	v_mfma_f32_16x16x32_bf16 v[42:45], v[234:237], v[182:185], v[112:115]
	v_mfma_f32_16x16x32_bf16 v[182:185], v[238:241], v[200:203], v[42:45]
	v_mfma_f32_16x16x32_bf16 v[42:45], v[212:215], v[204:207], v[86:89]
	v_mfma_f32_16x16x32_bf16 v[22:25], v[230:233], v[46:49], v[22:25]
	v_mfma_f32_16x16x32_bf16 v[200:203], v[230:233], v[208:211], v[42:45]
	v_mfma_f32_16x16x32_bf16 v[42:45], v[234:237], v[204:207], v[90:93]
	v_mfma_f32_16x16x32_bf16 v[204:207], v[238:241], v[208:211], v[42:45]
	s_setprio 0
	s_barrier
	ds_read_b128 v[208:211], v12
	ds_read_b128 v[212:215], v12 offset:1024
	ds_read_b128 v[230:233], v12 offset:2048
	ds_read_b128 v[234:237], v12 offset:3072
	s_add_u32 s0, s28, 0x90000
	s_addc_u32 s1, s29, 0
	s_mov_b32 m0, s47
	v_lshl_add_u64 v[98:99], s[0:1], 0, v[134:135]
	ds_read_b128 v[42:45], v152 offset:32768
	ds_read_b128 v[46:49], v152 offset:33792
	ds_read_b128 v[50:53], v152 offset:34816
	ds_read_b128 v[86:89], v152 offset:35840
	ds_read_b128 v[90:93], v152 offset:36864
	ds_read_b128 v[94:97], v152 offset:37888
	ds_read_b128 v[238:241], v152 offset:38912
	ds_read_b128 v[250:253], v152 offset:39936
	global_load_lds_dwordx4 v[98:99], off
	v_lshl_add_u64 v[98:99], s[0:1], 0, v[138:139]
	s_mov_b32 m0, s48
	s_nop 0
	global_load_lds_dwordx4 v[98:99], off
	s_waitcnt lgkmcnt(8)
	s_barrier
	s_waitcnt lgkmcnt(0)
	s_setprio 1
	s_waitcnt lgkmcnt(0)
	v_mfma_f32_16x16x32_bf16 v[54:57], v[208:211], v[42:45], v[54:57]
	v_mfma_f32_16x16x32_bf16 v[126:129], v[212:215], v[46:49], v[54:57]
	v_mfma_f32_16x16x32_bf16 v[54:57], v[230:233], v[42:45], v[58:61]
	v_mfma_f32_16x16x32_bf16 v[122:125], v[234:237], v[46:49], v[54:57]
	v_mfma_f32_16x16x32_bf16 v[54:57], v[208:211], v[50:53], v[62:65]
	v_mfma_f32_16x16x32_bf16 v[118:121], v[212:215], v[86:89], v[54:57]
	v_mfma_f32_16x16x32_bf16 v[54:57], v[230:233], v[50:53], v[66:69]
	v_mfma_f32_16x16x32_bf16 v[114:117], v[234:237], v[86:89], v[54:57]
	v_mfma_f32_16x16x32_bf16 v[54:57], v[208:211], v[90:93], v[70:73]
	v_mfma_f32_16x16x32_bf16 v[110:113], v[212:215], v[94:97], v[54:57]
	v_mfma_f32_16x16x32_bf16 v[54:57], v[230:233], v[90:93], v[74:77]
	v_mfma_f32_16x16x32_bf16 v[106:109], v[234:237], v[94:97], v[54:57]
	v_mfma_f32_16x16x32_bf16 v[54:57], v[208:211], v[238:241], v[78:81]
	v_mfma_f32_16x16x32_bf16 v[102:105], v[212:215], v[250:253], v[54:57]
	v_mfma_f32_16x16x32_bf16 v[54:57], v[230:233], v[238:241], v[82:85]
	v_mfma_f32_16x16x32_bf16 v[98:101], v[234:237], v[250:253], v[54:57]
	s_setprio 0
	s_barrier
	s_mov_b32 m0, s34
	v_lshl_add_u64 v[10:11], v[10:11], 0, s[90:91]
	ds_read_b128 v[226:229], v13
	ds_read_b128 v[222:225], v13 offset:1024
	ds_read_b128 v[190:193], v13 offset:2048
	ds_read_b128 v[194:197], v13 offset:3072
	global_load_lds_dwordx4 v[10:11], off
	v_lshl_add_u64 v[10:11], v[150:151], 0, s[90:91]
	s_mov_b32 m0, s9
	s_nop 0
	global_load_lds_dwordx4 v[10:11], off
	s_barrier
	s_waitcnt lgkmcnt(0)
	s_setprio 1
	s_waitcnt lgkmcnt(0)
	v_mfma_f32_16x16x32_bf16 v[2:5], v[226:229], v[42:45], v[2:5]
	v_mfma_f32_16x16x32_bf16 v[62:65], v[222:225], v[46:49], v[2:5]
	v_mfma_f32_16x16x32_bf16 v[2:5], v[190:193], v[42:45], v[26:29]
	v_mfma_f32_16x16x32_bf16 v[58:61], v[194:197], v[46:49], v[2:5]
	v_mfma_f32_16x16x32_bf16 v[2:5], v[226:229], v[50:53], v[142:145]
	v_mfma_f32_16x16x32_bf16 v[54:57], v[222:225], v[86:89], v[2:5]
	v_mfma_f32_16x16x32_bf16 v[2:5], v[190:193], v[50:53], v[30:33]
	v_mfma_f32_16x16x32_bf16 v[50:53], v[194:197], v[86:89], v[2:5]
	v_mfma_f32_16x16x32_bf16 v[2:5], v[226:229], v[90:93], v[34:37]
	v_mfma_f32_16x16x32_bf16 v[46:49], v[222:225], v[94:97], v[2:5]
	v_mfma_f32_16x16x32_bf16 v[2:5], v[190:193], v[90:93], v[38:41]
	v_mfma_f32_16x16x32_bf16 v[42:45], v[194:197], v[94:97], v[2:5]
	v_mfma_f32_16x16x32_bf16 v[2:5], v[226:229], v[238:241], v[146:149]
	v_mfma_f32_16x16x32_bf16 v[38:41], v[222:225], v[250:253], v[2:5]
	v_mfma_f32_16x16x32_bf16 v[2:5], v[190:193], v[238:241], v[174:177]
	v_mfma_f32_16x16x32_bf16 v[34:37], v[194:197], v[250:253], v[2:5]
	s_setprio 0
	s_mov_b32 m0, s49
	v_lshl_add_u64 v[26:27], v[186:187], 0, s[90:91]
	s_barrier
	s_nop 2
	ds_read_b128 v[2:5], v152 offset:49152
	ds_read_b128 v[10:13], v152 offset:50176
	ds_read_b128 v[142:145], v152 offset:51200
	ds_read_b128 v[146:149], v152 offset:52224
	ds_read_b128 v[174:177], v152 offset:53248
	ds_read_b128 v[238:241], v152 offset:54272
	ds_read_b128 v[250:253], v152 offset:55296
	ds_read_b128 v[216:219], v152 offset:56320
	global_load_lds_dwordx4 v[26:27], off
	v_lshl_add_u64 v[26:27], v[198:199], 0, s[90:91]
	s_mov_b32 m0, s58
	s_nop 0
	global_load_lds_dwordx4 v[26:27], off
	s_barrier
; __device__ __forceinline__ int opaque_tid() { int t = threadIdx.x; asm volatile("" : "+v"(t)); return t; }
; #define PG8_WAIT_V(n) asm volatile("s_waitcnt vmcnt(" #n ")" ::: "memory")
; #define PG8_WAIT_L(n) asm volatile("s_waitcnt lgkmcnt(" #n ")" ::: "memory")
; template <class Epi, class Sched>
; __device__ __forceinline__ void gemm_phase(LAS unsigned char* lds, const Gemm g, const Sched& S, const Epi& E) {
;     ...
;             PG8_WAIT_V(6); PG8_BAR; PG8_MMA(1, 1, At, B1); PG8_BAR;
;             PG8_LDB(B0, 1, 0); PG8_SCHED; PG8_LDA(At, 1, 0); PG8_STAGE(PG8_SA(0, 1), a2 + hstepA, voffA);
;             PG8_WAIT_L(8); PG8_BAR; PG8_WAIT_L(0); PG8_MMA(0, 0, At, B0); PG8_BAR; PG8_SCHED;
;             PG8_LDB(B1, 1, 1); PG8_STAGE(PG8_SB(1, 0), b3, voffB);
;             PG8_BAR; PG8_WAIT_L(0); PG8_MMA(0, 1, At, B1); PG8_BAR;
;             PG8_LDA(At, 1, 1); PG8_STAGE(PG8_SA(1, 0), a3, voffA);
;             PG8_BAR; PG8_WAIT_L(0); PG8_MMA(1, 0, At, B0); PG8_BAR; PG8_SCHED;
;             PG8_STAGE(PG8_SB(1, 1), b3 + hstepB, voffB);
;             PG8_WAIT_V(6); PG8_BAR; PG8_MMA(1, 1, At, B1); PG8_BAR;
;     __device__ __forceinline__ void operator()(const f32x4 (&acc)[2][2][4][2], const Unit& u, int wr, int wc, int fr, int fq) const {
;         { const int t_ = opaque_tid(); wr = t_ >> 8; wc = (t_ >> 6) & 3; fr = t_ & 15; fq = (t_ >> 4) & 3; }
;         const int row0 = u.pm * 256 + wr * 64 + fr;
; #pragma unroll
;         for (int bj = 0; bj < 2; ++bj) {
;             const int cg0 = u.pn * 256 + bj * 128 + wc * 32;
;             if (cg0 >= 896) continue;
; #pragma unroll
;             for (int ai = 0; ai < 2; ++ai)
; #pragma unroll
;                 for (int m = 0; m < 4; ++m) {
;                     __builtin_amdgcn_sched_barrier(0);
;                     const int row = row0 + ai * 128 + m * 16;
;                     float v[8];
;                     if (cg0 < 384) {
;                         const float rs = RSTD[row * 2];
; #pragma unroll
;                         for (int n = 0; n < 2; ++n)
; #pragma unroll
;                             for (int j = 0; j < 4; ++j) v[4 * n + j] = acc[ai][bj][m][n][j] * rs;
;                         const int d0 = cg0 % 96;
;                         if (d0 == 64) {
;                             const bool lat = row < RL; const int t = row & 8191; const int pos = (fq >> 1) ? (t & 63) : (t >> 6); const bool isx2 = fq & 1;
	s_waitcnt lgkmcnt(0)
	s_setprio 1
	s_waitcnt lgkmcnt(0)
	v_mfma_f32_16x16x32_bf16 v[6:9], v[208:211], v[2:5], v[6:9]
	v_mfma_f32_16x16x32_bf16 v[94:97], v[212:215], v[10:13], v[6:9]
	v_mfma_f32_16x16x32_bf16 v[6:9], v[230:233], v[2:5], v[154:157]
	v_mfma_f32_16x16x32_bf16 v[90:93], v[234:237], v[10:13], v[6:9]
	v_mfma_f32_16x16x32_bf16 v[6:9], v[208:211], v[142:145], v[158:161]
	v_mfma_f32_16x16x32_bf16 v[86:89], v[212:215], v[146:149], v[6:9]
	v_mfma_f32_16x16x32_bf16 v[6:9], v[230:233], v[142:145], v[162:165]
	v_mfma_f32_16x16x32_bf16 v[82:85], v[234:237], v[146:149], v[6:9]
	v_mfma_f32_16x16x32_bf16 v[6:9], v[208:211], v[174:177], v[166:169]
	v_mfma_f32_16x16x32_bf16 v[78:81], v[212:215], v[238:241], v[6:9]
	v_mfma_f32_16x16x32_bf16 v[6:9], v[230:233], v[174:177], v[170:173]
	v_mfma_f32_16x16x32_bf16 v[74:77], v[234:237], v[238:241], v[6:9]
	v_mfma_f32_16x16x32_bf16 v[6:9], v[208:211], v[250:253], v[14:17]
	v_mfma_f32_16x16x32_bf16 v[70:73], v[212:215], v[216:219], v[6:9]
	v_mfma_f32_16x16x32_bf16 v[6:9], v[230:233], v[250:253], v[18:21]
	v_mfma_f32_16x16x32_bf16 v[66:69], v[234:237], v[216:219], v[6:9]
	s_setprio 0
	s_barrier
	s_add_u32 s0, s30, 0x18080
	s_addc_u32 s1, s31, 0
	s_mov_b32 m0, s35
	s_nop 1
	v_lshl_add_u64 v[6:7], s[0:1], 0, v[136:137]
	global_load_lds_dwordx4 v[6:7], off
	v_lshl_add_u64 v[6:7], s[0:1], 0, v[140:141]
	s_mov_b32 m0, s15
	s_nop 0
	global_load_lds_dwordx4 v[6:7], off
	s_waitcnt vmcnt(6)
	s_barrier
	s_setprio 1
	v_mfma_f32_16x16x32_bf16 v[6:9], v[226:229], v[2:5], v[22:25]
	v_mfma_f32_16x16x32_bf16 v[2:5], v[190:193], v[2:5], v[130:133]
	v_mfma_f32_16x16x32_bf16 v[26:29], v[194:197], v[10:13], v[2:5]
	v_mfma_f32_16x16x32_bf16 v[2:5], v[226:229], v[142:145], v[242:245]
	v_mfma_f32_16x16x32_bf16 v[22:25], v[222:225], v[146:149], v[2:5]
	v_mfma_f32_16x16x32_bf16 v[2:5], v[190:193], v[142:145], v[178:181]
	v_mfma_f32_16x16x32_bf16 v[18:21], v[194:197], v[146:149], v[2:5]
	v_mfma_f32_16x16x32_bf16 v[2:5], v[226:229], v[174:177], v[246:249]
	v_mfma_f32_16x16x32_bf16 v[14:17], v[222:225], v[238:241], v[2:5]
	v_mfma_f32_16x16x32_bf16 v[2:5], v[190:193], v[174:177], v[182:185]
	v_mfma_f32_16x16x32_bf16 v[30:33], v[222:225], v[10:13], v[6:9]
	v_mfma_f32_16x16x32_bf16 v[10:13], v[194:197], v[238:241], v[2:5]
	v_mfma_f32_16x16x32_bf16 v[2:5], v[226:229], v[250:253], v[200:203]
	v_mfma_f32_16x16x32_bf16 v[6:9], v[222:225], v[216:219], v[2:5]
	v_mfma_f32_16x16x32_bf16 v[2:5], v[190:193], v[250:253], v[204:207]
	v_mfma_f32_16x16x32_bf16 v[2:5], v[194:197], v[216:219], v[2:5]
	s_setprio 0
	v_mov_b32_e32 v130, v189
	s_barrier
	s_lshl_b32 s63, s12, 8
	v_and_b32_e32 v157, 15, v130
	v_ashrrev_i32_e32 v132, 2, v130
	v_lshrrev_b32_e32 v133, 1, v130
	v_and_b32_e32 v132, 0xffffffc0, v132
	v_and_b32_e32 v154, 0x60, v133
	v_lshl_or_b32 v133, s13, 8, v157
	v_add_u32_e32 v144, v133, v132
	v_bfe_u32 v131, v130, 4, 2
	v_and_b32_e32 v130, 16, v130
	v_or_b32_e32 v142, s63, v154
	s_movk_i32 s0, 0x380
	v_lshlrev_b32_e32 v146, 1, v144
	v_cmp_lt_u32_e64 s[8:9], 63, v154
	v_lshlrev_b32_e32 v159, 3, v131
	v_cmp_gt_u32_e64 s[6:7], 2, v131
	v_cmp_eq_u32_e32 vcc, 0, v130
	v_or_b32_e32 v156, 16, v157
	v_or_b32_e32 v155, 32, v157
	v_or_b32_e32 v153, 48, v157
	v_cmp_gt_i32_e64 s[10:11], s0, v142
	v_bfe_u32 v158, v144, 6, 7
	v_ashrrev_i32_e32 v147, 31, v146
	s_and_saveexec_b64 s[34:35], s[10:11]
	s_cbranch_execz .LBB0_388
	s_movk_i32 s0, 0x17f
	v_cmp_lt_i32_e64 s[12:13], s0, v142
	s_add_i32 s0, s63, 0xfffffe80
	s_lshr_b32 s64, s0, 1
	s_lshr_b32 s0, s0, 7
	s_mul_i32 s88, s0, 0x60
	s_mov_b32 s0, 0x2aaaaaab
	v_mul_hi_i32 v130, v142, s0
	v_lshrrev_b32_e32 v131, 31, v130
	v_lshrrev_b32_e32 v130, 4, v130
	v_add_u32_e32 v130, v130, v131
	s_movk_i32 s0, 0x60
	v_mul_lo_u32 v130, v130, s0
	v_sub_u32_e32 v130, v142, v130
	v_cmp_ne_u32_e64 s[10:11], 64, v130
	v_lshl_add_u64 v[150:151], v[146:147], 2, s[24:25]
	global_load_dwordx2 v[222:223], v[150:151], off
	global_load_dwordx2 v[224:225], v[150:151], off offset:128
	global_load_dwordx2 v[226:227], v[150:151], off offset:256
	global_load_dwordx2 v[228:229], v[150:151], off offset:384
	global_load_dwordx2 v[230:231], v[150:151], off offset:1024
	global_load_dwordx2 v[232:233], v[150:151], off offset:1152
	global_load_dwordx2 v[234:235], v[150:151], off offset:1280
	global_load_dwordx2 v[236:237], v[150:151], off offset:1408
	s_waitcnt vmcnt(0)
	s_and_saveexec_b64 s[0:1], s[12:13]
	s_xor_b64 s[0:1], exec, s[0:1]
	s_cbranch_execz .LBB0_311
	v_mov_b32_e32 v130, v223
	v_ashrrev_i32_e32 v145, 31, v144
	s_and_saveexec_b64 s[2:3], s[8:9]
	s_xor_b64 s[2:3], exec, s[2:3]
	s_cbranch_execz .LBB0_308
	v_lshlrev_b64 v[132:133], 9, v[144:145]
	v_lshl_add_u64 v[132:133], s[22:23], 0, v[132:133]
	s_lshl_b32 s14, s64, 1
	s_mov_b32 s15, s89
	v_lshl_add_u64 v[132:133], v[132:133], 0, s[14:15]
	v_lshlrev_b32_e32 v148, 1, v154
	v_mov_b32_e32 v149, v0
	s_movk_i32 s14, 0xff80
	v_lshl_add_u64 v[132:133], v[132:133], 0, v[148:149]
	s_mov_b32 s15, -1
	v_lshl_add_u64 v[148:149], v[132:133], 0, s[14:15]

; __device__ __forceinline__ unsigned cvt_pk_bf16(float lo, float hi) { const f32x2_ v = {lo, hi}; return __builtin_bit_cast(unsigned, __builtin_convertvector(v, bf16x2_)); }
;     __device__ __forceinline__ void operator()(const f32x4 (&acc)[2][2][4][2], const Unit& u, int wr, int wc, int fr, int fq) const {
;     ...
;                     if (cg0 < 384) {
;                         const float rs = RSTD[row * 2];
; #pragma unroll
;                         for (int n = 0; n < 2; ++n)
; #pragma unroll
;                             for (int j = 0; j < 4; ++j) v[4 * n + j] = acc[ai][bj][m][n][j] * rs;
;                         const int d0 = cg0 % 96;
;                         if (d0 == 64) {
;                             const bool lat = row < RL; const int t = row & 8191; const int pos = (fq >> 1) ? (t & 63) : (t >> 6); const bool isx2 = fq & 1;
; #pragma unroll
;                             for (int e = 0; e < 8; ++e) {
;                                 const float pr = shflx(v[e], 16);
;                                 const float2 cs = RT[pos * 8 + e];
;                                 const float r = isx2 ? (pr * cs.y + v[e] * cs.x) : (v[e] * cs.x - pr * cs.y);
;                                 v[e] = lat ? r : v[e];
;                             }
;                         }
;                         u32x4 w; w.x = cvt_pk_bf16(v[0], v[1]); w.y = cvt_pk_bf16(v[2], v[3]); w.z = cvt_pk_bf16(v[4], v[5]); w.w = cvt_pk_bf16(v[6], v[7]);
;                         *(u32x4*)(MQ + (size_t)row * 384 + cg0 + 8 * fq) = w;
.LBB0_311:
	s_or_saveexec_b64 s[2:3], s[0:1]
	v_ashrrev_i32_e32 v143, 31, v142
	s_xor_b64 exec, exec, s[2:3]
	s_cbranch_execz .LBB0_315
	v_mov_b32_e32 v130, v222
	s_waitcnt vmcnt(0)
	v_pk_mul_f32 v[126:127], v[126:127], v[130:131] op_sel_hi:[1,0]
	v_pk_mul_f32 v[128:129], v[128:129], v[130:131] op_sel_hi:[1,0]
	v_pk_mul_f32 v[122:123], v[122:123], v[130:131] op_sel_hi:[1,0]
	v_pk_mul_f32 v[124:125], v[124:125], v[130:131] op_sel_hi:[1,0]
	s_and_saveexec_b64 s[0:1], s[10:11]
	s_xor_b64 s[0:1], exec, s[0:1]
	s_andn2_saveexec_b64 s[36:37], s[0:1]
	s_cbranch_execz .LBB0_314
	v_mov_b32_e32 v131, v220
	v_cndmask_b32_e64 v130, v157, v158, s[6:7]
	v_lshlrev_b32_e32 v131, 2, v131
	v_xor_b32_e32 v131, 64, v131
	v_lshlrev_b32_e32 v133, 6, v130
	ds_bpermute_b32 v132, v131, v126
	global_load_dwordx2 v[174:175], v133, s[26:27]
	global_load_dwordx2 v[176:177], v133, s[26:27] offset:8
	global_load_dwordx2 v[178:179], v133, s[26:27] offset:16
	global_load_dwordx2 v[180:181], v133, s[26:27] offset:24
	global_load_dwordx2 v[182:183], v133, s[26:27] offset:32
	global_load_dwordx2 v[184:185], v133, s[26:27] offset:40
	global_load_dwordx2 v[208:209], v133, s[26:27] offset:48
	global_load_dwordx2 v[210:211], v133, s[26:27] offset:56
	v_cmp_gt_i32_e64 s[14:15], s95, v144
	s_waitcnt vmcnt(7) lgkmcnt(0)
	v_mul_f32_e32 v131, v175, v132
	v_cndmask_b32_e64 v131, v131, -v131, vcc
	v_fmac_f32_e32 v131, v126, v174
	v_mov_b32_e32 v130, v220
	v_cndmask_b32_e64 v126, v126, v131, s[14:15]
	v_lshlrev_b32_e32 v130, 2, v130
	v_xor_b32_e32 v130, 64, v130
	ds_bpermute_b32 v132, v130, v127
	s_waitcnt vmcnt(6) lgkmcnt(0)
	v_mul_f32_e32 v131, v177, v132
	v_cndmask_b32_e64 v131, v131, -v131, vcc
	v_fmac_f32_e32 v131, v127, v176
	v_mov_b32_e32 v130, v220
	v_cndmask_b32_e64 v127, v127, v131, s[14:15]
	v_lshlrev_b32_e32 v130, 2, v130
	v_xor_b32_e32 v130, 64, v130
	ds_bpermute_b32 v132, v130, v128
	s_waitcnt vmcnt(5) lgkmcnt(0)
	v_mul_f32_e32 v131, v179, v132
	v_cndmask_b32_e64 v131, v131, -v131, vcc
	v_fmac_f32_e32 v131, v128, v178
	v_mov_b32_e32 v130, v220
	v_cndmask_b32_e64 v128, v128, v131, s[14:15]
	v_lshlrev_b32_e32 v130, 2, v130
	v_xor_b32_e32 v130, 64, v130
	ds_bpermute_b32 v132, v130, v129
	s_waitcnt vmcnt(4) lgkmcnt(0)
	v_mul_f32_e32 v131, v181, v132
	v_cndmask_b32_e64 v131, v131, -v131, vcc
	v_fmac_f32_e32 v131, v129, v180
	v_mov_b32_e32 v130, v220
	v_cndmask_b32_e64 v129, v129, v131, s[14:15]
	v_lshlrev_b32_e32 v130, 2, v130
	v_xor_b32_e32 v130, 64, v130
	ds_bpermute_b32 v132, v130, v122
	s_waitcnt vmcnt(3) lgkmcnt(0)
	v_mul_f32_e32 v131, v183, v132
	v_cndmask_b32_e64 v131, v131, -v131, vcc
	v_fmac_f32_e32 v131, v122, v182
	v_mov_b32_e32 v130, v220
	v_cndmask_b32_e64 v122, v122, v131, s[14:15]
	v_lshlrev_b32_e32 v130, 2, v130
	v_xor_b32_e32 v130, 64, v130
	ds_bpermute_b32 v132, v130, v123
	s_waitcnt vmcnt(2) lgkmcnt(0)
	v_mul_f32_e32 v131, v185, v132
	v_cndmask_b32_e64 v131, v131, -v131, vcc
	v_fmac_f32_e32 v131, v123, v184
	v_mov_b32_e32 v130, v220
	v_cndmask_b32_e64 v123, v123, v131, s[14:15]
	v_lshlrev_b32_e32 v130, 2, v130
	v_xor_b32_e32 v130, 64, v130
	ds_bpermute_b32 v132, v130, v124
	s_waitcnt vmcnt(1) lgkmcnt(0)
	v_mul_f32_e32 v131, v209, v132
	v_cndmask_b32_e64 v131, v131, -v131, vcc
	v_fmac_f32_e32 v131, v124, v208
	v_mov_b32_e32 v130, v220
	v_cndmask_b32_e64 v124, v124, v131, s[14:15]
	v_lshlrev_b32_e32 v130, 2, v130
	v_xor_b32_e32 v130, 64, v130
	ds_bpermute_b32 v132, v130, v125
	s_waitcnt vmcnt(0) lgkmcnt(0)
	v_mul_f32_e32 v131, v211, v132
	v_cndmask_b32_e64 v131, v131, -v131, vcc
	v_fmac_f32_e32 v131, v125, v210
	v_cndmask_b32_e64 v125, v125, v131, s[14:15]

; __device__ __forceinline__ unsigned cvt_pk_bf16(float lo, float hi) { const f32x2_ v = {lo, hi}; return __builtin_bit_cast(unsigned, __builtin_convertvector(v, bf16x2_)); }
;     __device__ __forceinline__ void operator()(const f32x4 (&acc)[2][2][4][2], const Unit& u, int wr, int wc, int fr, int fq) const {
;     ...
;                     const int row = row0 + ai * 128 + m * 16;
;                     float v[8];
;                     if (cg0 < 384) {
;                         const float rs = RSTD[row * 2];
; #pragma unroll
;                         for (int n = 0; n < 2; ++n)
; #pragma unroll
;                             for (int j = 0; j < 4; ++j) v[4 * n + j] = acc[ai][bj][m][n][j] * rs;
;     ...
;                         *(u32x4*)(MQ + (size_t)row * 384 + cg0 + 8 * fq) = w;
;                     } else {
;                         const float rs = RSTD[row * 2 + 1];
; #pragma unroll
;                         for (int n = 0; n < 2; ++n)
; #pragma unroll
;                             for (int j = 0; j < 4; ++j) v[4 * n + j] = acc[ai][bj][m][n][j] * rs;
;                         const int cp = cg0 - 384, hd = cp >> 7, d0 = cp & 127;
;                         u32x4 w; w.x = cvt_pk_bf16(v[0], v[1]); w.y = cvt_pk_bf16(v[2], v[3]); w.z = cvt_pk_bf16(v[4], v[5]); w.w = cvt_pk_bf16(v[6], v[7]);
;                         if (d0 < 64) *(u32x4*)(MK + (size_t)row * 384 + hd * 96 + d0 + 8 * fq) = w;
;                         else *(u32x4*)(MV + (size_t)row * 256 + hd * 64 + (d0 - 64) + 8 * fq) = w;
.LBB0_315:
	s_or_b64 exec, exec, s[2:3]
	v_lshlrev_b32_e32 v126, 1, v159
	v_mov_b32_e32 v127, v0
	v_lshl_add_u64 v[122:123], v[148:149], 0, v[126:127]
	global_store_dwordx4 v[122:123], v[130:133], off
	v_or_b32_e32 v128, 16, v144
	v_lshlrev_b32_e32 v122, 1, v128
	v_ashrrev_i32_e32 v123, 31, v122
	v_lshl_add_u64 v[132:133], v[122:123], 2, s[24:25]
	s_and_saveexec_b64 s[0:1], s[12:13]
	s_xor_b64 s[0:1], exec, s[0:1]
	s_cbranch_execz .LBB0_321
	v_mov_b32_e32 v122, v225
	v_ashrrev_i32_e32 v129, 31, v128
	s_and_saveexec_b64 s[2:3], s[8:9]
	s_xor_b64 s[2:3], exec, s[2:3]
	s_cbranch_execz .LBB0_318
	v_lshlrev_b64 v[124:125], 9, v[128:129]
	v_lshl_add_u64 v[124:125], s[22:23], 0, v[124:125]
	s_lshl_b32 s14, s64, 1
	s_mov_b32 s15, s89
	v_lshl_add_u64 v[124:125], v[124:125], 0, s[14:15]
	v_lshlrev_b32_e32 v128, 1, v154
	v_mov_b32_e32 v129, v0
	s_movk_i32 s14, 0xff80
	v_lshl_add_u64 v[124:125], v[124:125], 0, v[128:129]
	s_mov_b32 s15, -1
	v_lshl_add_u64 v[130:131], v[124:125], 0, s[14:15]
.LBB0_318:
	s_andn2_saveexec_b64 s[2:3], s[2:3]
	v_mov_b64_e32 v[124:125], s[20:21]
	s_movk_i32 s14, 0x300
	v_mad_i64_i32 v[124:125], s[14:15], v128, s14, v[124:125]
	v_lshl_add_u64 v[124:125], s[88:89], 1, v[124:125]
	v_lshlrev_b32_e32 v128, 1, v154
	v_mov_b32_e32 v129, v0
	v_lshl_add_u64 v[130:131], v[124:125], 0, v[128:129]
	s_or_b64 exec, exec, s[2:3]
	v_pk_mul_f32 v[118:119], v[118:119], v[122:123] op_sel_hi:[1,0]
	v_pk_mul_f32 v[120:121], v[120:121], v[122:123] op_sel_hi:[1,0]
	v_pk_mul_f32 v[114:115], v[114:115], v[122:123] op_sel_hi:[1,0]
	v_pk_mul_f32 v[116:117], v[116:117], v[122:123] op_sel_hi:[1,0]
	v_cvt_pk_bf16_f32 v122, v118, v119
	v_cvt_pk_bf16_f32 v123, v120, v121
	v_cvt_pk_bf16_f32 v124, v114, v115
	v_cvt_pk_bf16_f32 v125, v116, v117
.LBB0_321:
	s_andn2_saveexec_b64 s[2:3], s[0:1]
	s_cbranch_execz .LBB0_325
	v_mov_b32_e32 v122, v224
	v_pk_mul_f32 v[118:119], v[118:119], v[122:123] op_sel_hi:[1,0]
	v_pk_mul_f32 v[120:121], v[120:121], v[122:123] op_sel_hi:[1,0]
	v_pk_mul_f32 v[114:115], v[114:115], v[122:123] op_sel_hi:[1,0]
	v_pk_mul_f32 v[116:117], v[116:117], v[122:123] op_sel_hi:[1,0]
	s_and_saveexec_b64 s[0:1], s[10:11]
	s_xor_b64 s[0:1], exec, s[0:1]
	s_andn2_saveexec_b64 s[36:37], s[0:1]
	s_cbranch_execz .LBB0_324
	v_mov_b32_e32 v123, v220
	v_cndmask_b32_e64 v122, v156, v158, s[6:7]
	v_lshlrev_b32_e32 v123, 2, v123
	v_xor_b32_e32 v123, 64, v123
	v_lshlrev_b32_e32 v125, 6, v122
	ds_bpermute_b32 v124, v123, v118
	global_load_dwordx2 v[174:175], v125, s[26:27]
	global_load_dwordx2 v[176:177], v125, s[26:27] offset:8
	global_load_dwordx2 v[178:179], v125, s[26:27] offset:16
	global_load_dwordx2 v[180:181], v125, s[26:27] offset:24
	global_load_dwordx2 v[182:183], v125, s[26:27] offset:32
	global_load_dwordx2 v[184:185], v125, s[26:27] offset:40
	global_load_dwordx2 v[208:209], v125, s[26:27] offset:48
	global_load_dwordx2 v[210:211], v125, s[26:27] offset:56
	v_cmp_gt_i32_e64 s[14:15], s95, v128
	s_waitcnt vmcnt(7) lgkmcnt(0)
	v_mul_f32_e32 v123, v175, v124
	v_cndmask_b32_e64 v123, v123, -v123, vcc
	v_fmac_f32_e32 v123, v118, v174
	v_mov_b32_e32 v122, v220
	v_cndmask_b32_e64 v118, v118, v123, s[14:15]
	v_lshlrev_b32_e32 v122, 2, v122
	v_xor_b32_e32 v122, 64, v122
	ds_bpermute_b32 v124, v122, v119
	s_waitcnt vmcnt(6) lgkmcnt(0)
	v_mul_f32_e32 v123, v177, v124
	v_cndmask_b32_e64 v123, v123, -v123, vcc
	v_fmac_f32_e32 v123, v119, v176
	v_mov_b32_e32 v122, v220
	v_cndmask_b32_e64 v119, v119, v123, s[14:15]
	v_lshlrev_b32_e32 v122, 2, v122
	v_xor_b32_e32 v122, 64, v122
	ds_bpermute_b32 v124, v122, v120
	s_waitcnt vmcnt(5) lgkmcnt(0)
	v_mul_f32_e32 v123, v179, v124
	v_cndmask_b32_e64 v123, v123, -v123, vcc
	v_fmac_f32_e32 v123, v120, v178
	v_mov_b32_e32 v122, v220
	v_cndmask_b32_e64 v120, v120, v123, s[14:15]
	v_lshlrev_b32_e32 v122, 2, v122
	v_xor_b32_e32 v122, 64, v122
	ds_bpermute_b32 v124, v122, v121
	s_waitcnt vmcnt(4) lgkmcnt(0)
	v_mul_f32_e32 v123, v181, v124
	v_cndmask_b32_e64 v123, v123, -v123, vcc
	v_fmac_f32_e32 v123, v121, v180
	v_mov_b32_e32 v122, v220
	v_cndmask_b32_e64 v121, v121, v123, s[14:15]
	v_lshlrev_b32_e32 v122, 2, v122
	v_xor_b32_e32 v122, 64, v122
	ds_bpermute_b32 v124, v122, v114
	s_waitcnt vmcnt(3) lgkmcnt(0)
	v_mul_f32_e32 v123, v183, v124
	v_cndmask_b32_e64 v123, v123, -v123, vcc
	v_fmac_f32_e32 v123, v114, v182
	v_mov_b32_e32 v122, v220
	v_cndmask_b32_e64 v114, v114, v123, s[14:15]
	v_lshlrev_b32_e32 v122, 2, v122
	v_xor_b32_e32 v122, 64, v122
	ds_bpermute_b32 v124, v122, v115
	s_waitcnt vmcnt(2) lgkmcnt(0)
	v_mul_f32_e32 v123, v185, v124
	v_cndmask_b32_e64 v123, v123, -v123, vcc
	v_fmac_f32_e32 v123, v115, v184
	v_mov_b32_e32 v122, v220
	v_cndmask_b32_e64 v115, v115, v123, s[14:15]
	v_lshlrev_b32_e32 v122, 2, v122
	v_xor_b32_e32 v122, 64, v122
	ds_bpermute_b32 v124, v122, v116
	s_waitcnt vmcnt(1) lgkmcnt(0)
	v_mul_f32_e32 v123, v209, v124
	v_cndmask_b32_e64 v123, v123, -v123, vcc
	v_fmac_f32_e32 v123, v116, v208
	v_mov_b32_e32 v122, v220
	v_cndmask_b32_e64 v116, v116, v123, s[14:15]
	v_lshlrev_b32_e32 v122, 2, v122
	v_xor_b32_e32 v122, 64, v122
	ds_bpermute_b32 v124, v122, v117
	s_waitcnt vmcnt(0) lgkmcnt(0)
	v_mul_f32_e32 v123, v211, v124
	v_cndmask_b32_e64 v123, v123, -v123, vcc
	v_fmac_f32_e32 v123, v117, v210
	v_cndmask_b32_e64 v117, v117, v123, s[14:15]

; __device__ __forceinline__ unsigned cvt_pk_bf16(float lo, float hi) { const f32x2_ v = {lo, hi}; return __builtin_bit_cast(unsigned, __builtin_convertvector(v, bf16x2_)); }
;     __device__ __forceinline__ void operator()(const f32x4 (&acc)[2][2][4][2], const Unit& u, int wr, int wc, int fr, int fq) const {
;     ...
;                     const int row = row0 + ai * 128 + m * 16;
;                     float v[8];
;                     if (cg0 < 384) {
;                         const float rs = RSTD[row * 2];
; #pragma unroll
;                         for (int n = 0; n < 2; ++n)
; #pragma unroll
;                             for (int j = 0; j < 4; ++j) v[4 * n + j] = acc[ai][bj][m][n][j] * rs;
;     ...
;                         *(u32x4*)(MQ + (size_t)row * 384 + cg0 + 8 * fq) = w;
;                     } else {
;                         const float rs = RSTD[row * 2 + 1];
; #pragma unroll
;                         for (int n = 0; n < 2; ++n)
; #pragma unroll
;                             for (int j = 0; j < 4; ++j) v[4 * n + j] = acc[ai][bj][m][n][j] * rs;
;                         const int cp = cg0 - 384, hd = cp >> 7, d0 = cp & 127;
;                         u32x4 w; w.x = cvt_pk_bf16(v[0], v[1]); w.y = cvt_pk_bf16(v[2], v[3]); w.z = cvt_pk_bf16(v[4], v[5]); w.w = cvt_pk_bf16(v[6], v[7]);
;                         if (d0 < 64) *(u32x4*)(MK + (size_t)row * 384 + hd * 96 + d0 + 8 * fq) = w;
;                         else *(u32x4*)(MV + (size_t)row * 256 + hd * 64 + (d0 - 64) + 8 * fq) = w;
.LBB0_325:
	s_or_b64 exec, exec, s[2:3]
	v_mov_b32_e32 v127, v0
	v_lshl_add_u64 v[114:115], v[130:131], 0, v[126:127]
	global_store_dwordx4 v[114:115], v[122:125], off
	v_or_b32_e32 v118, 32, v144
	v_lshlrev_b32_e32 v114, 1, v118
	v_ashrrev_i32_e32 v115, 31, v114
	v_lshl_add_u64 v[122:123], v[114:115], 2, s[24:25]
	s_and_saveexec_b64 s[0:1], s[12:13]
	s_xor_b64 s[0:1], exec, s[0:1]
	s_cbranch_execz .LBB0_331
	v_mov_b32_e32 v114, v227
	v_ashrrev_i32_e32 v119, 31, v118
	s_and_saveexec_b64 s[2:3], s[8:9]
	s_xor_b64 s[2:3], exec, s[2:3]
	s_cbranch_execz .LBB0_328
	v_lshlrev_b64 v[116:117], 9, v[118:119]
	v_lshl_add_u64 v[116:117], s[22:23], 0, v[116:117]
	s_lshl_b32 s14, s64, 1
	s_mov_b32 s15, s89
	v_lshl_add_u64 v[116:117], v[116:117], 0, s[14:15]
	v_lshlrev_b32_e32 v118, 1, v154
	v_mov_b32_e32 v119, v0
	s_movk_i32 s14, 0xff80
	v_lshl_add_u64 v[116:117], v[116:117], 0, v[118:119]
	s_mov_b32 s15, -1
	v_lshl_add_u64 v[120:121], v[116:117], 0, s[14:15]
.LBB0_328:
	s_andn2_saveexec_b64 s[2:3], s[2:3]
	v_mov_b64_e32 v[116:117], s[20:21]
	s_movk_i32 s14, 0x300
	v_mad_i64_i32 v[116:117], s[14:15], v118, s14, v[116:117]
	v_lshl_add_u64 v[116:117], s[88:89], 1, v[116:117]
	v_lshlrev_b32_e32 v118, 1, v154
	v_mov_b32_e32 v119, v0
	v_lshl_add_u64 v[120:121], v[116:117], 0, v[118:119]
	s_or_b64 exec, exec, s[2:3]
	v_pk_mul_f32 v[110:111], v[110:111], v[114:115] op_sel_hi:[1,0]
	v_pk_mul_f32 v[112:113], v[112:113], v[114:115] op_sel_hi:[1,0]
	v_pk_mul_f32 v[106:107], v[106:107], v[114:115] op_sel_hi:[1,0]
	v_pk_mul_f32 v[108:109], v[108:109], v[114:115] op_sel_hi:[1,0]
	v_cvt_pk_bf16_f32 v114, v110, v111
	v_cvt_pk_bf16_f32 v115, v112, v113
	v_cvt_pk_bf16_f32 v116, v106, v107
	v_cvt_pk_bf16_f32 v117, v108, v109
.LBB0_331:
	s_andn2_saveexec_b64 s[2:3], s[0:1]
	s_cbranch_execz .LBB0_335
	v_mov_b32_e32 v114, v226
	v_pk_mul_f32 v[110:111], v[110:111], v[114:115] op_sel_hi:[1,0]
	v_pk_mul_f32 v[112:113], v[112:113], v[114:115] op_sel_hi:[1,0]
	v_pk_mul_f32 v[106:107], v[106:107], v[114:115] op_sel_hi:[1,0]
	v_pk_mul_f32 v[108:109], v[108:109], v[114:115] op_sel_hi:[1,0]
	s_and_saveexec_b64 s[0:1], s[10:11]
	s_xor_b64 s[0:1], exec, s[0:1]
	s_andn2_saveexec_b64 s[36:37], s[0:1]
	s_cbranch_execz .LBB0_334
	v_mov_b32_e32 v115, v220
	v_cndmask_b32_e64 v114, v155, v158, s[6:7]
	v_lshlrev_b32_e32 v115, 2, v115
	v_xor_b32_e32 v115, 64, v115
	v_lshlrev_b32_e32 v117, 6, v114
	ds_bpermute_b32 v116, v115, v110
	global_load_dwordx2 v[174:175], v117, s[26:27]
	global_load_dwordx2 v[176:177], v117, s[26:27] offset:8
	global_load_dwordx2 v[178:179], v117, s[26:27] offset:16
	global_load_dwordx2 v[180:181], v117, s[26:27] offset:24
	global_load_dwordx2 v[182:183], v117, s[26:27] offset:32
	global_load_dwordx2 v[184:185], v117, s[26:27] offset:40
	global_load_dwordx2 v[208:209], v117, s[26:27] offset:48
	global_load_dwordx2 v[210:211], v117, s[26:27] offset:56
	v_cmp_gt_i32_e64 s[14:15], s95, v118
	s_waitcnt vmcnt(7) lgkmcnt(0)
	v_mul_f32_e32 v115, v175, v116
	v_cndmask_b32_e64 v115, v115, -v115, vcc
	v_fmac_f32_e32 v115, v110, v174
	v_mov_b32_e32 v114, v220
	v_cndmask_b32_e64 v110, v110, v115, s[14:15]
	v_lshlrev_b32_e32 v114, 2, v114
	v_xor_b32_e32 v114, 64, v114
	ds_bpermute_b32 v116, v114, v111
	s_waitcnt vmcnt(6) lgkmcnt(0)
	v_mul_f32_e32 v115, v177, v116
	v_cndmask_b32_e64 v115, v115, -v115, vcc
	v_fmac_f32_e32 v115, v111, v176
	v_mov_b32_e32 v114, v220
	v_cndmask_b32_e64 v111, v111, v115, s[14:15]
	v_lshlrev_b32_e32 v114, 2, v114
	v_xor_b32_e32 v114, 64, v114
	ds_bpermute_b32 v116, v114, v112
	s_waitcnt vmcnt(5) lgkmcnt(0)
	v_mul_f32_e32 v115, v179, v116
	v_cndmask_b32_e64 v115, v115, -v115, vcc
	v_fmac_f32_e32 v115, v112, v178
	v_mov_b32_e32 v114, v220
	v_cndmask_b32_e64 v112, v112, v115, s[14:15]
	v_lshlrev_b32_e32 v114, 2, v114
	v_xor_b32_e32 v114, 64, v114
	ds_bpermute_b32 v116, v114, v113
	s_waitcnt vmcnt(4) lgkmcnt(0)
	v_mul_f32_e32 v115, v181, v116
	v_cndmask_b32_e64 v115, v115, -v115, vcc
	v_fmac_f32_e32 v115, v113, v180
	v_mov_b32_e32 v114, v220
	v_cndmask_b32_e64 v113, v113, v115, s[14:15]
	v_lshlrev_b32_e32 v114, 2, v114
	v_xor_b32_e32 v114, 64, v114
	ds_bpermute_b32 v116, v114, v106
	s_waitcnt vmcnt(3) lgkmcnt(0)
	v_mul_f32_e32 v115, v183, v116
	v_cndmask_b32_e64 v115, v115, -v115, vcc
	v_fmac_f32_e32 v115, v106, v182
	v_mov_b32_e32 v114, v220
	v_cndmask_b32_e64 v106, v106, v115, s[14:15]
	v_lshlrev_b32_e32 v114, 2, v114
	v_xor_b32_e32 v114, 64, v114
	ds_bpermute_b32 v116, v114, v107
	s_waitcnt vmcnt(2) lgkmcnt(0)
	v_mul_f32_e32 v115, v185, v116
	v_cndmask_b32_e64 v115, v115, -v115, vcc
	v_fmac_f32_e32 v115, v107, v184
	v_mov_b32_e32 v114, v220
	v_cndmask_b32_e64 v107, v107, v115, s[14:15]
	v_lshlrev_b32_e32 v114, 2, v114
	v_xor_b32_e32 v114, 64, v114
	ds_bpermute_b32 v116, v114, v108
	s_waitcnt vmcnt(1) lgkmcnt(0)
	v_mul_f32_e32 v115, v209, v116
	v_cndmask_b32_e64 v115, v115, -v115, vcc
	v_fmac_f32_e32 v115, v108, v208
	v_mov_b32_e32 v114, v220
	v_cndmask_b32_e64 v108, v108, v115, s[14:15]
	v_lshlrev_b32_e32 v114, 2, v114
	v_xor_b32_e32 v114, 64, v114
	ds_bpermute_b32 v116, v114, v109
	s_waitcnt vmcnt(0) lgkmcnt(0)
	v_mul_f32_e32 v115, v211, v116
	v_cndmask_b32_e64 v115, v115, -v115, vcc
	v_fmac_f32_e32 v115, v109, v210
	v_cndmask_b32_e64 v109, v109, v115, s[14:15]

; __device__ __forceinline__ unsigned cvt_pk_bf16(float lo, float hi) { const f32x2_ v = {lo, hi}; return __builtin_bit_cast(unsigned, __builtin_convertvector(v, bf16x2_)); }
;     __device__ __forceinline__ void operator()(const f32x4 (&acc)[2][2][4][2], const Unit& u, int wr, int wc, int fr, int fq) const {
;     ...
;                     const int row = row0 + ai * 128 + m * 16;
;                     float v[8];
;                     if (cg0 < 384) {
;                         const float rs = RSTD[row * 2];
; #pragma unroll
;                         for (int n = 0; n < 2; ++n)
; #pragma unroll
;                             for (int j = 0; j < 4; ++j) v[4 * n + j] = acc[ai][bj][m][n][j] * rs;
;     ...
;                         *(u32x4*)(MQ + (size_t)row * 384 + cg0 + 8 * fq) = w;
;                     } else {
;                         const float rs = RSTD[row * 2 + 1];
; #pragma unroll
;                         for (int n = 0; n < 2; ++n)
; #pragma unroll
;                             for (int j = 0; j < 4; ++j) v[4 * n + j] = acc[ai][bj][m][n][j] * rs;
;                         const int cp = cg0 - 384, hd = cp >> 7, d0 = cp & 127;
;                         u32x4 w; w.x = cvt_pk_bf16(v[0], v[1]); w.y = cvt_pk_bf16(v[2], v[3]); w.z = cvt_pk_bf16(v[4], v[5]); w.w = cvt_pk_bf16(v[6], v[7]);
;                         if (d0 < 64) *(u32x4*)(MK + (size_t)row * 384 + hd * 96 + d0 + 8 * fq) = w;
;                         else *(u32x4*)(MV + (size_t)row * 256 + hd * 64 + (d0 - 64) + 8 * fq) = w;
.LBB0_335:
	s_or_b64 exec, exec, s[2:3]
	v_mov_b32_e32 v127, v0
	v_lshl_add_u64 v[106:107], v[120:121], 0, v[126:127]
	global_store_dwordx4 v[106:107], v[114:117], off
	v_or_b32_e32 v110, 48, v144
	v_lshlrev_b32_e32 v106, 1, v110
	v_ashrrev_i32_e32 v107, 31, v106
	v_lshl_add_u64 v[114:115], v[106:107], 2, s[24:25]
	s_and_saveexec_b64 s[0:1], s[12:13]
	s_xor_b64 s[0:1], exec, s[0:1]
	s_cbranch_execz .LBB0_341
	v_mov_b32_e32 v106, v229
	v_ashrrev_i32_e32 v111, 31, v110
	s_and_saveexec_b64 s[2:3], s[8:9]
	s_xor_b64 s[2:3], exec, s[2:3]
	s_cbranch_execz .LBB0_338
	v_lshlrev_b64 v[108:109], 9, v[110:111]
	v_lshl_add_u64 v[108:109], s[22:23], 0, v[108:109]
	s_lshl_b32 s14, s64, 1
	s_mov_b32 s15, s89
	v_lshl_add_u64 v[108:109], v[108:109], 0, s[14:15]
	v_lshlrev_b32_e32 v110, 1, v154
	v_mov_b32_e32 v111, v0
	s_movk_i32 s14, 0xff80
	v_lshl_add_u64 v[108:109], v[108:109], 0, v[110:111]
	s_mov_b32 s15, -1
	v_lshl_add_u64 v[112:113], v[108:109], 0, s[14:15]
.LBB0_338:
	s_andn2_saveexec_b64 s[2:3], s[2:3]
	v_mov_b64_e32 v[108:109], s[20:21]
	s_movk_i32 s14, 0x300
	v_mad_i64_i32 v[108:109], s[14:15], v110, s14, v[108:109]
	v_lshl_add_u64 v[108:109], s[88:89], 1, v[108:109]
	v_lshlrev_b32_e32 v110, 1, v154
	v_mov_b32_e32 v111, v0
	v_lshl_add_u64 v[112:113], v[108:109], 0, v[110:111]
	s_or_b64 exec, exec, s[2:3]
	v_pk_mul_f32 v[102:103], v[102:103], v[106:107] op_sel_hi:[1,0]
	v_pk_mul_f32 v[104:105], v[104:105], v[106:107] op_sel_hi:[1,0]
	v_pk_mul_f32 v[98:99], v[98:99], v[106:107] op_sel_hi:[1,0]
	v_pk_mul_f32 v[100:101], v[100:101], v[106:107] op_sel_hi:[1,0]
	v_cvt_pk_bf16_f32 v106, v102, v103
	v_cvt_pk_bf16_f32 v107, v104, v105
	v_cvt_pk_bf16_f32 v108, v98, v99
	v_cvt_pk_bf16_f32 v109, v100, v101
.LBB0_341:
	s_andn2_saveexec_b64 s[2:3], s[0:1]
	s_cbranch_execz .LBB0_345
	v_mov_b32_e32 v106, v228
	v_pk_mul_f32 v[102:103], v[102:103], v[106:107] op_sel_hi:[1,0]
	v_pk_mul_f32 v[104:105], v[104:105], v[106:107] op_sel_hi:[1,0]
	v_pk_mul_f32 v[98:99], v[98:99], v[106:107] op_sel_hi:[1,0]
	v_pk_mul_f32 v[100:101], v[100:101], v[106:107] op_sel_hi:[1,0]
	s_and_saveexec_b64 s[0:1], s[10:11]
	s_xor_b64 s[0:1], exec, s[0:1]
	s_andn2_saveexec_b64 s[36:37], s[0:1]
	s_cbranch_execz .LBB0_344
	v_mov_b32_e32 v107, v220
	v_cndmask_b32_e64 v106, v153, v158, s[6:7]
	v_lshlrev_b32_e32 v107, 2, v107
	v_xor_b32_e32 v107, 64, v107
	v_lshlrev_b32_e32 v109, 6, v106
	ds_bpermute_b32 v108, v107, v102
	global_load_dwordx2 v[174:175], v109, s[26:27]
	global_load_dwordx2 v[176:177], v109, s[26:27] offset:8
	global_load_dwordx2 v[178:179], v109, s[26:27] offset:16
	global_load_dwordx2 v[180:181], v109, s[26:27] offset:24
	global_load_dwordx2 v[182:183], v109, s[26:27] offset:32
	global_load_dwordx2 v[184:185], v109, s[26:27] offset:40
	global_load_dwordx2 v[208:209], v109, s[26:27] offset:48
	global_load_dwordx2 v[210:211], v109, s[26:27] offset:56
	v_cmp_gt_i32_e64 s[14:15], s95, v110
	s_waitcnt vmcnt(7) lgkmcnt(0)
	v_mul_f32_e32 v107, v175, v108
	v_cndmask_b32_e64 v107, v107, -v107, vcc
	v_fmac_f32_e32 v107, v102, v174
	v_mov_b32_e32 v106, v220
	v_cndmask_b32_e64 v102, v102, v107, s[14:15]
	v_lshlrev_b32_e32 v106, 2, v106
	v_xor_b32_e32 v106, 64, v106
	ds_bpermute_b32 v108, v106, v103
	s_waitcnt vmcnt(6) lgkmcnt(0)
	v_mul_f32_e32 v107, v177, v108
	v_cndmask_b32_e64 v107, v107, -v107, vcc
	v_fmac_f32_e32 v107, v103, v176
	v_mov_b32_e32 v106, v220
	v_cndmask_b32_e64 v103, v103, v107, s[14:15]
	v_lshlrev_b32_e32 v106, 2, v106
	v_xor_b32_e32 v106, 64, v106
	ds_bpermute_b32 v108, v106, v104
	s_waitcnt vmcnt(5) lgkmcnt(0)
	v_mul_f32_e32 v107, v179, v108
	v_cndmask_b32_e64 v107, v107, -v107, vcc
	v_fmac_f32_e32 v107, v104, v178
	v_mov_b32_e32 v106, v220
	v_cndmask_b32_e64 v104, v104, v107, s[14:15]
	v_lshlrev_b32_e32 v106, 2, v106
	v_xor_b32_e32 v106, 64, v106
	ds_bpermute_b32 v108, v106, v105
	s_waitcnt vmcnt(4) lgkmcnt(0)
	v_mul_f32_e32 v107, v181, v108
	v_cndmask_b32_e64 v107, v107, -v107, vcc
	v_fmac_f32_e32 v107, v105, v180
	v_mov_b32_e32 v106, v220
	v_cndmask_b32_e64 v105, v105, v107, s[14:15]
	v_lshlrev_b32_e32 v106, 2, v106
	v_xor_b32_e32 v106, 64, v106
	ds_bpermute_b32 v108, v106, v98
	s_waitcnt vmcnt(3) lgkmcnt(0)
	v_mul_f32_e32 v107, v183, v108
	v_cndmask_b32_e64 v107, v107, -v107, vcc
	v_fmac_f32_e32 v107, v98, v182
	v_mov_b32_e32 v106, v220
	v_cndmask_b32_e64 v98, v98, v107, s[14:15]
	v_lshlrev_b32_e32 v106, 2, v106
	v_xor_b32_e32 v106, 64, v106
	ds_bpermute_b32 v108, v106, v99
	s_waitcnt vmcnt(2) lgkmcnt(0)
	v_mul_f32_e32 v107, v185, v108
	v_cndmask_b32_e64 v107, v107, -v107, vcc
	v_fmac_f32_e32 v107, v99, v184
	v_mov_b32_e32 v106, v220
	v_cndmask_b32_e64 v99, v99, v107, s[14:15]
	v_lshlrev_b32_e32 v106, 2, v106
	v_xor_b32_e32 v106, 64, v106
	ds_bpermute_b32 v108, v106, v100
	s_waitcnt vmcnt(1) lgkmcnt(0)
	v_mul_f32_e32 v107, v209, v108
	v_cndmask_b32_e64 v107, v107, -v107, vcc
	v_fmac_f32_e32 v107, v100, v208
	v_mov_b32_e32 v106, v220
	v_cndmask_b32_e64 v100, v100, v107, s[14:15]
	v_lshlrev_b32_e32 v106, 2, v106
	v_xor_b32_e32 v106, 64, v106
	ds_bpermute_b32 v108, v106, v101
	s_waitcnt vmcnt(0) lgkmcnt(0)
	v_mul_f32_e32 v107, v211, v108
	v_cndmask_b32_e64 v107, v107, -v107, vcc
	v_fmac_f32_e32 v107, v101, v210
	v_cndmask_b32_e64 v101, v101, v107, s[14:15]

; __device__ __forceinline__ unsigned cvt_pk_bf16(float lo, float hi) { const f32x2_ v = {lo, hi}; return __builtin_bit_cast(unsigned, __builtin_convertvector(v, bf16x2_)); }
;     __device__ __forceinline__ void operator()(const f32x4 (&acc)[2][2][4][2], const Unit& u, int wr, int wc, int fr, int fq) const {
;     ...
;                     const int row = row0 + ai * 128 + m * 16;
;                     float v[8];
;                     if (cg0 < 384) {
;                         const float rs = RSTD[row * 2];
; #pragma unroll
;                         for (int n = 0; n < 2; ++n)
; #pragma unroll
;                             for (int j = 0; j < 4; ++j) v[4 * n + j] = acc[ai][bj][m][n][j] * rs;
;     ...
;                         *(u32x4*)(MQ + (size_t)row * 384 + cg0 + 8 * fq) = w;
;                     } else {
;                         const float rs = RSTD[row * 2 + 1];
; #pragma unroll
;                         for (int n = 0; n < 2; ++n)
; #pragma unroll
;                             for (int j = 0; j < 4; ++j) v[4 * n + j] = acc[ai][bj][m][n][j] * rs;
;                         const int cp = cg0 - 384, hd = cp >> 7, d0 = cp & 127;
;                         u32x4 w; w.x = cvt_pk_bf16(v[0], v[1]); w.y = cvt_pk_bf16(v[2], v[3]); w.z = cvt_pk_bf16(v[4], v[5]); w.w = cvt_pk_bf16(v[6], v[7]);
;                         if (d0 < 64) *(u32x4*)(MK + (size_t)row * 384 + hd * 96 + d0 + 8 * fq) = w;
;                         else *(u32x4*)(MV + (size_t)row * 256 + hd * 64 + (d0 - 64) + 8 * fq) = w;
.LBB0_345:
	s_or_b64 exec, exec, s[2:3]
	v_mov_b32_e32 v127, v0
	v_lshl_add_u64 v[98:99], v[112:113], 0, v[126:127]
	v_add_u32_e32 v102, 0x80, v144
	global_store_dwordx4 v[98:99], v[106:109], off
	v_lshlrev_b32_e32 v98, 1, v102
	v_ashrrev_i32_e32 v99, 31, v98
	v_lshl_add_u64 v[106:107], v[98:99], 2, s[24:25]
	s_and_saveexec_b64 s[0:1], s[12:13]
	s_xor_b64 s[0:1], exec, s[0:1]
	s_cbranch_execz .LBB0_351
	v_mov_b32_e32 v98, v231
	v_ashrrev_i32_e32 v103, 31, v102
	s_and_saveexec_b64 s[2:3], s[8:9]
	s_xor_b64 s[2:3], exec, s[2:3]
	s_cbranch_execz .LBB0_348
	v_lshlrev_b64 v[100:101], 9, v[102:103]
	v_lshl_add_u64 v[100:101], s[22:23], 0, v[100:101]
	s_lshl_b32 s14, s64, 1
	s_mov_b32 s15, s89
	v_lshl_add_u64 v[100:101], v[100:101], 0, s[14:15]
	v_lshlrev_b32_e32 v104, 1, v154
	v_mov_b32_e32 v105, v0
	s_movk_i32 s14, 0xff80
	v_lshl_add_u64 v[100:101], v[100:101], 0, v[104:105]
	s_mov_b32 s15, -1
	v_lshl_add_u64 v[104:105], v[100:101], 0, s[14:15]
.LBB0_348:
	s_andn2_saveexec_b64 s[2:3], s[2:3]
	v_mov_b64_e32 v[100:101], s[20:21]
	s_movk_i32 s14, 0x300
	v_mad_i64_i32 v[100:101], s[14:15], v102, s14, v[100:101]
	v_lshl_add_u64 v[100:101], s[88:89], 1, v[100:101]
	v_lshlrev_b32_e32 v104, 1, v154
	v_mov_b32_e32 v105, v0
	v_lshl_add_u64 v[104:105], v[100:101], 0, v[104:105]
	s_or_b64 exec, exec, s[2:3]
	v_pk_mul_f32 v[94:95], v[94:95], v[98:99] op_sel_hi:[1,0]
	v_pk_mul_f32 v[96:97], v[96:97], v[98:99] op_sel_hi:[1,0]
	v_pk_mul_f32 v[90:91], v[90:91], v[98:99] op_sel_hi:[1,0]
	v_pk_mul_f32 v[92:93], v[92:93], v[98:99] op_sel_hi:[1,0]
	v_cvt_pk_bf16_f32 v98, v94, v95
	v_cvt_pk_bf16_f32 v99, v96, v97
	v_cvt_pk_bf16_f32 v100, v90, v91
	v_cvt_pk_bf16_f32 v101, v92, v93
.LBB0_351:
	s_or_saveexec_b64 s[2:3], s[0:1]
	v_bfe_u32 v103, v102, 6, 7
	s_xor_b64 exec, exec, s[2:3]
	s_cbranch_execz .LBB0_355
	v_mov_b32_e32 v98, v230
	v_pk_mul_f32 v[94:95], v[94:95], v[98:99] op_sel_hi:[1,0]
	v_pk_mul_f32 v[96:97], v[96:97], v[98:99] op_sel_hi:[1,0]
	v_pk_mul_f32 v[90:91], v[90:91], v[98:99] op_sel_hi:[1,0]
	v_pk_mul_f32 v[92:93], v[92:93], v[98:99] op_sel_hi:[1,0]
	s_and_saveexec_b64 s[0:1], s[10:11]
	s_xor_b64 s[0:1], exec, s[0:1]
	s_andn2_saveexec_b64 s[36:37], s[0:1]
	s_cbranch_execz .LBB0_354
	v_mov_b32_e32 v99, v220
	v_cndmask_b32_e64 v98, v157, v103, s[6:7]
	v_lshlrev_b32_e32 v99, 2, v99
	v_xor_b32_e32 v99, 64, v99
	v_lshlrev_b32_e32 v101, 6, v98
	ds_bpermute_b32 v100, v99, v94
	global_load_dwordx2 v[174:175], v101, s[26:27]
	global_load_dwordx2 v[176:177], v101, s[26:27] offset:8
	global_load_dwordx2 v[178:179], v101, s[26:27] offset:16
	global_load_dwordx2 v[180:181], v101, s[26:27] offset:24
	global_load_dwordx2 v[182:183], v101, s[26:27] offset:32
	global_load_dwordx2 v[184:185], v101, s[26:27] offset:40
	global_load_dwordx2 v[208:209], v101, s[26:27] offset:48
	global_load_dwordx2 v[210:211], v101, s[26:27] offset:56
	s_movk_i32 s0, 0x7f80
	v_cmp_gt_i32_e64 s[14:15], s0, v144
	s_waitcnt vmcnt(7) lgkmcnt(0)
	v_mul_f32_e32 v99, v175, v100
	v_cndmask_b32_e64 v99, v99, -v99, vcc
	v_fmac_f32_e32 v99, v94, v174
	v_mov_b32_e32 v98, v220
	v_cndmask_b32_e64 v94, v94, v99, s[14:15]
	v_lshlrev_b32_e32 v98, 2, v98
	v_xor_b32_e32 v98, 64, v98
	ds_bpermute_b32 v100, v98, v95
	s_waitcnt vmcnt(6) lgkmcnt(0)
	v_mul_f32_e32 v99, v177, v100
	v_cndmask_b32_e64 v99, v99, -v99, vcc
	v_fmac_f32_e32 v99, v95, v176
	v_mov_b32_e32 v98, v220
	v_cndmask_b32_e64 v95, v95, v99, s[14:15]
	v_lshlrev_b32_e32 v98, 2, v98
	v_xor_b32_e32 v98, 64, v98
	ds_bpermute_b32 v100, v98, v96
	s_waitcnt vmcnt(5) lgkmcnt(0)
	v_mul_f32_e32 v99, v179, v100
	v_cndmask_b32_e64 v99, v99, -v99, vcc
	v_fmac_f32_e32 v99, v96, v178
	v_mov_b32_e32 v98, v220
	v_cndmask_b32_e64 v96, v96, v99, s[14:15]
	v_lshlrev_b32_e32 v98, 2, v98
	v_xor_b32_e32 v98, 64, v98
	ds_bpermute_b32 v100, v98, v97
	s_waitcnt vmcnt(4) lgkmcnt(0)
	v_mul_f32_e32 v99, v181, v100
	v_cndmask_b32_e64 v99, v99, -v99, vcc
	v_fmac_f32_e32 v99, v97, v180
	v_mov_b32_e32 v98, v220
	v_cndmask_b32_e64 v97, v97, v99, s[14:15]
	v_lshlrev_b32_e32 v98, 2, v98
	v_xor_b32_e32 v98, 64, v98
	ds_bpermute_b32 v100, v98, v90
	s_waitcnt vmcnt(3) lgkmcnt(0)
	v_mul_f32_e32 v99, v183, v100
	v_cndmask_b32_e64 v99, v99, -v99, vcc
	v_fmac_f32_e32 v99, v90, v182
	v_mov_b32_e32 v98, v220
	v_cndmask_b32_e64 v90, v90, v99, s[14:15]
	v_lshlrev_b32_e32 v98, 2, v98
	v_xor_b32_e32 v98, 64, v98
	ds_bpermute_b32 v100, v98, v91
	s_waitcnt vmcnt(2) lgkmcnt(0)
	v_mul_f32_e32 v99, v185, v100
	v_cndmask_b32_e64 v99, v99, -v99, vcc
	v_fmac_f32_e32 v99, v91, v184
	v_mov_b32_e32 v98, v220
	v_cndmask_b32_e64 v91, v91, v99, s[14:15]
	v_lshlrev_b32_e32 v98, 2, v98
	v_xor_b32_e32 v98, 64, v98
	ds_bpermute_b32 v100, v98, v92
	s_waitcnt vmcnt(1) lgkmcnt(0)
	v_mul_f32_e32 v99, v209, v100
	v_cndmask_b32_e64 v99, v99, -v99, vcc
	v_fmac_f32_e32 v99, v92, v208
	v_mov_b32_e32 v98, v220
	v_cndmask_b32_e64 v92, v92, v99, s[14:15]
	v_lshlrev_b32_e32 v98, 2, v98
	v_xor_b32_e32 v98, 64, v98
	ds_bpermute_b32 v100, v98, v93
	s_waitcnt vmcnt(0) lgkmcnt(0)
	v_mul_f32_e32 v99, v211, v100
	v_cndmask_b32_e64 v99, v99, -v99, vcc
	v_fmac_f32_e32 v99, v93, v210
	v_cndmask_b32_e64 v93, v93, v99, s[14:15]

; __device__ __forceinline__ unsigned cvt_pk_bf16(float lo, float hi) { const f32x2_ v = {lo, hi}; return __builtin_bit_cast(unsigned, __builtin_convertvector(v, bf16x2_)); }
;     __device__ __forceinline__ void operator()(const f32x4 (&acc)[2][2][4][2], const Unit& u, int wr, int wc, int fr, int fq) const {
;     ...
;                     const int row = row0 + ai * 128 + m * 16;
;                     float v[8];
;                     if (cg0 < 384) {
;                         const float rs = RSTD[row * 2];
; #pragma unroll
;                         for (int n = 0; n < 2; ++n)
; #pragma unroll
;                             for (int j = 0; j < 4; ++j) v[4 * n + j] = acc[ai][bj][m][n][j] * rs;
;     ...
;                         *(u32x4*)(MQ + (size_t)row * 384 + cg0 + 8 * fq) = w;
;                     } else {
;                         const float rs = RSTD[row * 2 + 1];
; #pragma unroll
;                         for (int n = 0; n < 2; ++n)
; #pragma unroll
;                             for (int j = 0; j < 4; ++j) v[4 * n + j] = acc[ai][bj][m][n][j] * rs;
;                         const int cp = cg0 - 384, hd = cp >> 7, d0 = cp & 127;
;                         u32x4 w; w.x = cvt_pk_bf16(v[0], v[1]); w.y = cvt_pk_bf16(v[2], v[3]); w.z = cvt_pk_bf16(v[4], v[5]); w.w = cvt_pk_bf16(v[6], v[7]);
;                         if (d0 < 64) *(u32x4*)(MK + (size_t)row * 384 + hd * 96 + d0 + 8 * fq) = w;
;                         else *(u32x4*)(MV + (size_t)row * 256 + hd * 64 + (d0 - 64) + 8 * fq) = w;
.LBB0_355:
	s_or_b64 exec, exec, s[2:3]
	v_mov_b32_e32 v127, v0
	v_lshl_add_u64 v[90:91], v[104:105], 0, v[126:127]
	global_store_dwordx4 v[90:91], v[98:101], off
	v_add_u32_e32 v94, 0x90, v144
	v_lshlrev_b32_e32 v90, 1, v94
	v_ashrrev_i32_e32 v91, 31, v90
	v_lshl_add_u64 v[98:99], v[90:91], 2, s[24:25]
	s_and_saveexec_b64 s[0:1], s[12:13]
	s_xor_b64 s[0:1], exec, s[0:1]
	s_cbranch_execz .LBB0_361
	v_mov_b32_e32 v90, v233
	v_ashrrev_i32_e32 v95, 31, v94
	s_and_saveexec_b64 s[2:3], s[8:9]
	s_xor_b64 s[2:3], exec, s[2:3]
	s_cbranch_execz .LBB0_358
	v_lshlrev_b64 v[92:93], 9, v[94:95]
	v_lshl_add_u64 v[92:93], s[22:23], 0, v[92:93]
	s_lshl_b32 s14, s64, 1
	s_mov_b32 s15, s89
	v_lshl_add_u64 v[92:93], v[92:93], 0, s[14:15]
	v_lshlrev_b32_e32 v94, 1, v154
	v_mov_b32_e32 v95, v0
	s_movk_i32 s14, 0xff80
	v_lshl_add_u64 v[92:93], v[92:93], 0, v[94:95]
	s_mov_b32 s15, -1
	v_lshl_add_u64 v[96:97], v[92:93], 0, s[14:15]
.LBB0_358:
	s_andn2_saveexec_b64 s[2:3], s[2:3]
	v_mov_b64_e32 v[92:93], s[20:21]
	s_movk_i32 s14, 0x300
	v_mad_i64_i32 v[92:93], s[14:15], v94, s14, v[92:93]
	v_lshl_add_u64 v[92:93], s[88:89], 1, v[92:93]
	v_lshlrev_b32_e32 v94, 1, v154
	v_mov_b32_e32 v95, v0
	v_lshl_add_u64 v[96:97], v[92:93], 0, v[94:95]
	s_or_b64 exec, exec, s[2:3]
	v_pk_mul_f32 v[86:87], v[86:87], v[90:91] op_sel_hi:[1,0]
	v_pk_mul_f32 v[88:89], v[88:89], v[90:91] op_sel_hi:[1,0]
	v_pk_mul_f32 v[82:83], v[82:83], v[90:91] op_sel_hi:[1,0]
	v_pk_mul_f32 v[84:85], v[84:85], v[90:91] op_sel_hi:[1,0]
	v_cvt_pk_bf16_f32 v90, v86, v87
	v_cvt_pk_bf16_f32 v91, v88, v89
	v_cvt_pk_bf16_f32 v92, v82, v83
	v_cvt_pk_bf16_f32 v93, v84, v85
.LBB0_361:
	s_andn2_saveexec_b64 s[2:3], s[0:1]
	s_cbranch_execz .LBB0_365
	v_mov_b32_e32 v90, v232
	v_pk_mul_f32 v[86:87], v[86:87], v[90:91] op_sel_hi:[1,0]
	v_pk_mul_f32 v[88:89], v[88:89], v[90:91] op_sel_hi:[1,0]
	v_pk_mul_f32 v[82:83], v[82:83], v[90:91] op_sel_hi:[1,0]
	v_pk_mul_f32 v[84:85], v[84:85], v[90:91] op_sel_hi:[1,0]
	s_and_saveexec_b64 s[0:1], s[10:11]
	s_xor_b64 s[0:1], exec, s[0:1]
	s_andn2_saveexec_b64 s[36:37], s[0:1]
	s_cbranch_execz .LBB0_364
	v_mov_b32_e32 v91, v220
	v_cndmask_b32_e64 v90, v156, v103, s[6:7]
	v_lshlrev_b32_e32 v91, 2, v91
	v_xor_b32_e32 v91, 64, v91
	v_lshlrev_b32_e32 v93, 6, v90
	ds_bpermute_b32 v92, v91, v86
	global_load_dwordx2 v[174:175], v93, s[26:27]
	global_load_dwordx2 v[176:177], v93, s[26:27] offset:8
	global_load_dwordx2 v[178:179], v93, s[26:27] offset:16
	global_load_dwordx2 v[180:181], v93, s[26:27] offset:24
	global_load_dwordx2 v[182:183], v93, s[26:27] offset:32
	global_load_dwordx2 v[184:185], v93, s[26:27] offset:40
	global_load_dwordx2 v[208:209], v93, s[26:27] offset:48
	global_load_dwordx2 v[210:211], v93, s[26:27] offset:56
	s_movk_i32 s0, 0x7f70
	v_cmp_gt_i32_e64 s[14:15], s0, v144
	s_waitcnt vmcnt(7) lgkmcnt(0)
	v_mul_f32_e32 v91, v175, v92
	v_cndmask_b32_e64 v91, v91, -v91, vcc
	v_fmac_f32_e32 v91, v86, v174
	v_mov_b32_e32 v90, v220
	v_cndmask_b32_e64 v86, v86, v91, s[14:15]
	v_lshlrev_b32_e32 v90, 2, v90
	v_xor_b32_e32 v90, 64, v90
	ds_bpermute_b32 v92, v90, v87
	s_waitcnt vmcnt(6) lgkmcnt(0)
	v_mul_f32_e32 v91, v177, v92
	v_cndmask_b32_e64 v91, v91, -v91, vcc
	v_fmac_f32_e32 v91, v87, v176
	v_mov_b32_e32 v90, v220
	v_cndmask_b32_e64 v87, v87, v91, s[14:15]
	v_lshlrev_b32_e32 v90, 2, v90
	v_xor_b32_e32 v90, 64, v90
	ds_bpermute_b32 v92, v90, v88
	s_waitcnt vmcnt(5) lgkmcnt(0)
	v_mul_f32_e32 v91, v179, v92
	v_cndmask_b32_e64 v91, v91, -v91, vcc
	v_fmac_f32_e32 v91, v88, v178
	v_mov_b32_e32 v90, v220
	v_cndmask_b32_e64 v88, v88, v91, s[14:15]
	v_lshlrev_b32_e32 v90, 2, v90
	v_xor_b32_e32 v90, 64, v90
	ds_bpermute_b32 v92, v90, v89
	s_waitcnt vmcnt(4) lgkmcnt(0)
	v_mul_f32_e32 v91, v181, v92
	v_cndmask_b32_e64 v91, v91, -v91, vcc
	v_fmac_f32_e32 v91, v89, v180
	v_mov_b32_e32 v90, v220
	v_cndmask_b32_e64 v89, v89, v91, s[14:15]
	v_lshlrev_b32_e32 v90, 2, v90
	v_xor_b32_e32 v90, 64, v90
	ds_bpermute_b32 v92, v90, v82
	s_waitcnt vmcnt(3) lgkmcnt(0)
	v_mul_f32_e32 v91, v183, v92
	v_cndmask_b32_e64 v91, v91, -v91, vcc
	v_fmac_f32_e32 v91, v82, v182
	v_mov_b32_e32 v90, v220
	v_cndmask_b32_e64 v82, v82, v91, s[14:15]
	v_lshlrev_b32_e32 v90, 2, v90
	v_xor_b32_e32 v90, 64, v90
	ds_bpermute_b32 v92, v90, v83
	s_waitcnt vmcnt(2) lgkmcnt(0)
	v_mul_f32_e32 v91, v185, v92
	v_cndmask_b32_e64 v91, v91, -v91, vcc
	v_fmac_f32_e32 v91, v83, v184
	v_mov_b32_e32 v90, v220
	v_cndmask_b32_e64 v83, v83, v91, s[14:15]
	v_lshlrev_b32_e32 v90, 2, v90
	v_xor_b32_e32 v90, 64, v90
	ds_bpermute_b32 v92, v90, v84
	s_waitcnt vmcnt(1) lgkmcnt(0)
	v_mul_f32_e32 v91, v209, v92
	v_cndmask_b32_e64 v91, v91, -v91, vcc
	v_fmac_f32_e32 v91, v84, v208
	v_mov_b32_e32 v90, v220
	v_cndmask_b32_e64 v84, v84, v91, s[14:15]
	v_lshlrev_b32_e32 v90, 2, v90
	v_xor_b32_e32 v90, 64, v90
	ds_bpermute_b32 v92, v90, v85
	s_waitcnt vmcnt(0) lgkmcnt(0)
	v_mul_f32_e32 v91, v211, v92
	v_cndmask_b32_e64 v91, v91, -v91, vcc
	v_fmac_f32_e32 v91, v85, v210
	v_cndmask_b32_e64 v85, v85, v91, s[14:15]

; __device__ __forceinline__ unsigned cvt_pk_bf16(float lo, float hi) { const f32x2_ v = {lo, hi}; return __builtin_bit_cast(unsigned, __builtin_convertvector(v, bf16x2_)); }
;     __device__ __forceinline__ void operator()(const f32x4 (&acc)[2][2][4][2], const Unit& u, int wr, int wc, int fr, int fq) const {
;     ...
;                     const int row = row0 + ai * 128 + m * 16;
;                     float v[8];
;                     if (cg0 < 384) {
;                         const float rs = RSTD[row * 2];
; #pragma unroll
;                         for (int n = 0; n < 2; ++n)
; #pragma unroll
;                             for (int j = 0; j < 4; ++j) v[4 * n + j] = acc[ai][bj][m][n][j] * rs;
;     ...
;                         *(u32x4*)(MQ + (size_t)row * 384 + cg0 + 8 * fq) = w;
;                     } else {
;                         const float rs = RSTD[row * 2 + 1];
; #pragma unroll
;                         for (int n = 0; n < 2; ++n)
; #pragma unroll
;                             for (int j = 0; j < 4; ++j) v[4 * n + j] = acc[ai][bj][m][n][j] * rs;
;                         const int cp = cg0 - 384, hd = cp >> 7, d0 = cp & 127;
;                         u32x4 w; w.x = cvt_pk_bf16(v[0], v[1]); w.y = cvt_pk_bf16(v[2], v[3]); w.z = cvt_pk_bf16(v[4], v[5]); w.w = cvt_pk_bf16(v[6], v[7]);
;                         if (d0 < 64) *(u32x4*)(MK + (size_t)row * 384 + hd * 96 + d0 + 8 * fq) = w;
;                         else *(u32x4*)(MV + (size_t)row * 256 + hd * 64 + (d0 - 64) + 8 * fq) = w;
.LBB0_365:
	s_or_b64 exec, exec, s[2:3]
	v_mov_b32_e32 v127, v0
	v_lshl_add_u64 v[82:83], v[96:97], 0, v[126:127]
	global_store_dwordx4 v[82:83], v[90:93], off
	v_add_u32_e32 v86, 0xa0, v144
	v_lshlrev_b32_e32 v82, 1, v86
	v_ashrrev_i32_e32 v83, 31, v82
	v_lshl_add_u64 v[90:91], v[82:83], 2, s[24:25]
	s_and_saveexec_b64 s[0:1], s[12:13]
	s_xor_b64 s[0:1], exec, s[0:1]
	s_cbranch_execz .LBB0_371
	v_mov_b32_e32 v82, v235
	v_ashrrev_i32_e32 v87, 31, v86
	s_and_saveexec_b64 s[2:3], s[8:9]
	s_xor_b64 s[2:3], exec, s[2:3]
	s_cbranch_execz .LBB0_368
	v_lshlrev_b64 v[84:85], 9, v[86:87]
	v_lshl_add_u64 v[84:85], s[22:23], 0, v[84:85]
	s_lshl_b32 s14, s64, 1
	s_mov_b32 s15, s89
	v_lshl_add_u64 v[84:85], v[84:85], 0, s[14:15]
	v_lshlrev_b32_e32 v86, 1, v154
	v_mov_b32_e32 v87, v0
	s_movk_i32 s14, 0xff80
	v_lshl_add_u64 v[84:85], v[84:85], 0, v[86:87]
	s_mov_b32 s15, -1
	v_lshl_add_u64 v[88:89], v[84:85], 0, s[14:15]
.LBB0_368:
	s_andn2_saveexec_b64 s[2:3], s[2:3]
	v_mov_b64_e32 v[84:85], s[20:21]
	s_movk_i32 s14, 0x300
	v_mad_i64_i32 v[84:85], s[14:15], v86, s14, v[84:85]
	v_lshl_add_u64 v[84:85], s[88:89], 1, v[84:85]
	v_lshlrev_b32_e32 v86, 1, v154
	v_mov_b32_e32 v87, v0
	v_lshl_add_u64 v[88:89], v[84:85], 0, v[86:87]
	s_or_b64 exec, exec, s[2:3]
	v_pk_mul_f32 v[78:79], v[78:79], v[82:83] op_sel_hi:[1,0]
	v_pk_mul_f32 v[80:81], v[80:81], v[82:83] op_sel_hi:[1,0]
	v_pk_mul_f32 v[74:75], v[74:75], v[82:83] op_sel_hi:[1,0]
	v_pk_mul_f32 v[76:77], v[76:77], v[82:83] op_sel_hi:[1,0]
	v_cvt_pk_bf16_f32 v82, v78, v79
	v_cvt_pk_bf16_f32 v83, v80, v81
	v_cvt_pk_bf16_f32 v84, v74, v75
	v_cvt_pk_bf16_f32 v85, v76, v77
.LBB0_371:
	s_andn2_saveexec_b64 s[2:3], s[0:1]
	s_cbranch_execz .LBB0_375
	v_mov_b32_e32 v82, v234
	v_pk_mul_f32 v[78:79], v[78:79], v[82:83] op_sel_hi:[1,0]
	v_pk_mul_f32 v[80:81], v[80:81], v[82:83] op_sel_hi:[1,0]
	v_pk_mul_f32 v[74:75], v[74:75], v[82:83] op_sel_hi:[1,0]
	v_pk_mul_f32 v[76:77], v[76:77], v[82:83] op_sel_hi:[1,0]
	s_and_saveexec_b64 s[0:1], s[10:11]
	s_xor_b64 s[0:1], exec, s[0:1]
	s_andn2_saveexec_b64 s[36:37], s[0:1]
	s_cbranch_execz .LBB0_374
	v_mov_b32_e32 v83, v220
	v_cndmask_b32_e64 v82, v155, v103, s[6:7]
	v_lshlrev_b32_e32 v83, 2, v83
	v_xor_b32_e32 v83, 64, v83
	v_lshlrev_b32_e32 v85, 6, v82
	ds_bpermute_b32 v84, v83, v78
	global_load_dwordx2 v[174:175], v85, s[26:27]
	global_load_dwordx2 v[176:177], v85, s[26:27] offset:8
	global_load_dwordx2 v[178:179], v85, s[26:27] offset:16
	global_load_dwordx2 v[180:181], v85, s[26:27] offset:24
	global_load_dwordx2 v[182:183], v85, s[26:27] offset:32
	global_load_dwordx2 v[184:185], v85, s[26:27] offset:40
	global_load_dwordx2 v[208:209], v85, s[26:27] offset:48
	global_load_dwordx2 v[210:211], v85, s[26:27] offset:56
	s_movk_i32 s0, 0x7f60
	v_cmp_gt_i32_e64 s[14:15], s0, v144
	s_waitcnt vmcnt(7) lgkmcnt(0)
	v_mul_f32_e32 v83, v175, v84
	v_cndmask_b32_e64 v83, v83, -v83, vcc
	v_fmac_f32_e32 v83, v78, v174
	v_mov_b32_e32 v82, v220
	v_cndmask_b32_e64 v78, v78, v83, s[14:15]
	v_lshlrev_b32_e32 v82, 2, v82
	v_xor_b32_e32 v82, 64, v82
	ds_bpermute_b32 v84, v82, v79
	s_waitcnt vmcnt(6) lgkmcnt(0)
	v_mul_f32_e32 v83, v177, v84
	v_cndmask_b32_e64 v83, v83, -v83, vcc
	v_fmac_f32_e32 v83, v79, v176
	v_mov_b32_e32 v82, v220
	v_cndmask_b32_e64 v79, v79, v83, s[14:15]
	v_lshlrev_b32_e32 v82, 2, v82
	v_xor_b32_e32 v82, 64, v82
	ds_bpermute_b32 v84, v82, v80
	s_waitcnt vmcnt(5) lgkmcnt(0)
	v_mul_f32_e32 v83, v179, v84
	v_cndmask_b32_e64 v83, v83, -v83, vcc
	v_fmac_f32_e32 v83, v80, v178
	v_mov_b32_e32 v82, v220
	v_cndmask_b32_e64 v80, v80, v83, s[14:15]
	v_lshlrev_b32_e32 v82, 2, v82
	v_xor_b32_e32 v82, 64, v82
	ds_bpermute_b32 v84, v82, v81
	s_waitcnt vmcnt(4) lgkmcnt(0)
	v_mul_f32_e32 v83, v181, v84
	v_cndmask_b32_e64 v83, v83, -v83, vcc
	v_fmac_f32_e32 v83, v81, v180
	v_mov_b32_e32 v82, v220
	v_cndmask_b32_e64 v81, v81, v83, s[14:15]
	v_lshlrev_b32_e32 v82, 2, v82
	v_xor_b32_e32 v82, 64, v82
	ds_bpermute_b32 v84, v82, v74
	s_waitcnt vmcnt(3) lgkmcnt(0)
	v_mul_f32_e32 v83, v183, v84
	v_cndmask_b32_e64 v83, v83, -v83, vcc
	v_fmac_f32_e32 v83, v74, v182
	v_mov_b32_e32 v82, v220
	v_cndmask_b32_e64 v74, v74, v83, s[14:15]
	v_lshlrev_b32_e32 v82, 2, v82
	v_xor_b32_e32 v82, 64, v82
	ds_bpermute_b32 v84, v82, v75
	s_waitcnt vmcnt(2) lgkmcnt(0)
	v_mul_f32_e32 v83, v185, v84
	v_cndmask_b32_e64 v83, v83, -v83, vcc
	v_fmac_f32_e32 v83, v75, v184
	v_mov_b32_e32 v82, v220
	v_cndmask_b32_e64 v75, v75, v83, s[14:15]
	v_lshlrev_b32_e32 v82, 2, v82
	v_xor_b32_e32 v82, 64, v82
	ds_bpermute_b32 v84, v82, v76
	s_waitcnt vmcnt(1) lgkmcnt(0)
	v_mul_f32_e32 v83, v209, v84
	v_cndmask_b32_e64 v83, v83, -v83, vcc
	v_fmac_f32_e32 v83, v76, v208
	v_mov_b32_e32 v82, v220
	v_cndmask_b32_e64 v76, v76, v83, s[14:15]
	v_lshlrev_b32_e32 v82, 2, v82
	v_xor_b32_e32 v82, 64, v82
	ds_bpermute_b32 v84, v82, v77
	s_waitcnt vmcnt(0) lgkmcnt(0)
	v_mul_f32_e32 v83, v211, v84
	v_cndmask_b32_e64 v83, v83, -v83, vcc
	v_fmac_f32_e32 v83, v77, v210
	v_cndmask_b32_e64 v77, v77, v83, s[14:15]

; __device__ __forceinline__ unsigned cvt_pk_bf16(float lo, float hi) { const f32x2_ v = {lo, hi}; return __builtin_bit_cast(unsigned, __builtin_convertvector(v, bf16x2_)); }
;     __device__ __forceinline__ void operator()(const f32x4 (&acc)[2][2][4][2], const Unit& u, int wr, int wc, int fr, int fq) const {
;     ...
;                     const int row = row0 + ai * 128 + m * 16;
;                     float v[8];
;                     if (cg0 < 384) {
;                         const float rs = RSTD[row * 2];
; #pragma unroll
;                         for (int n = 0; n < 2; ++n)
; #pragma unroll
;                             for (int j = 0; j < 4; ++j) v[4 * n + j] = acc[ai][bj][m][n][j] * rs;
;     ...
;                         *(u32x4*)(MQ + (size_t)row * 384 + cg0 + 8 * fq) = w;
;                     } else {
;                         const float rs = RSTD[row * 2 + 1];
; #pragma unroll
;                         for (int n = 0; n < 2; ++n)
; #pragma unroll
;                             for (int j = 0; j < 4; ++j) v[4 * n + j] = acc[ai][bj][m][n][j] * rs;
;                         const int cp = cg0 - 384, hd = cp >> 7, d0 = cp & 127;
;                         u32x4 w; w.x = cvt_pk_bf16(v[0], v[1]); w.y = cvt_pk_bf16(v[2], v[3]); w.z = cvt_pk_bf16(v[4], v[5]); w.w = cvt_pk_bf16(v[6], v[7]);
;                         if (d0 < 64) *(u32x4*)(MK + (size_t)row * 384 + hd * 96 + d0 + 8 * fq) = w;
;                         else *(u32x4*)(MV + (size_t)row * 256 + hd * 64 + (d0 - 64) + 8 * fq) = w;
.LBB0_375:
	s_or_b64 exec, exec, s[2:3]
	v_mov_b32_e32 v127, v0
	v_lshl_add_u64 v[74:75], v[88:89], 0, v[126:127]
	global_store_dwordx4 v[74:75], v[82:85], off
	v_add_u32_e32 v78, 0xb0, v144
	v_lshlrev_b32_e32 v74, 1, v78
	v_ashrrev_i32_e32 v75, 31, v74
	v_lshl_add_u64 v[82:83], v[74:75], 2, s[24:25]
	s_and_saveexec_b64 s[0:1], s[12:13]
	s_xor_b64 s[0:1], exec, s[0:1]
	s_cbranch_execz .LBB0_381
	v_mov_b32_e32 v74, v237
	v_ashrrev_i32_e32 v79, 31, v78
	s_and_saveexec_b64 s[2:3], s[8:9]
	s_xor_b64 s[2:3], exec, s[2:3]
	s_cbranch_execz .LBB0_378
	v_lshlrev_b64 v[76:77], 9, v[78:79]
	v_lshl_add_u64 v[76:77], s[22:23], 0, v[76:77]
	s_lshl_b32 s12, s64, 1
	s_mov_b32 s13, s89
	v_lshl_add_u64 v[76:77], v[76:77], 0, s[12:13]
	v_lshlrev_b32_e32 v78, 1, v154
	v_mov_b32_e32 v79, v0
	s_movk_i32 s12, 0xff80
	v_lshl_add_u64 v[76:77], v[76:77], 0, v[78:79]
	s_mov_b32 s13, -1
	v_lshl_add_u64 v[80:81], v[76:77], 0, s[12:13]
.LBB0_378:
	s_andn2_saveexec_b64 s[2:3], s[2:3]
	v_mov_b64_e32 v[76:77], s[20:21]
	s_movk_i32 s12, 0x300
	v_mad_i64_i32 v[76:77], s[12:13], v78, s12, v[76:77]
	v_lshl_add_u64 v[76:77], s[88:89], 1, v[76:77]
	v_lshlrev_b32_e32 v78, 1, v154
	v_mov_b32_e32 v79, v0
	v_lshl_add_u64 v[80:81], v[76:77], 0, v[78:79]
	s_or_b64 exec, exec, s[2:3]
	v_pk_mul_f32 v[70:71], v[70:71], v[74:75] op_sel_hi:[1,0]
	v_pk_mul_f32 v[72:73], v[72:73], v[74:75] op_sel_hi:[1,0]
	v_pk_mul_f32 v[66:67], v[66:67], v[74:75] op_sel_hi:[1,0]
	v_pk_mul_f32 v[68:69], v[68:69], v[74:75] op_sel_hi:[1,0]
	v_cvt_pk_bf16_f32 v74, v70, v71
	v_cvt_pk_bf16_f32 v75, v72, v73
	v_cvt_pk_bf16_f32 v76, v66, v67
	v_cvt_pk_bf16_f32 v77, v68, v69
.LBB0_381:
	s_or_saveexec_b64 s[2:3], s[0:1]
	v_readlane_b32 s64, v254, 51
	v_readlane_b32 s65, v254, 52
	s_xor_b64 exec, exec, s[2:3]
	s_cbranch_execz .LBB0_387
	v_mov_b32_e32 v74, v236
	v_pk_mul_f32 v[70:71], v[70:71], v[74:75] op_sel_hi:[1,0]
	v_pk_mul_f32 v[72:73], v[72:73], v[74:75] op_sel_hi:[1,0]
	v_pk_mul_f32 v[66:67], v[66:67], v[74:75] op_sel_hi:[1,0]
	v_pk_mul_f32 v[68:69], v[68:69], v[74:75] op_sel_hi:[1,0]
	s_and_saveexec_b64 s[0:1], s[10:11]
	s_xor_b64 s[0:1], exec, s[0:1]
	s_andn2_saveexec_b64 s[12:13], s[0:1]
	s_cbranch_execz .LBB0_386
	v_mov_b32_e32 v75, v220
	v_cndmask_b32_e64 v74, v153, v103, s[6:7]
	v_lshlrev_b32_e32 v75, 2, v75
	v_xor_b32_e32 v75, 64, v75
	v_lshlrev_b32_e32 v77, 6, v74
	ds_bpermute_b32 v76, v75, v70
	global_load_dwordx2 v[174:175], v77, s[26:27]
	global_load_dwordx2 v[176:177], v77, s[26:27] offset:8
	global_load_dwordx2 v[178:179], v77, s[26:27] offset:16
	global_load_dwordx2 v[180:181], v77, s[26:27] offset:24
	global_load_dwordx2 v[182:183], v77, s[26:27] offset:32
	global_load_dwordx2 v[184:185], v77, s[26:27] offset:40
	global_load_dwordx2 v[208:209], v77, s[26:27] offset:48
	global_load_dwordx2 v[210:211], v77, s[26:27] offset:56
	s_movk_i32 s0, 0x7f50
	v_cmp_gt_i32_e64 s[10:11], s0, v144
	s_waitcnt vmcnt(7) lgkmcnt(0)
	v_mul_f32_e32 v75, v175, v76
	v_cndmask_b32_e64 v75, v75, -v75, vcc
	v_fmac_f32_e32 v75, v70, v174
	v_mov_b32_e32 v74, v220
	v_cndmask_b32_e64 v70, v70, v75, s[10:11]
	v_lshlrev_b32_e32 v74, 2, v74
	v_xor_b32_e32 v74, 64, v74
	ds_bpermute_b32 v76, v74, v71
	s_waitcnt vmcnt(6) lgkmcnt(0)
	v_mul_f32_e32 v75, v177, v76
	v_cndmask_b32_e64 v75, v75, -v75, vcc
	v_fmac_f32_e32 v75, v71, v176
	v_mov_b32_e32 v74, v220
	v_cndmask_b32_e64 v71, v71, v75, s[10:11]
	v_lshlrev_b32_e32 v74, 2, v74
	v_xor_b32_e32 v74, 64, v74
	ds_bpermute_b32 v76, v74, v72
	s_waitcnt vmcnt(5) lgkmcnt(0)
	v_mul_f32_e32 v75, v179, v76
	v_cndmask_b32_e64 v75, v75, -v75, vcc
	v_fmac_f32_e32 v75, v72, v178
	v_mov_b32_e32 v74, v220
	v_cndmask_b32_e64 v72, v72, v75, s[10:11]
	v_lshlrev_b32_e32 v74, 2, v74
	v_xor_b32_e32 v74, 64, v74
	ds_bpermute_b32 v76, v74, v73
	s_waitcnt vmcnt(4) lgkmcnt(0)
	v_mul_f32_e32 v75, v181, v76
	v_cndmask_b32_e64 v75, v75, -v75, vcc
	v_fmac_f32_e32 v75, v73, v180
	v_mov_b32_e32 v74, v220
	v_cndmask_b32_e64 v73, v73, v75, s[10:11]
	v_lshlrev_b32_e32 v74, 2, v74
	v_xor_b32_e32 v74, 64, v74
	ds_bpermute_b32 v76, v74, v66
	s_waitcnt vmcnt(3) lgkmcnt(0)
	v_mul_f32_e32 v75, v183, v76
	v_cndmask_b32_e64 v75, v75, -v75, vcc
	v_fmac_f32_e32 v75, v66, v182
	v_mov_b32_e32 v74, v220
	v_cndmask_b32_e64 v66, v66, v75, s[10:11]
	v_lshlrev_b32_e32 v74, 2, v74
	v_xor_b32_e32 v74, 64, v74
	ds_bpermute_b32 v76, v74, v67
	s_waitcnt vmcnt(2) lgkmcnt(0)
	v_mul_f32_e32 v75, v185, v76
	v_cndmask_b32_e64 v75, v75, -v75, vcc
	v_fmac_f32_e32 v75, v67, v184
	v_mov_b32_e32 v74, v220
	v_cndmask_b32_e64 v67, v67, v75, s[10:11]
	v_lshlrev_b32_e32 v74, 2, v74
	v_xor_b32_e32 v74, 64, v74
	ds_bpermute_b32 v76, v74, v68
	s_waitcnt vmcnt(1) lgkmcnt(0)
	v_mul_f32_e32 v75, v209, v76
	v_cndmask_b32_e64 v75, v75, -v75, vcc
	v_fmac_f32_e32 v75, v68, v208
	v_mov_b32_e32 v74, v220
	v_cndmask_b32_e64 v68, v68, v75, s[10:11]
	v_lshlrev_b32_e32 v74, 2, v74
	v_xor_b32_e32 v74, 64, v74
	ds_bpermute_b32 v76, v74, v69
	s_waitcnt vmcnt(0) lgkmcnt(0)
	v_mul_f32_e32 v75, v211, v76
	v_cndmask_b32_e64 v75, v75, -v75, vcc
	v_fmac_f32_e32 v75, v69, v210
	v_cndmask_b32_e64 v69, v69, v75, s[10:11]

;     __device__ __forceinline__ void operator()(const f32x4 (&acc)[2][2][4][2], const Unit& u, int wr, int wc, int fr, int fq) const {
;     ...
;         for (int bj = 0; bj < 2; ++bj) {
;             const int cg0 = u.pn * 256 + bj * 128 + wc * 32;
;             if (cg0 >= 896) continue;
; #pragma unroll
;             for (int ai = 0; ai < 2; ++ai)
; #pragma unroll
;                 for (int m = 0; m < 4; ++m) {
;                     __builtin_amdgcn_sched_barrier(0);
;                     const int row = row0 + ai * 128 + m * 16;
;                     float v[8];
;                     if (cg0 < 384) {
;                         const float rs = RSTD[row * 2];
; #pragma unroll
;                         for (int n = 0; n < 2; ++n)
; #pragma unroll
;                             for (int j = 0; j < 4; ++j) v[4 * n + j] = acc[ai][bj][m][n][j] * rs;
;                         const int d0 = cg0 % 96;
;                         if (d0 == 64) {
;                             const bool lat = row < RL; const int t = row & 8191; const int pos = (fq >> 1) ? (t & 63) : (t >> 6); const bool isx2 = fq & 1;
; #pragma unroll
;                             for (int e = 0; e < 8; ++e) {
;                                 const float pr = shflx(v[e], 16);
;                                 const float2 cs = RT[pos * 8 + e];
;                                 const float r = isx2 ? (pr * cs.y + v[e] * cs.x) : (v[e] * cs.x - pr * cs.y);
;                                 v[e] = lat ? r : v[e];
;                             }
;                         }
;                         u32x4 w; w.x = cvt_pk_bf16(v[0], v[1]); w.y = cvt_pk_bf16(v[2], v[3]); w.z = cvt_pk_bf16(v[4], v[5]); w.w = cvt_pk_bf16(v[6], v[7]);
;                         *(u32x4*)(MQ + (size_t)row * 384 + cg0 + 8 * fq) = w;
;                     } else {
;                         const float rs = RSTD[row * 2 + 1];
; #pragma unroll
;                         for (int n = 0; n < 2; ++n)
; #pragma unroll
;                             for (int j = 0; j < 4; ++j) v[4 * n + j] = acc[ai][bj][m][n][j] * rs;
;                         const int cp = cg0 - 384, hd = cp >> 7, d0 = cp & 127;
;                         u32x4 w; w.x = cvt_pk_bf16(v[0], v[1]); w.y = cvt_pk_bf16(v[2], v[3]); w.z = cvt_pk_bf16(v[4], v[5]); w.w = cvt_pk_bf16(v[6], v[7]);
.LBB0_388:
	s_or_b64 exec, exec, s[34:35]
	v_or_b32_e32 v66, 0x80, v142
	s_movk_i32 s0, 0x380
	v_mov_b64_e32 v[242:243], 0x200
	v_mov_b64_e32 v[244:245], 0x1ff
	v_cmp_gt_i32_e64 s[10:11], s0, v66
	s_and_saveexec_b64 s[34:35], s[10:11]
	s_cbranch_execz .LBB0_297
	s_movk_i32 s0, 0x17f
	v_cmp_lt_i32_e64 s[12:13], s0, v66
	s_add_i32 s0, s63, 0xffffff00
	s_lshr_b32 s63, s0, 1
	s_lshr_b32 s0, s0, 7
	s_mul_i32 s88, s0, 0x60
	s_mov_b32 s0, 0x2aaaaaab
	v_mul_hi_i32 v67, v66, s0
	v_lshrrev_b32_e32 v68, 31, v67
	v_lshrrev_b32_e32 v67, 4, v67
	v_add_u32_e32 v67, v67, v68
	s_movk_i32 s0, 0x60
	v_mul_lo_u32 v67, v67, s0
	v_sub_u32_e32 v66, v66, v67
	v_cmp_ne_u32_e64 s[10:11], 64, v66
	v_lshl_add_u64 v[72:73], v[146:147], 2, s[24:25]
	s_and_saveexec_b64 s[0:1], s[12:13]
	s_xor_b64 s[0:1], exec, s[0:1]
	s_cbranch_execz .LBB0_395
	v_mov_b32_e32 v66, v223
	v_ashrrev_i32_e32 v145, 31, v144
	s_and_saveexec_b64 s[2:3], s[8:9]
	s_xor_b64 s[2:3], exec, s[2:3]
	s_cbranch_execz .LBB0_392
	v_lshlrev_b64 v[68:69], 9, v[144:145]
	v_lshl_add_u64 v[68:69], s[22:23], 0, v[68:69]
	s_lshl_b32 s14, s63, 1
	s_mov_b32 s15, s89
	v_lshl_add_u64 v[68:69], v[68:69], 0, s[14:15]
	v_lshlrev_b32_e32 v70, 1, v154
	v_mov_b32_e32 v71, v0
	s_movk_i32 s14, 0xff80
	v_lshl_add_u64 v[68:69], v[68:69], 0, v[70:71]
	s_mov_b32 s15, -1
	v_lshl_add_u64 v[70:71], v[68:69], 0, s[14:15]
.LBB0_392:
	s_andn2_saveexec_b64 s[2:3], s[2:3]
	v_mov_b64_e32 v[68:69], s[20:21]
	s_movk_i32 s14, 0x300
	v_mad_i64_i32 v[68:69], s[14:15], v144, s14, v[68:69]
	v_lshl_add_u64 v[68:69], s[88:89], 1, v[68:69]
	v_lshlrev_b32_e32 v70, 1, v154
	v_mov_b32_e32 v71, v0
	v_lshl_add_u64 v[70:71], v[68:69], 0, v[70:71]
	s_or_b64 exec, exec, s[2:3]
	v_pk_mul_f32 v[62:63], v[62:63], v[66:67] op_sel_hi:[1,0]
	v_pk_mul_f32 v[64:65], v[64:65], v[66:67] op_sel_hi:[1,0]
	v_pk_mul_f32 v[58:59], v[58:59], v[66:67] op_sel_hi:[1,0]
	v_pk_mul_f32 v[60:61], v[60:61], v[66:67] op_sel_hi:[1,0]
	v_cvt_pk_bf16_f32 v66, v62, v63
	v_cvt_pk_bf16_f32 v67, v64, v65
	v_cvt_pk_bf16_f32 v68, v58, v59
	v_cvt_pk_bf16_f32 v69, v60, v61
.LBB0_395:
	s_andn2_saveexec_b64 s[2:3], s[0:1]
	s_cbranch_execz .LBB0_399
	v_mov_b32_e32 v66, v222
	v_pk_mul_f32 v[62:63], v[62:63], v[66:67] op_sel_hi:[1,0]
	v_pk_mul_f32 v[64:65], v[64:65], v[66:67] op_sel_hi:[1,0]
	v_pk_mul_f32 v[58:59], v[58:59], v[66:67] op_sel_hi:[1,0]
	v_pk_mul_f32 v[60:61], v[60:61], v[66:67] op_sel_hi:[1,0]
	s_and_saveexec_b64 s[0:1], s[10:11]
	s_xor_b64 s[0:1], exec, s[0:1]
	s_andn2_saveexec_b64 s[36:37], s[0:1]
	s_cbranch_execz .LBB0_398
	v_mov_b32_e32 v67, v220
	v_cndmask_b32_e64 v66, v157, v158, s[6:7]
	v_lshlrev_b32_e32 v67, 2, v67
	v_xor_b32_e32 v67, 64, v67
	v_lshlrev_b32_e32 v69, 6, v66
	ds_bpermute_b32 v68, v67, v62
	global_load_dwordx2 v[174:175], v69, s[26:27]
	global_load_dwordx2 v[176:177], v69, s[26:27] offset:8
	global_load_dwordx2 v[178:179], v69, s[26:27] offset:16
	global_load_dwordx2 v[180:181], v69, s[26:27] offset:24
	global_load_dwordx2 v[182:183], v69, s[26:27] offset:32
	global_load_dwordx2 v[184:185], v69, s[26:27] offset:40
	global_load_dwordx2 v[208:209], v69, s[26:27] offset:48
	global_load_dwordx2 v[210:211], v69, s[26:27] offset:56
	v_cmp_gt_i32_e64 s[14:15], s95, v144
	s_waitcnt vmcnt(7) lgkmcnt(0)
	v_mul_f32_e32 v67, v175, v68
	v_cndmask_b32_e64 v67, v67, -v67, vcc
	v_fmac_f32_e32 v67, v62, v174
	v_mov_b32_e32 v66, v220
	v_cndmask_b32_e64 v62, v62, v67, s[14:15]
	v_lshlrev_b32_e32 v66, 2, v66
	v_xor_b32_e32 v66, 64, v66
	ds_bpermute_b32 v68, v66, v63
	s_waitcnt vmcnt(6) lgkmcnt(0)
	v_mul_f32_e32 v67, v177, v68
	v_cndmask_b32_e64 v67, v67, -v67, vcc
	v_fmac_f32_e32 v67, v63, v176
	v_mov_b32_e32 v66, v220
	v_cndmask_b32_e64 v63, v63, v67, s[14:15]
	v_lshlrev_b32_e32 v66, 2, v66
	v_xor_b32_e32 v66, 64, v66
	ds_bpermute_b32 v68, v66, v64
	s_waitcnt vmcnt(5) lgkmcnt(0)
	v_mul_f32_e32 v67, v179, v68
	v_cndmask_b32_e64 v67, v67, -v67, vcc
	v_fmac_f32_e32 v67, v64, v178
	v_mov_b32_e32 v66, v220
	v_cndmask_b32_e64 v64, v64, v67, s[14:15]
	v_lshlrev_b32_e32 v66, 2, v66
	v_xor_b32_e32 v66, 64, v66
	ds_bpermute_b32 v68, v66, v65
	s_waitcnt vmcnt(4) lgkmcnt(0)
	v_mul_f32_e32 v67, v181, v68
	v_cndmask_b32_e64 v67, v67, -v67, vcc
	v_fmac_f32_e32 v67, v65, v180
	v_mov_b32_e32 v66, v220
	v_cndmask_b32_e64 v65, v65, v67, s[14:15]
	v_lshlrev_b32_e32 v66, 2, v66
	v_xor_b32_e32 v66, 64, v66
	ds_bpermute_b32 v68, v66, v58
	s_waitcnt vmcnt(3) lgkmcnt(0)
	v_mul_f32_e32 v67, v183, v68
	v_cndmask_b32_e64 v67, v67, -v67, vcc
	v_fmac_f32_e32 v67, v58, v182
	v_mov_b32_e32 v66, v220
	v_cndmask_b32_e64 v58, v58, v67, s[14:15]
	v_lshlrev_b32_e32 v66, 2, v66
	v_xor_b32_e32 v66, 64, v66
	ds_bpermute_b32 v68, v66, v59
	s_waitcnt vmcnt(2) lgkmcnt(0)
	v_mul_f32_e32 v67, v185, v68
	v_cndmask_b32_e64 v67, v67, -v67, vcc
	v_fmac_f32_e32 v67, v59, v184
	v_mov_b32_e32 v66, v220
	v_cndmask_b32_e64 v59, v59, v67, s[14:15]
	v_lshlrev_b32_e32 v66, 2, v66
	v_xor_b32_e32 v66, 64, v66
	ds_bpermute_b32 v68, v66, v60
	s_waitcnt vmcnt(1) lgkmcnt(0)
	v_mul_f32_e32 v67, v209, v68
	v_cndmask_b32_e64 v67, v67, -v67, vcc
	v_fmac_f32_e32 v67, v60, v208
	v_mov_b32_e32 v66, v220
	v_cndmask_b32_e64 v60, v60, v67, s[14:15]
	v_lshlrev_b32_e32 v66, 2, v66
	v_xor_b32_e32 v66, 64, v66
	ds_bpermute_b32 v68, v66, v61
	s_waitcnt vmcnt(0) lgkmcnt(0)
	v_mul_f32_e32 v67, v211, v68
	v_cndmask_b32_e64 v67, v67, -v67, vcc
	v_fmac_f32_e32 v67, v61, v210
	v_cndmask_b32_e64 v61, v61, v67, s[14:15]

; __device__ __forceinline__ unsigned cvt_pk_bf16(float lo, float hi) { const f32x2_ v = {lo, hi}; return __builtin_bit_cast(unsigned, __builtin_convertvector(v, bf16x2_)); }
;     __device__ __forceinline__ void operator()(const f32x4 (&acc)[2][2][4][2], const Unit& u, int wr, int wc, int fr, int fq) const {
;     ...
;                     const int row = row0 + ai * 128 + m * 16;
;                     float v[8];
;                     if (cg0 < 384) {
;                         const float rs = RSTD[row * 2];
; #pragma unroll
;                         for (int n = 0; n < 2; ++n)
; #pragma unroll
;                             for (int j = 0; j < 4; ++j) v[4 * n + j] = acc[ai][bj][m][n][j] * rs;
;     ...
;                         *(u32x4*)(MQ + (size_t)row * 384 + cg0 + 8 * fq) = w;
;                     } else {
;                         const float rs = RSTD[row * 2 + 1];
; #pragma unroll
;                         for (int n = 0; n < 2; ++n)
; #pragma unroll
;                             for (int j = 0; j < 4; ++j) v[4 * n + j] = acc[ai][bj][m][n][j] * rs;
;                         const int cp = cg0 - 384, hd = cp >> 7, d0 = cp & 127;
;                         u32x4 w; w.x = cvt_pk_bf16(v[0], v[1]); w.y = cvt_pk_bf16(v[2], v[3]); w.z = cvt_pk_bf16(v[4], v[5]); w.w = cvt_pk_bf16(v[6], v[7]);
;                         if (d0 < 64) *(u32x4*)(MK + (size_t)row * 384 + hd * 96 + d0 + 8 * fq) = w;
;                         else *(u32x4*)(MV + (size_t)row * 256 + hd * 64 + (d0 - 64) + 8 * fq) = w;
.LBB0_399:
	s_or_b64 exec, exec, s[2:3]
	v_lshlrev_b32_e32 v62, 1, v159
	v_mov_b32_e32 v63, v0
	v_lshl_add_u64 v[58:59], v[70:71], 0, v[62:63]
	global_store_dwordx4 v[58:59], v[66:69], off
	v_or_b32_e32 v64, 16, v144
	v_lshlrev_b32_e32 v58, 1, v64
	v_ashrrev_i32_e32 v59, 31, v58
	v_lshl_add_u64 v[68:69], v[58:59], 2, s[24:25]
	s_and_saveexec_b64 s[0:1], s[12:13]
	s_xor_b64 s[0:1], exec, s[0:1]
	s_cbranch_execz .LBB0_405
	v_mov_b32_e32 v58, v225
	v_ashrrev_i32_e32 v65, 31, v64
	s_and_saveexec_b64 s[2:3], s[8:9]
	s_xor_b64 s[2:3], exec, s[2:3]
	s_cbranch_execz .LBB0_402
	v_lshlrev_b64 v[60:61], 9, v[64:65]
	v_lshl_add_u64 v[60:61], s[22:23], 0, v[60:61]
	s_lshl_b32 s14, s63, 1
	s_mov_b32 s15, s89
	v_lshl_add_u64 v[60:61], v[60:61], 0, s[14:15]
	v_lshlrev_b32_e32 v64, 1, v154
	v_mov_b32_e32 v65, v0
	s_movk_i32 s14, 0xff80
	v_lshl_add_u64 v[60:61], v[60:61], 0, v[64:65]
	s_mov_b32 s15, -1
	v_lshl_add_u64 v[66:67], v[60:61], 0, s[14:15]
.LBB0_402:
	s_andn2_saveexec_b64 s[2:3], s[2:3]
	v_mov_b64_e32 v[60:61], s[20:21]
	s_movk_i32 s14, 0x300
	v_mad_i64_i32 v[60:61], s[14:15], v64, s14, v[60:61]
	v_lshl_add_u64 v[60:61], s[88:89], 1, v[60:61]
	v_lshlrev_b32_e32 v64, 1, v154
	v_mov_b32_e32 v65, v0
	v_lshl_add_u64 v[66:67], v[60:61], 0, v[64:65]
	s_or_b64 exec, exec, s[2:3]
	v_pk_mul_f32 v[54:55], v[54:55], v[58:59] op_sel_hi:[1,0]
	v_pk_mul_f32 v[56:57], v[56:57], v[58:59] op_sel_hi:[1,0]
	v_pk_mul_f32 v[50:51], v[50:51], v[58:59] op_sel_hi:[1,0]
	v_pk_mul_f32 v[52:53], v[52:53], v[58:59] op_sel_hi:[1,0]
	v_cvt_pk_bf16_f32 v58, v54, v55
	v_cvt_pk_bf16_f32 v59, v56, v57
	v_cvt_pk_bf16_f32 v60, v50, v51
	v_cvt_pk_bf16_f32 v61, v52, v53
.LBB0_405:
	s_andn2_saveexec_b64 s[2:3], s[0:1]
	s_cbranch_execz .LBB0_409
	v_mov_b32_e32 v58, v224
	v_pk_mul_f32 v[54:55], v[54:55], v[58:59] op_sel_hi:[1,0]
	v_pk_mul_f32 v[56:57], v[56:57], v[58:59] op_sel_hi:[1,0]
	v_pk_mul_f32 v[50:51], v[50:51], v[58:59] op_sel_hi:[1,0]
	v_pk_mul_f32 v[52:53], v[52:53], v[58:59] op_sel_hi:[1,0]
	s_and_saveexec_b64 s[0:1], s[10:11]
	s_xor_b64 s[0:1], exec, s[0:1]
	s_andn2_saveexec_b64 s[36:37], s[0:1]
	s_cbranch_execz .LBB0_408
	v_mov_b32_e32 v59, v220
	v_cndmask_b32_e64 v58, v156, v158, s[6:7]
	v_lshlrev_b32_e32 v59, 2, v59
	v_xor_b32_e32 v59, 64, v59
	v_lshlrev_b32_e32 v61, 6, v58
	ds_bpermute_b32 v60, v59, v54
	global_load_dwordx2 v[174:175], v61, s[26:27]
	global_load_dwordx2 v[176:177], v61, s[26:27] offset:8
	global_load_dwordx2 v[178:179], v61, s[26:27] offset:16
	global_load_dwordx2 v[180:181], v61, s[26:27] offset:24
	global_load_dwordx2 v[182:183], v61, s[26:27] offset:32
	global_load_dwordx2 v[184:185], v61, s[26:27] offset:40
	global_load_dwordx2 v[208:209], v61, s[26:27] offset:48
	global_load_dwordx2 v[210:211], v61, s[26:27] offset:56
	v_cmp_gt_i32_e64 s[14:15], s95, v64
	s_waitcnt vmcnt(7) lgkmcnt(0)
	v_mul_f32_e32 v59, v175, v60
	v_cndmask_b32_e64 v59, v59, -v59, vcc
	v_fmac_f32_e32 v59, v54, v174
	v_mov_b32_e32 v58, v220
	v_cndmask_b32_e64 v54, v54, v59, s[14:15]
	v_lshlrev_b32_e32 v58, 2, v58
	v_xor_b32_e32 v58, 64, v58
	ds_bpermute_b32 v60, v58, v55
	s_waitcnt vmcnt(6) lgkmcnt(0)
	v_mul_f32_e32 v59, v177, v60
	v_cndmask_b32_e64 v59, v59, -v59, vcc
	v_fmac_f32_e32 v59, v55, v176
	v_mov_b32_e32 v58, v220
	v_cndmask_b32_e64 v55, v55, v59, s[14:15]
	v_lshlrev_b32_e32 v58, 2, v58
	v_xor_b32_e32 v58, 64, v58
	ds_bpermute_b32 v60, v58, v56
	s_waitcnt vmcnt(5) lgkmcnt(0)
	v_mul_f32_e32 v59, v179, v60
	v_cndmask_b32_e64 v59, v59, -v59, vcc
	v_fmac_f32_e32 v59, v56, v178
	v_mov_b32_e32 v58, v220
	v_cndmask_b32_e64 v56, v56, v59, s[14:15]
	v_lshlrev_b32_e32 v58, 2, v58
	v_xor_b32_e32 v58, 64, v58
	ds_bpermute_b32 v60, v58, v57
	s_waitcnt vmcnt(4) lgkmcnt(0)
	v_mul_f32_e32 v59, v181, v60
	v_cndmask_b32_e64 v59, v59, -v59, vcc
	v_fmac_f32_e32 v59, v57, v180
	v_mov_b32_e32 v58, v220
	v_cndmask_b32_e64 v57, v57, v59, s[14:15]
	v_lshlrev_b32_e32 v58, 2, v58
	v_xor_b32_e32 v58, 64, v58
	ds_bpermute_b32 v60, v58, v50
	s_waitcnt vmcnt(3) lgkmcnt(0)
	v_mul_f32_e32 v59, v183, v60
	v_cndmask_b32_e64 v59, v59, -v59, vcc
	v_fmac_f32_e32 v59, v50, v182
	v_mov_b32_e32 v58, v220
	v_cndmask_b32_e64 v50, v50, v59, s[14:15]
	v_lshlrev_b32_e32 v58, 2, v58
	v_xor_b32_e32 v58, 64, v58
	ds_bpermute_b32 v60, v58, v51
	s_waitcnt vmcnt(2) lgkmcnt(0)
	v_mul_f32_e32 v59, v185, v60
	v_cndmask_b32_e64 v59, v59, -v59, vcc
	v_fmac_f32_e32 v59, v51, v184
	v_mov_b32_e32 v58, v220
	v_cndmask_b32_e64 v51, v51, v59, s[14:15]
	v_lshlrev_b32_e32 v58, 2, v58
	v_xor_b32_e32 v58, 64, v58
	ds_bpermute_b32 v60, v58, v52
	s_waitcnt vmcnt(1) lgkmcnt(0)
	v_mul_f32_e32 v59, v209, v60
	v_cndmask_b32_e64 v59, v59, -v59, vcc
	v_fmac_f32_e32 v59, v52, v208
	v_mov_b32_e32 v58, v220
	v_cndmask_b32_e64 v52, v52, v59, s[14:15]
	v_lshlrev_b32_e32 v58, 2, v58
	v_xor_b32_e32 v58, 64, v58
	ds_bpermute_b32 v60, v58, v53
	s_waitcnt vmcnt(0) lgkmcnt(0)
	v_mul_f32_e32 v59, v211, v60
	v_cndmask_b32_e64 v59, v59, -v59, vcc
	v_fmac_f32_e32 v59, v53, v210
	v_cndmask_b32_e64 v53, v53, v59, s[14:15]

; __device__ __forceinline__ unsigned cvt_pk_bf16(float lo, float hi) { const f32x2_ v = {lo, hi}; return __builtin_bit_cast(unsigned, __builtin_convertvector(v, bf16x2_)); }
;     __device__ __forceinline__ void operator()(const f32x4 (&acc)[2][2][4][2], const Unit& u, int wr, int wc, int fr, int fq) const {
;     ...
;                     const int row = row0 + ai * 128 + m * 16;
;                     float v[8];
;                     if (cg0 < 384) {
;                         const float rs = RSTD[row * 2];
; #pragma unroll
;                         for (int n = 0; n < 2; ++n)
; #pragma unroll
;                             for (int j = 0; j < 4; ++j) v[4 * n + j] = acc[ai][bj][m][n][j] * rs;
;     ...
;                         *(u32x4*)(MQ + (size_t)row * 384 + cg0 + 8 * fq) = w;
;                     } else {
;                         const float rs = RSTD[row * 2 + 1];
; #pragma unroll
;                         for (int n = 0; n < 2; ++n)
; #pragma unroll
;                             for (int j = 0; j < 4; ++j) v[4 * n + j] = acc[ai][bj][m][n][j] * rs;
;                         const int cp = cg0 - 384, hd = cp >> 7, d0 = cp & 127;
;                         u32x4 w; w.x = cvt_pk_bf16(v[0], v[1]); w.y = cvt_pk_bf16(v[2], v[3]); w.z = cvt_pk_bf16(v[4], v[5]); w.w = cvt_pk_bf16(v[6], v[7]);
;                         if (d0 < 64) *(u32x4*)(MK + (size_t)row * 384 + hd * 96 + d0 + 8 * fq) = w;
;                         else *(u32x4*)(MV + (size_t)row * 256 + hd * 64 + (d0 - 64) + 8 * fq) = w;
.LBB0_409:
	s_or_b64 exec, exec, s[2:3]
	v_mov_b32_e32 v63, v0
	v_lshl_add_u64 v[50:51], v[66:67], 0, v[62:63]
	global_store_dwordx4 v[50:51], v[58:61], off
	v_or_b32_e32 v54, 32, v144
	v_lshlrev_b32_e32 v50, 1, v54
	v_ashrrev_i32_e32 v51, 31, v50
	v_lshl_add_u64 v[58:59], v[50:51], 2, s[24:25]
	s_and_saveexec_b64 s[0:1], s[12:13]
	s_xor_b64 s[0:1], exec, s[0:1]
	s_cbranch_execz .LBB0_415
	v_mov_b32_e32 v50, v227
	v_ashrrev_i32_e32 v55, 31, v54
	s_and_saveexec_b64 s[2:3], s[8:9]
	s_xor_b64 s[2:3], exec, s[2:3]
	s_cbranch_execz .LBB0_412
	v_lshlrev_b64 v[52:53], 9, v[54:55]
	v_lshl_add_u64 v[52:53], s[22:23], 0, v[52:53]
	s_lshl_b32 s14, s63, 1
	s_mov_b32 s15, s89
	v_lshl_add_u64 v[52:53], v[52:53], 0, s[14:15]
	v_lshlrev_b32_e32 v54, 1, v154
	v_mov_b32_e32 v55, v0
	s_movk_i32 s14, 0xff80
	v_lshl_add_u64 v[52:53], v[52:53], 0, v[54:55]
	s_mov_b32 s15, -1
	v_lshl_add_u64 v[56:57], v[52:53], 0, s[14:15]
.LBB0_412:
	s_andn2_saveexec_b64 s[2:3], s[2:3]
	v_mov_b64_e32 v[52:53], s[20:21]
	s_movk_i32 s14, 0x300
	v_mad_i64_i32 v[52:53], s[14:15], v54, s14, v[52:53]
	v_lshl_add_u64 v[52:53], s[88:89], 1, v[52:53]
	v_lshlrev_b32_e32 v54, 1, v154
	v_mov_b32_e32 v55, v0
	v_lshl_add_u64 v[56:57], v[52:53], 0, v[54:55]
	s_or_b64 exec, exec, s[2:3]
	v_pk_mul_f32 v[46:47], v[46:47], v[50:51] op_sel_hi:[1,0]
	v_pk_mul_f32 v[48:49], v[48:49], v[50:51] op_sel_hi:[1,0]
	v_pk_mul_f32 v[42:43], v[42:43], v[50:51] op_sel_hi:[1,0]
	v_pk_mul_f32 v[44:45], v[44:45], v[50:51] op_sel_hi:[1,0]
	v_cvt_pk_bf16_f32 v50, v46, v47
	v_cvt_pk_bf16_f32 v51, v48, v49
	v_cvt_pk_bf16_f32 v52, v42, v43
	v_cvt_pk_bf16_f32 v53, v44, v45
.LBB0_415:
	s_andn2_saveexec_b64 s[2:3], s[0:1]
	s_cbranch_execz .LBB0_419
	v_mov_b32_e32 v50, v226
	v_pk_mul_f32 v[46:47], v[46:47], v[50:51] op_sel_hi:[1,0]
	v_pk_mul_f32 v[48:49], v[48:49], v[50:51] op_sel_hi:[1,0]
	v_pk_mul_f32 v[42:43], v[42:43], v[50:51] op_sel_hi:[1,0]
	v_pk_mul_f32 v[44:45], v[44:45], v[50:51] op_sel_hi:[1,0]
	s_and_saveexec_b64 s[0:1], s[10:11]
	s_xor_b64 s[0:1], exec, s[0:1]
	s_andn2_saveexec_b64 s[36:37], s[0:1]
	s_cbranch_execz .LBB0_418
	v_mov_b32_e32 v51, v220
	v_cndmask_b32_e64 v50, v155, v158, s[6:7]
	v_lshlrev_b32_e32 v51, 2, v51
	v_xor_b32_e32 v51, 64, v51
	v_lshlrev_b32_e32 v53, 6, v50
	ds_bpermute_b32 v52, v51, v46
	global_load_dwordx2 v[174:175], v53, s[26:27]
	global_load_dwordx2 v[176:177], v53, s[26:27] offset:8
	global_load_dwordx2 v[178:179], v53, s[26:27] offset:16
	global_load_dwordx2 v[180:181], v53, s[26:27] offset:24
	global_load_dwordx2 v[182:183], v53, s[26:27] offset:32
	global_load_dwordx2 v[184:185], v53, s[26:27] offset:40
	global_load_dwordx2 v[208:209], v53, s[26:27] offset:48
	global_load_dwordx2 v[210:211], v53, s[26:27] offset:56
	v_cmp_gt_i32_e64 s[14:15], s95, v54
	s_waitcnt vmcnt(7) lgkmcnt(0)
	v_mul_f32_e32 v51, v175, v52
	v_cndmask_b32_e64 v51, v51, -v51, vcc
	v_fmac_f32_e32 v51, v46, v174
	v_mov_b32_e32 v50, v220
	v_cndmask_b32_e64 v46, v46, v51, s[14:15]
	v_lshlrev_b32_e32 v50, 2, v50
	v_xor_b32_e32 v50, 64, v50
	ds_bpermute_b32 v52, v50, v47
	s_waitcnt vmcnt(6) lgkmcnt(0)
	v_mul_f32_e32 v51, v177, v52
	v_cndmask_b32_e64 v51, v51, -v51, vcc
	v_fmac_f32_e32 v51, v47, v176
	v_mov_b32_e32 v50, v220
	v_cndmask_b32_e64 v47, v47, v51, s[14:15]
	v_lshlrev_b32_e32 v50, 2, v50
	v_xor_b32_e32 v50, 64, v50
	ds_bpermute_b32 v52, v50, v48
	s_waitcnt vmcnt(5) lgkmcnt(0)
	v_mul_f32_e32 v51, v179, v52
	v_cndmask_b32_e64 v51, v51, -v51, vcc
	v_fmac_f32_e32 v51, v48, v178
	v_mov_b32_e32 v50, v220
	v_cndmask_b32_e64 v48, v48, v51, s[14:15]
	v_lshlrev_b32_e32 v50, 2, v50
	v_xor_b32_e32 v50, 64, v50
	ds_bpermute_b32 v52, v50, v49
	s_waitcnt vmcnt(4) lgkmcnt(0)
	v_mul_f32_e32 v51, v181, v52
	v_cndmask_b32_e64 v51, v51, -v51, vcc
	v_fmac_f32_e32 v51, v49, v180
	v_mov_b32_e32 v50, v220
	v_cndmask_b32_e64 v49, v49, v51, s[14:15]
	v_lshlrev_b32_e32 v50, 2, v50
	v_xor_b32_e32 v50, 64, v50
	ds_bpermute_b32 v52, v50, v42
	s_waitcnt vmcnt(3) lgkmcnt(0)
	v_mul_f32_e32 v51, v183, v52
	v_cndmask_b32_e64 v51, v51, -v51, vcc
	v_fmac_f32_e32 v51, v42, v182
	v_mov_b32_e32 v50, v220
	v_cndmask_b32_e64 v42, v42, v51, s[14:15]
	v_lshlrev_b32_e32 v50, 2, v50
	v_xor_b32_e32 v50, 64, v50
	ds_bpermute_b32 v52, v50, v43
	s_waitcnt vmcnt(2) lgkmcnt(0)
	v_mul_f32_e32 v51, v185, v52
	v_cndmask_b32_e64 v51, v51, -v51, vcc
	v_fmac_f32_e32 v51, v43, v184
	v_mov_b32_e32 v50, v220
	v_cndmask_b32_e64 v43, v43, v51, s[14:15]
	v_lshlrev_b32_e32 v50, 2, v50
	v_xor_b32_e32 v50, 64, v50
	ds_bpermute_b32 v52, v50, v44
	s_waitcnt vmcnt(1) lgkmcnt(0)
	v_mul_f32_e32 v51, v209, v52
	v_cndmask_b32_e64 v51, v51, -v51, vcc
	v_fmac_f32_e32 v51, v44, v208
	v_mov_b32_e32 v50, v220
	v_cndmask_b32_e64 v44, v44, v51, s[14:15]
	v_lshlrev_b32_e32 v50, 2, v50
	v_xor_b32_e32 v50, 64, v50
	ds_bpermute_b32 v52, v50, v45
	s_waitcnt vmcnt(0) lgkmcnt(0)
	v_mul_f32_e32 v51, v211, v52
	v_cndmask_b32_e64 v51, v51, -v51, vcc
	v_fmac_f32_e32 v51, v45, v210
	v_cndmask_b32_e64 v45, v45, v51, s[14:15]

; __device__ __forceinline__ unsigned cvt_pk_bf16(float lo, float hi) { const f32x2_ v = {lo, hi}; return __builtin_bit_cast(unsigned, __builtin_convertvector(v, bf16x2_)); }
;     __device__ __forceinline__ void operator()(const f32x4 (&acc)[2][2][4][2], const Unit& u, int wr, int wc, int fr, int fq) const {
;     ...
;                     const int row = row0 + ai * 128 + m * 16;
;                     float v[8];
;                     if (cg0 < 384) {
;                         const float rs = RSTD[row * 2];
; #pragma unroll
;                         for (int n = 0; n < 2; ++n)
; #pragma unroll
;                             for (int j = 0; j < 4; ++j) v[4 * n + j] = acc[ai][bj][m][n][j] * rs;
;     ...
;                         *(u32x4*)(MQ + (size_t)row * 384 + cg0 + 8 * fq) = w;
;                     } else {
;                         const float rs = RSTD[row * 2 + 1];
; #pragma unroll
;                         for (int n = 0; n < 2; ++n)
; #pragma unroll
;                             for (int j = 0; j < 4; ++j) v[4 * n + j] = acc[ai][bj][m][n][j] * rs;
;                         const int cp = cg0 - 384, hd = cp >> 7, d0 = cp & 127;
;                         u32x4 w; w.x = cvt_pk_bf16(v[0], v[1]); w.y = cvt_pk_bf16(v[2], v[3]); w.z = cvt_pk_bf16(v[4], v[5]); w.w = cvt_pk_bf16(v[6], v[7]);
;                         if (d0 < 64) *(u32x4*)(MK + (size_t)row * 384 + hd * 96 + d0 + 8 * fq) = w;
;                         else *(u32x4*)(MV + (size_t)row * 256 + hd * 64 + (d0 - 64) + 8 * fq) = w;
.LBB0_419:
	s_or_b64 exec, exec, s[2:3]
	v_mov_b32_e32 v63, v0
	v_lshl_add_u64 v[42:43], v[56:57], 0, v[62:63]
	global_store_dwordx4 v[42:43], v[50:53], off
	v_or_b32_e32 v46, 48, v144
	v_lshlrev_b32_e32 v42, 1, v46
	v_ashrrev_i32_e32 v43, 31, v42
	v_lshl_add_u64 v[50:51], v[42:43], 2, s[24:25]
	s_and_saveexec_b64 s[0:1], s[12:13]
	s_xor_b64 s[0:1], exec, s[0:1]
	s_cbranch_execz .LBB0_425
	v_mov_b32_e32 v42, v229
	v_ashrrev_i32_e32 v47, 31, v46
	s_and_saveexec_b64 s[2:3], s[8:9]
	s_xor_b64 s[2:3], exec, s[2:3]
	s_cbranch_execz .LBB0_422
	v_lshlrev_b64 v[44:45], 9, v[46:47]
	v_lshl_add_u64 v[44:45], s[22:23], 0, v[44:45]
	s_lshl_b32 s14, s63, 1
	s_mov_b32 s15, s89
	v_lshl_add_u64 v[44:45], v[44:45], 0, s[14:15]
	v_lshlrev_b32_e32 v46, 1, v154
	v_mov_b32_e32 v47, v0
	s_movk_i32 s14, 0xff80
	v_lshl_add_u64 v[44:45], v[44:45], 0, v[46:47]
	s_mov_b32 s15, -1
	v_lshl_add_u64 v[48:49], v[44:45], 0, s[14:15]
.LBB0_422:
	s_andn2_saveexec_b64 s[2:3], s[2:3]
	v_mov_b64_e32 v[44:45], s[20:21]
	s_movk_i32 s14, 0x300
	v_mad_i64_i32 v[44:45], s[14:15], v46, s14, v[44:45]
	v_lshl_add_u64 v[44:45], s[88:89], 1, v[44:45]
	v_lshlrev_b32_e32 v46, 1, v154
	v_mov_b32_e32 v47, v0
	v_lshl_add_u64 v[48:49], v[44:45], 0, v[46:47]
	s_or_b64 exec, exec, s[2:3]
	v_pk_mul_f32 v[38:39], v[38:39], v[42:43] op_sel_hi:[1,0]
	v_pk_mul_f32 v[40:41], v[40:41], v[42:43] op_sel_hi:[1,0]
	v_pk_mul_f32 v[34:35], v[34:35], v[42:43] op_sel_hi:[1,0]
	v_pk_mul_f32 v[36:37], v[36:37], v[42:43] op_sel_hi:[1,0]
	v_cvt_pk_bf16_f32 v42, v38, v39
	v_cvt_pk_bf16_f32 v43, v40, v41
	v_cvt_pk_bf16_f32 v44, v34, v35
	v_cvt_pk_bf16_f32 v45, v36, v37
.LBB0_425:
	s_andn2_saveexec_b64 s[2:3], s[0:1]
	s_cbranch_execz .LBB0_431
	v_mov_b32_e32 v42, v228
	v_pk_mul_f32 v[38:39], v[38:39], v[42:43] op_sel_hi:[1,0]
	v_pk_mul_f32 v[40:41], v[40:41], v[42:43] op_sel_hi:[1,0]
	v_pk_mul_f32 v[34:35], v[34:35], v[42:43] op_sel_hi:[1,0]
	v_pk_mul_f32 v[36:37], v[36:37], v[42:43] op_sel_hi:[1,0]
	s_and_saveexec_b64 s[0:1], s[10:11]
	s_xor_b64 s[0:1], exec, s[0:1]
	s_andn2_saveexec_b64 s[36:37], s[0:1]
	s_cbranch_execz .LBB0_430
	v_mov_b32_e32 v43, v220
	v_cndmask_b32_e64 v42, v153, v158, s[6:7]
	v_lshlrev_b32_e32 v43, 2, v43
	v_xor_b32_e32 v43, 64, v43
	v_lshlrev_b32_e32 v45, 6, v42
	ds_bpermute_b32 v44, v43, v38
	global_load_dwordx2 v[174:175], v45, s[26:27]
	global_load_dwordx2 v[176:177], v45, s[26:27] offset:8
	global_load_dwordx2 v[178:179], v45, s[26:27] offset:16
	global_load_dwordx2 v[180:181], v45, s[26:27] offset:24
	global_load_dwordx2 v[182:183], v45, s[26:27] offset:32
	global_load_dwordx2 v[184:185], v45, s[26:27] offset:40
	global_load_dwordx2 v[208:209], v45, s[26:27] offset:48
	global_load_dwordx2 v[210:211], v45, s[26:27] offset:56
	v_cmp_gt_i32_e64 s[14:15], s95, v46
	s_waitcnt vmcnt(7) lgkmcnt(0)
	v_mul_f32_e32 v43, v175, v44
	v_cndmask_b32_e64 v43, v43, -v43, vcc
	v_fmac_f32_e32 v43, v38, v174
	v_mov_b32_e32 v42, v220
	v_cndmask_b32_e64 v38, v38, v43, s[14:15]
	v_lshlrev_b32_e32 v42, 2, v42
	v_xor_b32_e32 v42, 64, v42
	ds_bpermute_b32 v44, v42, v39
	s_waitcnt vmcnt(6) lgkmcnt(0)
	v_mul_f32_e32 v43, v177, v44
	v_cndmask_b32_e64 v43, v43, -v43, vcc
	v_fmac_f32_e32 v43, v39, v176
	v_mov_b32_e32 v42, v220
	v_cndmask_b32_e64 v39, v39, v43, s[14:15]
	v_lshlrev_b32_e32 v42, 2, v42
	v_xor_b32_e32 v42, 64, v42
	ds_bpermute_b32 v44, v42, v40
	s_waitcnt vmcnt(5) lgkmcnt(0)
	v_mul_f32_e32 v43, v179, v44
	v_cndmask_b32_e64 v43, v43, -v43, vcc
	v_fmac_f32_e32 v43, v40, v178
	v_mov_b32_e32 v42, v220
	v_cndmask_b32_e64 v40, v40, v43, s[14:15]
	v_lshlrev_b32_e32 v42, 2, v42
	v_xor_b32_e32 v42, 64, v42
	ds_bpermute_b32 v44, v42, v41
	s_waitcnt vmcnt(4) lgkmcnt(0)
	v_mul_f32_e32 v43, v181, v44
	v_cndmask_b32_e64 v43, v43, -v43, vcc
	v_fmac_f32_e32 v43, v41, v180
	v_mov_b32_e32 v42, v220
	v_cndmask_b32_e64 v41, v41, v43, s[14:15]
	v_lshlrev_b32_e32 v42, 2, v42
	v_xor_b32_e32 v42, 64, v42
	ds_bpermute_b32 v44, v42, v34
	s_waitcnt vmcnt(3) lgkmcnt(0)
	v_mul_f32_e32 v43, v183, v44
	v_cndmask_b32_e64 v43, v43, -v43, vcc
	v_fmac_f32_e32 v43, v34, v182
	v_mov_b32_e32 v42, v220
	v_cndmask_b32_e64 v34, v34, v43, s[14:15]
	v_lshlrev_b32_e32 v42, 2, v42
	v_xor_b32_e32 v42, 64, v42
	ds_bpermute_b32 v44, v42, v35
	s_waitcnt vmcnt(2) lgkmcnt(0)
	v_mul_f32_e32 v43, v185, v44
	v_cndmask_b32_e64 v43, v43, -v43, vcc
	v_fmac_f32_e32 v43, v35, v184
	v_mov_b32_e32 v42, v220
	v_cndmask_b32_e64 v35, v35, v43, s[14:15]
	v_lshlrev_b32_e32 v42, 2, v42
	v_xor_b32_e32 v42, 64, v42
	ds_bpermute_b32 v44, v42, v36
	s_waitcnt vmcnt(1) lgkmcnt(0)
	v_mul_f32_e32 v43, v209, v44
	v_cndmask_b32_e64 v43, v43, -v43, vcc
	v_fmac_f32_e32 v43, v36, v208
	v_mov_b32_e32 v42, v220
	v_cndmask_b32_e64 v36, v36, v43, s[14:15]
	v_lshlrev_b32_e32 v42, 2, v42
	v_xor_b32_e32 v42, 64, v42
	ds_bpermute_b32 v44, v42, v37
	s_waitcnt vmcnt(0) lgkmcnt(0)
	v_mul_f32_e32 v43, v211, v44
	v_cndmask_b32_e64 v43, v43, -v43, vcc
	v_fmac_f32_e32 v43, v37, v210
	v_cndmask_b32_e64 v37, v37, v43, s[14:15]

; __device__ __forceinline__ unsigned cvt_pk_bf16(float lo, float hi) { const f32x2_ v = {lo, hi}; return __builtin_bit_cast(unsigned, __builtin_convertvector(v, bf16x2_)); }
;     __device__ __forceinline__ void operator()(const f32x4 (&acc)[2][2][4][2], const Unit& u, int wr, int wc, int fr, int fq) const {
;     ...
;                     const int row = row0 + ai * 128 + m * 16;
;                     float v[8];
;                     if (cg0 < 384) {
;                         const float rs = RSTD[row * 2];
; #pragma unroll
;                         for (int n = 0; n < 2; ++n)
; #pragma unroll
;                             for (int j = 0; j < 4; ++j) v[4 * n + j] = acc[ai][bj][m][n][j] * rs;
;     ...
;                         *(u32x4*)(MQ + (size_t)row * 384 + cg0 + 8 * fq) = w;
;                     } else {
;                         const float rs = RSTD[row * 2 + 1];
; #pragma unroll
;                         for (int n = 0; n < 2; ++n)
; #pragma unroll
;                             for (int j = 0; j < 4; ++j) v[4 * n + j] = acc[ai][bj][m][n][j] * rs;
;                         const int cp = cg0 - 384, hd = cp >> 7, d0 = cp & 127;
;                         u32x4 w; w.x = cvt_pk_bf16(v[0], v[1]); w.y = cvt_pk_bf16(v[2], v[3]); w.z = cvt_pk_bf16(v[4], v[5]); w.w = cvt_pk_bf16(v[6], v[7]);
;                         if (d0 < 64) *(u32x4*)(MK + (size_t)row * 384 + hd * 96 + d0 + 8 * fq) = w;
;                         else *(u32x4*)(MV + (size_t)row * 256 + hd * 64 + (d0 - 64) + 8 * fq) = w;
.LBB0_431:
	s_or_b64 exec, exec, s[2:3]
	v_mov_b32_e32 v63, v0
	v_lshl_add_u64 v[34:35], v[48:49], 0, v[62:63]
	v_add_u32_e32 v38, 0x80, v144
	global_store_dwordx4 v[34:35], v[42:45], off
	v_lshlrev_b32_e32 v34, 1, v38
	v_ashrrev_i32_e32 v35, 31, v34
	v_lshl_add_u64 v[42:43], v[34:35], 2, s[24:25]
	s_and_saveexec_b64 s[0:1], s[12:13]
	s_xor_b64 s[0:1], exec, s[0:1]
	s_cbranch_execz .LBB0_437
	v_mov_b32_e32 v34, v231
	v_ashrrev_i32_e32 v39, 31, v38
	s_and_saveexec_b64 s[2:3], s[8:9]
	s_xor_b64 s[2:3], exec, s[2:3]
	s_cbranch_execz .LBB0_434
	v_lshlrev_b64 v[36:37], 9, v[38:39]
	v_lshl_add_u64 v[36:37], s[22:23], 0, v[36:37]
	s_lshl_b32 s14, s63, 1
	s_mov_b32 s15, s89
	v_lshl_add_u64 v[36:37], v[36:37], 0, s[14:15]
	v_lshlrev_b32_e32 v40, 1, v154
	v_mov_b32_e32 v41, v0
	s_movk_i32 s14, 0xff80
	v_lshl_add_u64 v[36:37], v[36:37], 0, v[40:41]
	s_mov_b32 s15, -1
	v_lshl_add_u64 v[40:41], v[36:37], 0, s[14:15]
.LBB0_434:
	s_andn2_saveexec_b64 s[2:3], s[2:3]
	v_mov_b64_e32 v[36:37], s[20:21]
	s_movk_i32 s14, 0x300
	v_mad_i64_i32 v[36:37], s[14:15], v38, s14, v[36:37]
	v_lshl_add_u64 v[36:37], s[88:89], 1, v[36:37]
	v_lshlrev_b32_e32 v40, 1, v154
	v_mov_b32_e32 v41, v0
	v_lshl_add_u64 v[40:41], v[36:37], 0, v[40:41]
	s_or_b64 exec, exec, s[2:3]
	v_pk_mul_f32 v[30:31], v[30:31], v[34:35] op_sel_hi:[1,0]
	v_pk_mul_f32 v[32:33], v[32:33], v[34:35] op_sel_hi:[1,0]
	v_pk_mul_f32 v[26:27], v[26:27], v[34:35] op_sel_hi:[1,0]
	v_pk_mul_f32 v[28:29], v[28:29], v[34:35] op_sel_hi:[1,0]
	v_cvt_pk_bf16_f32 v34, v30, v31
	v_cvt_pk_bf16_f32 v35, v32, v33
	v_cvt_pk_bf16_f32 v36, v26, v27
	v_cvt_pk_bf16_f32 v37, v28, v29
.LBB0_437:
	s_or_saveexec_b64 s[2:3], s[0:1]
	v_bfe_u32 v39, v38, 6, 7
	s_xor_b64 exec, exec, s[2:3]
	s_cbranch_execz .LBB0_443
	v_mov_b32_e32 v34, v230
	v_pk_mul_f32 v[30:31], v[30:31], v[34:35] op_sel_hi:[1,0]
	v_pk_mul_f32 v[32:33], v[32:33], v[34:35] op_sel_hi:[1,0]
	v_pk_mul_f32 v[26:27], v[26:27], v[34:35] op_sel_hi:[1,0]
	v_pk_mul_f32 v[28:29], v[28:29], v[34:35] op_sel_hi:[1,0]
	s_and_saveexec_b64 s[0:1], s[10:11]
	s_xor_b64 s[0:1], exec, s[0:1]
	s_andn2_saveexec_b64 s[36:37], s[0:1]
	s_cbranch_execz .LBB0_442
	v_mov_b32_e32 v35, v220
	v_cndmask_b32_e64 v34, v157, v39, s[6:7]
	v_lshlrev_b32_e32 v35, 2, v35
	v_xor_b32_e32 v35, 64, v35
	v_lshlrev_b32_e32 v37, 6, v34
	ds_bpermute_b32 v36, v35, v30
	global_load_dwordx2 v[174:175], v37, s[26:27]
	global_load_dwordx2 v[176:177], v37, s[26:27] offset:8
	global_load_dwordx2 v[178:179], v37, s[26:27] offset:16
	global_load_dwordx2 v[180:181], v37, s[26:27] offset:24
	global_load_dwordx2 v[182:183], v37, s[26:27] offset:32
	global_load_dwordx2 v[184:185], v37, s[26:27] offset:40
	global_load_dwordx2 v[208:209], v37, s[26:27] offset:48
	global_load_dwordx2 v[210:211], v37, s[26:27] offset:56
	s_movk_i32 s0, 0x7f80
	v_cmp_gt_i32_e64 s[14:15], s0, v144
	s_waitcnt vmcnt(7) lgkmcnt(0)
	v_mul_f32_e32 v35, v175, v36
	v_cndmask_b32_e64 v35, v35, -v35, vcc
	v_fmac_f32_e32 v35, v30, v174
	v_mov_b32_e32 v34, v220
	v_cndmask_b32_e64 v30, v30, v35, s[14:15]
	v_lshlrev_b32_e32 v34, 2, v34
	v_xor_b32_e32 v34, 64, v34
	ds_bpermute_b32 v36, v34, v31
	s_waitcnt vmcnt(6) lgkmcnt(0)
	v_mul_f32_e32 v35, v177, v36
	v_cndmask_b32_e64 v35, v35, -v35, vcc
	v_fmac_f32_e32 v35, v31, v176
	v_mov_b32_e32 v34, v220
	v_cndmask_b32_e64 v31, v31, v35, s[14:15]
	v_lshlrev_b32_e32 v34, 2, v34
	v_xor_b32_e32 v34, 64, v34
	ds_bpermute_b32 v36, v34, v32
	s_waitcnt vmcnt(5) lgkmcnt(0)
	v_mul_f32_e32 v35, v179, v36
	v_cndmask_b32_e64 v35, v35, -v35, vcc
	v_fmac_f32_e32 v35, v32, v178
	v_mov_b32_e32 v34, v220
	v_cndmask_b32_e64 v32, v32, v35, s[14:15]
	v_lshlrev_b32_e32 v34, 2, v34
	v_xor_b32_e32 v34, 64, v34
	ds_bpermute_b32 v36, v34, v33
	s_waitcnt vmcnt(4) lgkmcnt(0)
	v_mul_f32_e32 v35, v181, v36
	v_cndmask_b32_e64 v35, v35, -v35, vcc
	v_fmac_f32_e32 v35, v33, v180
	v_mov_b32_e32 v34, v220
	v_cndmask_b32_e64 v33, v33, v35, s[14:15]
	v_lshlrev_b32_e32 v34, 2, v34
	v_xor_b32_e32 v34, 64, v34
	ds_bpermute_b32 v36, v34, v26
	s_waitcnt vmcnt(3) lgkmcnt(0)
	v_mul_f32_e32 v35, v183, v36
	v_cndmask_b32_e64 v35, v35, -v35, vcc
	v_fmac_f32_e32 v35, v26, v182
	v_mov_b32_e32 v34, v220
	v_cndmask_b32_e64 v26, v26, v35, s[14:15]
	v_lshlrev_b32_e32 v34, 2, v34
	v_xor_b32_e32 v34, 64, v34
	ds_bpermute_b32 v36, v34, v27
	s_waitcnt vmcnt(2) lgkmcnt(0)
	v_mul_f32_e32 v35, v185, v36
	v_cndmask_b32_e64 v35, v35, -v35, vcc
	v_fmac_f32_e32 v35, v27, v184
	v_mov_b32_e32 v34, v220
	v_cndmask_b32_e64 v27, v27, v35, s[14:15]
	v_lshlrev_b32_e32 v34, 2, v34
	v_xor_b32_e32 v34, 64, v34
	ds_bpermute_b32 v36, v34, v28
	s_waitcnt vmcnt(1) lgkmcnt(0)
	v_mul_f32_e32 v35, v209, v36
	v_cndmask_b32_e64 v35, v35, -v35, vcc
	v_fmac_f32_e32 v35, v28, v208
	v_mov_b32_e32 v34, v220
	v_cndmask_b32_e64 v28, v28, v35, s[14:15]
	v_lshlrev_b32_e32 v34, 2, v34
	v_xor_b32_e32 v34, 64, v34
	ds_bpermute_b32 v36, v34, v29
	s_waitcnt vmcnt(0) lgkmcnt(0)
	v_mul_f32_e32 v35, v211, v36
	v_cndmask_b32_e64 v35, v35, -v35, vcc
	v_fmac_f32_e32 v35, v29, v210
	v_cndmask_b32_e64 v29, v29, v35, s[14:15]

; __device__ __forceinline__ unsigned cvt_pk_bf16(float lo, float hi) { const f32x2_ v = {lo, hi}; return __builtin_bit_cast(unsigned, __builtin_convertvector(v, bf16x2_)); }
;     __device__ __forceinline__ void operator()(const f32x4 (&acc)[2][2][4][2], const Unit& u, int wr, int wc, int fr, int fq) const {
;     ...
;                     const int row = row0 + ai * 128 + m * 16;
;                     float v[8];
;                     if (cg0 < 384) {
;                         const float rs = RSTD[row * 2];
; #pragma unroll
;                         for (int n = 0; n < 2; ++n)
; #pragma unroll
;                             for (int j = 0; j < 4; ++j) v[4 * n + j] = acc[ai][bj][m][n][j] * rs;
;     ...
;                         *(u32x4*)(MQ + (size_t)row * 384 + cg0 + 8 * fq) = w;
;                     } else {
;                         const float rs = RSTD[row * 2 + 1];
; #pragma unroll
;                         for (int n = 0; n < 2; ++n)
; #pragma unroll
;                             for (int j = 0; j < 4; ++j) v[4 * n + j] = acc[ai][bj][m][n][j] * rs;
;                         const int cp = cg0 - 384, hd = cp >> 7, d0 = cp & 127;
;                         u32x4 w; w.x = cvt_pk_bf16(v[0], v[1]); w.y = cvt_pk_bf16(v[2], v[3]); w.z = cvt_pk_bf16(v[4], v[5]); w.w = cvt_pk_bf16(v[6], v[7]);
;                         if (d0 < 64) *(u32x4*)(MK + (size_t)row * 384 + hd * 96 + d0 + 8 * fq) = w;
;                         else *(u32x4*)(MV + (size_t)row * 256 + hd * 64 + (d0 - 64) + 8 * fq) = w;
.LBB0_443:
	s_or_b64 exec, exec, s[2:3]
	v_mov_b32_e32 v63, v0
	v_lshl_add_u64 v[26:27], v[40:41], 0, v[62:63]
	global_store_dwordx4 v[26:27], v[34:37], off
	v_add_u32_e32 v30, 0x90, v144
	v_lshlrev_b32_e32 v26, 1, v30
	v_ashrrev_i32_e32 v27, 31, v26
	v_lshl_add_u64 v[34:35], v[26:27], 2, s[24:25]
	s_and_saveexec_b64 s[0:1], s[12:13]
	s_xor_b64 s[0:1], exec, s[0:1]
	s_cbranch_execz .LBB0_449
	v_mov_b32_e32 v26, v233
	v_ashrrev_i32_e32 v31, 31, v30
	s_and_saveexec_b64 s[2:3], s[8:9]
	s_xor_b64 s[2:3], exec, s[2:3]
	s_cbranch_execz .LBB0_446
	v_lshlrev_b64 v[28:29], 9, v[30:31]
	v_lshl_add_u64 v[28:29], s[22:23], 0, v[28:29]
	s_lshl_b32 s14, s63, 1
	s_mov_b32 s15, s89
	v_lshl_add_u64 v[28:29], v[28:29], 0, s[14:15]
	v_lshlrev_b32_e32 v30, 1, v154
	v_mov_b32_e32 v31, v0
	s_movk_i32 s14, 0xff80
	v_lshl_add_u64 v[28:29], v[28:29], 0, v[30:31]
	s_mov_b32 s15, -1
	v_lshl_add_u64 v[32:33], v[28:29], 0, s[14:15]
.LBB0_446:
	s_andn2_saveexec_b64 s[2:3], s[2:3]
	v_mov_b64_e32 v[28:29], s[20:21]
	s_movk_i32 s14, 0x300
	v_mad_i64_i32 v[28:29], s[14:15], v30, s14, v[28:29]
	v_lshl_add_u64 v[28:29], s[88:89], 1, v[28:29]
	v_lshlrev_b32_e32 v30, 1, v154
	v_mov_b32_e32 v31, v0
	v_lshl_add_u64 v[32:33], v[28:29], 0, v[30:31]
	s_or_b64 exec, exec, s[2:3]
	v_pk_mul_f32 v[22:23], v[22:23], v[26:27] op_sel_hi:[1,0]
	v_pk_mul_f32 v[24:25], v[24:25], v[26:27] op_sel_hi:[1,0]
	v_pk_mul_f32 v[18:19], v[18:19], v[26:27] op_sel_hi:[1,0]
	v_pk_mul_f32 v[20:21], v[20:21], v[26:27] op_sel_hi:[1,0]
	v_cvt_pk_bf16_f32 v26, v22, v23
	v_cvt_pk_bf16_f32 v27, v24, v25
	v_cvt_pk_bf16_f32 v28, v18, v19
	v_cvt_pk_bf16_f32 v29, v20, v21
.LBB0_449:
	s_andn2_saveexec_b64 s[2:3], s[0:1]
	s_cbranch_execz .LBB0_455
	v_mov_b32_e32 v26, v232
	v_pk_mul_f32 v[22:23], v[22:23], v[26:27] op_sel_hi:[1,0]
	v_pk_mul_f32 v[24:25], v[24:25], v[26:27] op_sel_hi:[1,0]
	v_pk_mul_f32 v[18:19], v[18:19], v[26:27] op_sel_hi:[1,0]
	v_pk_mul_f32 v[20:21], v[20:21], v[26:27] op_sel_hi:[1,0]
	s_and_saveexec_b64 s[0:1], s[10:11]
	s_xor_b64 s[0:1], exec, s[0:1]
	s_andn2_saveexec_b64 s[36:37], s[0:1]
	s_cbranch_execz .LBB0_454
	v_mov_b32_e32 v27, v220
	v_cndmask_b32_e64 v26, v156, v39, s[6:7]
	v_lshlrev_b32_e32 v27, 2, v27
	v_xor_b32_e32 v27, 64, v27
	v_lshlrev_b32_e32 v29, 6, v26
	ds_bpermute_b32 v28, v27, v22
	global_load_dwordx2 v[174:175], v29, s[26:27]
	global_load_dwordx2 v[176:177], v29, s[26:27] offset:8
	global_load_dwordx2 v[178:179], v29, s[26:27] offset:16
	global_load_dwordx2 v[180:181], v29, s[26:27] offset:24
	global_load_dwordx2 v[182:183], v29, s[26:27] offset:32
	global_load_dwordx2 v[184:185], v29, s[26:27] offset:40
	global_load_dwordx2 v[208:209], v29, s[26:27] offset:48
	global_load_dwordx2 v[210:211], v29, s[26:27] offset:56
	s_movk_i32 s0, 0x7f70
	v_cmp_gt_i32_e64 s[14:15], s0, v144
	s_waitcnt vmcnt(7) lgkmcnt(0)
	v_mul_f32_e32 v27, v175, v28
	v_cndmask_b32_e64 v27, v27, -v27, vcc
	v_fmac_f32_e32 v27, v22, v174
	v_mov_b32_e32 v26, v220
	v_cndmask_b32_e64 v22, v22, v27, s[14:15]
	v_lshlrev_b32_e32 v26, 2, v26
	v_xor_b32_e32 v26, 64, v26
	ds_bpermute_b32 v28, v26, v23
	s_waitcnt vmcnt(6) lgkmcnt(0)
	v_mul_f32_e32 v27, v177, v28
	v_cndmask_b32_e64 v27, v27, -v27, vcc
	v_fmac_f32_e32 v27, v23, v176
	v_mov_b32_e32 v26, v220
	v_cndmask_b32_e64 v23, v23, v27, s[14:15]
	v_lshlrev_b32_e32 v26, 2, v26
	v_xor_b32_e32 v26, 64, v26
	ds_bpermute_b32 v28, v26, v24
	s_waitcnt vmcnt(5) lgkmcnt(0)
	v_mul_f32_e32 v27, v179, v28
	v_cndmask_b32_e64 v27, v27, -v27, vcc
	v_fmac_f32_e32 v27, v24, v178
	v_mov_b32_e32 v26, v220
	v_cndmask_b32_e64 v24, v24, v27, s[14:15]
	v_lshlrev_b32_e32 v26, 2, v26
	v_xor_b32_e32 v26, 64, v26
	ds_bpermute_b32 v28, v26, v25
	s_waitcnt vmcnt(4) lgkmcnt(0)
	v_mul_f32_e32 v27, v181, v28
	v_cndmask_b32_e64 v27, v27, -v27, vcc
	v_fmac_f32_e32 v27, v25, v180
	v_mov_b32_e32 v26, v220
	v_cndmask_b32_e64 v25, v25, v27, s[14:15]
	v_lshlrev_b32_e32 v26, 2, v26
	v_xor_b32_e32 v26, 64, v26
	ds_bpermute_b32 v28, v26, v18
	s_waitcnt vmcnt(3) lgkmcnt(0)
	v_mul_f32_e32 v27, v183, v28
	v_cndmask_b32_e64 v27, v27, -v27, vcc
	v_fmac_f32_e32 v27, v18, v182
	v_mov_b32_e32 v26, v220
	v_cndmask_b32_e64 v18, v18, v27, s[14:15]
	v_lshlrev_b32_e32 v26, 2, v26
	v_xor_b32_e32 v26, 64, v26
	ds_bpermute_b32 v28, v26, v19
	s_waitcnt vmcnt(2) lgkmcnt(0)
	v_mul_f32_e32 v27, v185, v28
	v_cndmask_b32_e64 v27, v27, -v27, vcc
	v_fmac_f32_e32 v27, v19, v184
	v_mov_b32_e32 v26, v220
	v_cndmask_b32_e64 v19, v19, v27, s[14:15]
	v_lshlrev_b32_e32 v26, 2, v26
	v_xor_b32_e32 v26, 64, v26
	ds_bpermute_b32 v28, v26, v20
	s_waitcnt vmcnt(1) lgkmcnt(0)
	v_mul_f32_e32 v27, v209, v28
	v_cndmask_b32_e64 v27, v27, -v27, vcc
	v_fmac_f32_e32 v27, v20, v208
	v_mov_b32_e32 v26, v220
	v_cndmask_b32_e64 v20, v20, v27, s[14:15]
	v_lshlrev_b32_e32 v26, 2, v26
	v_xor_b32_e32 v26, 64, v26
	ds_bpermute_b32 v28, v26, v21
	s_waitcnt vmcnt(0) lgkmcnt(0)
	v_mul_f32_e32 v27, v211, v28
	v_cndmask_b32_e64 v27, v27, -v27, vcc
	v_fmac_f32_e32 v27, v21, v210
	v_cndmask_b32_e64 v21, v21, v27, s[14:15]

; __device__ __forceinline__ unsigned cvt_pk_bf16(float lo, float hi) { const f32x2_ v = {lo, hi}; return __builtin_bit_cast(unsigned, __builtin_convertvector(v, bf16x2_)); }
;     __device__ __forceinline__ void operator()(const f32x4 (&acc)[2][2][4][2], const Unit& u, int wr, int wc, int fr, int fq) const {
;     ...
;                     const int row = row0 + ai * 128 + m * 16;
;                     float v[8];
;                     if (cg0 < 384) {
;                         const float rs = RSTD[row * 2];
; #pragma unroll
;                         for (int n = 0; n < 2; ++n)
; #pragma unroll
;                             for (int j = 0; j < 4; ++j) v[4 * n + j] = acc[ai][bj][m][n][j] * rs;
;     ...
;                         *(u32x4*)(MQ + (size_t)row * 384 + cg0 + 8 * fq) = w;
;                     } else {
;                         const float rs = RSTD[row * 2 + 1];
; #pragma unroll
;                         for (int n = 0; n < 2; ++n)
; #pragma unroll
;                             for (int j = 0; j < 4; ++j) v[4 * n + j] = acc[ai][bj][m][n][j] * rs;
;                         const int cp = cg0 - 384, hd = cp >> 7, d0 = cp & 127;
;                         u32x4 w; w.x = cvt_pk_bf16(v[0], v[1]); w.y = cvt_pk_bf16(v[2], v[3]); w.z = cvt_pk_bf16(v[4], v[5]); w.w = cvt_pk_bf16(v[6], v[7]);
;                         if (d0 < 64) *(u32x4*)(MK + (size_t)row * 384 + hd * 96 + d0 + 8 * fq) = w;
;                         else *(u32x4*)(MV + (size_t)row * 256 + hd * 64 + (d0 - 64) + 8 * fq) = w;
.LBB0_455:
	s_or_b64 exec, exec, s[2:3]
	v_mov_b32_e32 v63, v0
	v_lshl_add_u64 v[18:19], v[32:33], 0, v[62:63]
	global_store_dwordx4 v[18:19], v[26:29], off
	v_add_u32_e32 v22, 0xa0, v144
	v_lshlrev_b32_e32 v18, 1, v22
	v_ashrrev_i32_e32 v19, 31, v18
	v_lshl_add_u64 v[26:27], v[18:19], 2, s[24:25]
	s_and_saveexec_b64 s[0:1], s[12:13]
	s_xor_b64 s[0:1], exec, s[0:1]
	s_cbranch_execz .LBB0_461
	v_mov_b32_e32 v18, v235
	v_ashrrev_i32_e32 v23, 31, v22
	s_and_saveexec_b64 s[2:3], s[8:9]
	s_xor_b64 s[2:3], exec, s[2:3]
	s_cbranch_execz .LBB0_458
	v_lshlrev_b64 v[20:21], 9, v[22:23]
	v_lshl_add_u64 v[20:21], s[22:23], 0, v[20:21]
	s_lshl_b32 s14, s63, 1
	s_mov_b32 s15, s89
	v_lshl_add_u64 v[20:21], v[20:21], 0, s[14:15]
	v_lshlrev_b32_e32 v22, 1, v154
	v_mov_b32_e32 v23, v0
	s_movk_i32 s14, 0xff80
	v_lshl_add_u64 v[20:21], v[20:21], 0, v[22:23]
	s_mov_b32 s15, -1
	v_lshl_add_u64 v[24:25], v[20:21], 0, s[14:15]
.LBB0_458:
	s_andn2_saveexec_b64 s[2:3], s[2:3]
	v_mov_b64_e32 v[20:21], s[20:21]
	s_movk_i32 s14, 0x300
	v_mad_i64_i32 v[20:21], s[14:15], v22, s14, v[20:21]
	v_lshl_add_u64 v[20:21], s[88:89], 1, v[20:21]
	v_lshlrev_b32_e32 v22, 1, v154
	v_mov_b32_e32 v23, v0
	v_lshl_add_u64 v[24:25], v[20:21], 0, v[22:23]
	s_or_b64 exec, exec, s[2:3]
	v_pk_mul_f32 v[14:15], v[14:15], v[18:19] op_sel_hi:[1,0]
	v_pk_mul_f32 v[16:17], v[16:17], v[18:19] op_sel_hi:[1,0]
	v_pk_mul_f32 v[10:11], v[10:11], v[18:19] op_sel_hi:[1,0]
	v_pk_mul_f32 v[12:13], v[12:13], v[18:19] op_sel_hi:[1,0]
	v_cvt_pk_bf16_f32 v18, v14, v15
	v_cvt_pk_bf16_f32 v19, v16, v17
	v_cvt_pk_bf16_f32 v20, v10, v11
	v_cvt_pk_bf16_f32 v21, v12, v13
.LBB0_461:
	s_andn2_saveexec_b64 s[2:3], s[0:1]
	s_cbranch_execz .LBB0_467
	v_mov_b32_e32 v18, v234
	v_pk_mul_f32 v[14:15], v[14:15], v[18:19] op_sel_hi:[1,0]
	v_pk_mul_f32 v[16:17], v[16:17], v[18:19] op_sel_hi:[1,0]
	v_pk_mul_f32 v[10:11], v[10:11], v[18:19] op_sel_hi:[1,0]
	v_pk_mul_f32 v[12:13], v[12:13], v[18:19] op_sel_hi:[1,0]
	s_and_saveexec_b64 s[0:1], s[10:11]
	s_xor_b64 s[0:1], exec, s[0:1]
	s_andn2_saveexec_b64 s[36:37], s[0:1]
	s_cbranch_execz .LBB0_466
	v_mov_b32_e32 v19, v220
	v_cndmask_b32_e64 v18, v155, v39, s[6:7]
	v_lshlrev_b32_e32 v19, 2, v19
	v_xor_b32_e32 v19, 64, v19
	v_lshlrev_b32_e32 v21, 6, v18
	ds_bpermute_b32 v20, v19, v14
	global_load_dwordx2 v[174:175], v21, s[26:27]
	global_load_dwordx2 v[176:177], v21, s[26:27] offset:8
	global_load_dwordx2 v[178:179], v21, s[26:27] offset:16
	global_load_dwordx2 v[180:181], v21, s[26:27] offset:24
	global_load_dwordx2 v[182:183], v21, s[26:27] offset:32
	global_load_dwordx2 v[184:185], v21, s[26:27] offset:40
	global_load_dwordx2 v[208:209], v21, s[26:27] offset:48
	global_load_dwordx2 v[210:211], v21, s[26:27] offset:56
	s_movk_i32 s0, 0x7f60
	v_cmp_gt_i32_e64 s[14:15], s0, v144
	s_waitcnt vmcnt(7) lgkmcnt(0)
	v_mul_f32_e32 v19, v175, v20
	v_cndmask_b32_e64 v19, v19, -v19, vcc
	v_fmac_f32_e32 v19, v14, v174
	v_mov_b32_e32 v18, v220
	v_cndmask_b32_e64 v14, v14, v19, s[14:15]
	v_lshlrev_b32_e32 v18, 2, v18
	v_xor_b32_e32 v18, 64, v18
	ds_bpermute_b32 v20, v18, v15
	s_waitcnt vmcnt(6) lgkmcnt(0)
	v_mul_f32_e32 v19, v177, v20
	v_cndmask_b32_e64 v19, v19, -v19, vcc
	v_fmac_f32_e32 v19, v15, v176
	v_mov_b32_e32 v18, v220
	v_cndmask_b32_e64 v15, v15, v19, s[14:15]
	v_lshlrev_b32_e32 v18, 2, v18
	v_xor_b32_e32 v18, 64, v18
	ds_bpermute_b32 v20, v18, v16
	s_waitcnt vmcnt(5) lgkmcnt(0)
	v_mul_f32_e32 v19, v179, v20
	v_cndmask_b32_e64 v19, v19, -v19, vcc
	v_fmac_f32_e32 v19, v16, v178
	v_mov_b32_e32 v18, v220
	v_cndmask_b32_e64 v16, v16, v19, s[14:15]
	v_lshlrev_b32_e32 v18, 2, v18
	v_xor_b32_e32 v18, 64, v18
	ds_bpermute_b32 v20, v18, v17
	s_waitcnt vmcnt(4) lgkmcnt(0)
	v_mul_f32_e32 v19, v181, v20
	v_cndmask_b32_e64 v19, v19, -v19, vcc
	v_fmac_f32_e32 v19, v17, v180
	v_mov_b32_e32 v18, v220
	v_cndmask_b32_e64 v17, v17, v19, s[14:15]
	v_lshlrev_b32_e32 v18, 2, v18
	v_xor_b32_e32 v18, 64, v18
	ds_bpermute_b32 v20, v18, v10
	s_waitcnt vmcnt(3) lgkmcnt(0)
	v_mul_f32_e32 v19, v183, v20
	v_cndmask_b32_e64 v19, v19, -v19, vcc
	v_fmac_f32_e32 v19, v10, v182
	v_mov_b32_e32 v18, v220
	v_cndmask_b32_e64 v10, v10, v19, s[14:15]
	v_lshlrev_b32_e32 v18, 2, v18
	v_xor_b32_e32 v18, 64, v18
	ds_bpermute_b32 v20, v18, v11
	s_waitcnt vmcnt(2) lgkmcnt(0)
	v_mul_f32_e32 v19, v185, v20
	v_cndmask_b32_e64 v19, v19, -v19, vcc
	v_fmac_f32_e32 v19, v11, v184
	v_mov_b32_e32 v18, v220
	v_cndmask_b32_e64 v11, v11, v19, s[14:15]
	v_lshlrev_b32_e32 v18, 2, v18
	v_xor_b32_e32 v18, 64, v18
	ds_bpermute_b32 v20, v18, v12
	s_waitcnt vmcnt(1) lgkmcnt(0)
	v_mul_f32_e32 v19, v209, v20
	v_cndmask_b32_e64 v19, v19, -v19, vcc
	v_fmac_f32_e32 v19, v12, v208
	v_mov_b32_e32 v18, v220
	v_cndmask_b32_e64 v12, v12, v19, s[14:15]
	v_lshlrev_b32_e32 v18, 2, v18
	v_xor_b32_e32 v18, 64, v18
	ds_bpermute_b32 v20, v18, v13
	s_waitcnt vmcnt(0) lgkmcnt(0)
	v_mul_f32_e32 v19, v211, v20
	v_cndmask_b32_e64 v19, v19, -v19, vcc
	v_fmac_f32_e32 v19, v13, v210
	v_cndmask_b32_e64 v13, v13, v19, s[14:15]

; __device__ __forceinline__ unsigned cvt_pk_bf16(float lo, float hi) { const f32x2_ v = {lo, hi}; return __builtin_bit_cast(unsigned, __builtin_convertvector(v, bf16x2_)); }
;     __device__ __forceinline__ void operator()(const f32x4 (&acc)[2][2][4][2], const Unit& u, int wr, int wc, int fr, int fq) const {
;     ...
;                     const int row = row0 + ai * 128 + m * 16;
;                     float v[8];
;                     if (cg0 < 384) {
;                         const float rs = RSTD[row * 2];
; #pragma unroll
;                         for (int n = 0; n < 2; ++n)
; #pragma unroll
;                             for (int j = 0; j < 4; ++j) v[4 * n + j] = acc[ai][bj][m][n][j] * rs;
;     ...
;                         *(u32x4*)(MQ + (size_t)row * 384 + cg0 + 8 * fq) = w;
;                     } else {
;                         const float rs = RSTD[row * 2 + 1];
; #pragma unroll
;                         for (int n = 0; n < 2; ++n)
; #pragma unroll
;                             for (int j = 0; j < 4; ++j) v[4 * n + j] = acc[ai][bj][m][n][j] * rs;
;                         const int cp = cg0 - 384, hd = cp >> 7, d0 = cp & 127;
;                         u32x4 w; w.x = cvt_pk_bf16(v[0], v[1]); w.y = cvt_pk_bf16(v[2], v[3]); w.z = cvt_pk_bf16(v[4], v[5]); w.w = cvt_pk_bf16(v[6], v[7]);
;                         if (d0 < 64) *(u32x4*)(MK + (size_t)row * 384 + hd * 96 + d0 + 8 * fq) = w;
;                         else *(u32x4*)(MV + (size_t)row * 256 + hd * 64 + (d0 - 64) + 8 * fq) = w;
.LBB0_467:
	s_or_b64 exec, exec, s[2:3]
	v_mov_b32_e32 v63, v0
	v_lshl_add_u64 v[10:11], v[24:25], 0, v[62:63]
	global_store_dwordx4 v[10:11], v[18:21], off
	v_add_u32_e32 v14, 0xb0, v144
	v_lshlrev_b32_e32 v10, 1, v14
	v_ashrrev_i32_e32 v11, 31, v10
	v_lshl_add_u64 v[18:19], v[10:11], 2, s[24:25]
	s_and_saveexec_b64 s[0:1], s[12:13]
	s_xor_b64 s[0:1], exec, s[0:1]
	s_cbranch_execz .LBB0_473
	v_mov_b32_e32 v10, v237
	v_ashrrev_i32_e32 v15, 31, v14
	v_lshlrev_b32_e32 v12, 1, v154
	s_and_saveexec_b64 s[2:3], s[8:9]
	s_xor_b64 s[2:3], exec, s[2:3]
	s_cbranch_execz .LBB0_470
	v_lshlrev_b64 v[14:15], 9, v[14:15]
	v_lshl_add_u64 v[14:15], s[22:23], 0, v[14:15]
	s_lshl_b32 s8, s63, 1
	s_mov_b32 s9, s89
	v_lshl_add_u64 v[14:15], v[14:15], 0, s[8:9]
	v_mov_b32_e32 v13, v0
	s_movk_i32 s8, 0xff80
	v_lshl_add_u64 v[12:13], v[14:15], 0, v[12:13]
	s_mov_b32 s9, -1
	v_lshl_add_u64 v[16:17], v[12:13], 0, s[8:9]
.LBB0_470:
	s_andn2_saveexec_b64 s[2:3], s[2:3]
	v_mov_b64_e32 v[16:17], s[20:21]
	s_movk_i32 s8, 0x300
	v_mad_i64_i32 v[14:15], s[8:9], v14, s8, v[16:17]
	v_lshl_add_u64 v[14:15], s[88:89], 1, v[14:15]
	v_mov_b32_e32 v13, v0
	v_lshl_add_u64 v[16:17], v[14:15], 0, v[12:13]
	s_or_b64 exec, exec, s[2:3]
	v_pk_mul_f32 v[6:7], v[6:7], v[10:11] op_sel_hi:[1,0]
	v_pk_mul_f32 v[8:9], v[8:9], v[10:11] op_sel_hi:[1,0]
	v_pk_mul_f32 v[2:3], v[2:3], v[10:11] op_sel_hi:[1,0]
	v_pk_mul_f32 v[4:5], v[4:5], v[10:11] op_sel_hi:[1,0]
	v_cvt_pk_bf16_f32 v10, v6, v7
	v_cvt_pk_bf16_f32 v11, v8, v9
	v_cvt_pk_bf16_f32 v12, v2, v3
	v_cvt_pk_bf16_f32 v13, v4, v5
.LBB0_473:
	s_andn2_saveexec_b64 s[2:3], s[0:1]
	s_cbranch_execz .LBB0_296
	v_mov_b32_e32 v10, v236
	v_pk_mul_f32 v[6:7], v[6:7], v[10:11] op_sel_hi:[1,0]
	v_pk_mul_f32 v[8:9], v[8:9], v[10:11] op_sel_hi:[1,0]
	v_pk_mul_f32 v[2:3], v[2:3], v[10:11] op_sel_hi:[1,0]
	v_pk_mul_f32 v[4:5], v[4:5], v[10:11] op_sel_hi:[1,0]
	s_and_saveexec_b64 s[0:1], s[10:11]
	s_xor_b64 s[0:1], exec, s[0:1]
	s_andn2_saveexec_b64 s[10:11], s[0:1]
	s_cbranch_execz .LBB0_295
	v_mov_b32_e32 v11, v220
	v_cndmask_b32_e64 v10, v153, v39, s[6:7]
	v_lshlrev_b32_e32 v11, 2, v11
	v_xor_b32_e32 v11, 64, v11
	v_lshlrev_b32_e32 v13, 6, v10
	ds_bpermute_b32 v12, v11, v6
	global_load_dwordx2 v[174:175], v13, s[26:27]
	global_load_dwordx2 v[176:177], v13, s[26:27] offset:8
	global_load_dwordx2 v[178:179], v13, s[26:27] offset:16
	global_load_dwordx2 v[180:181], v13, s[26:27] offset:24
	global_load_dwordx2 v[182:183], v13, s[26:27] offset:32
	global_load_dwordx2 v[184:185], v13, s[26:27] offset:40
	global_load_dwordx2 v[208:209], v13, s[26:27] offset:48
	global_load_dwordx2 v[210:211], v13, s[26:27] offset:56
	s_movk_i32 s0, 0x7f50
	v_cmp_gt_i32_e64 s[8:9], s0, v144
	s_waitcnt vmcnt(7) lgkmcnt(0)
	v_mul_f32_e32 v11, v175, v12
	v_cndmask_b32_e64 v11, v11, -v11, vcc
	v_fmac_f32_e32 v11, v6, v174
	v_mov_b32_e32 v10, v220
	v_cndmask_b32_e64 v6, v6, v11, s[8:9]
	v_lshlrev_b32_e32 v10, 2, v10
	v_xor_b32_e32 v10, 64, v10
	ds_bpermute_b32 v12, v10, v7
	s_waitcnt vmcnt(6) lgkmcnt(0)
	v_mul_f32_e32 v11, v177, v12
	v_cndmask_b32_e64 v11, v11, -v11, vcc
	v_fmac_f32_e32 v11, v7, v176
	v_mov_b32_e32 v10, v220
	v_cndmask_b32_e64 v7, v7, v11, s[8:9]
	v_lshlrev_b32_e32 v10, 2, v10
	v_xor_b32_e32 v10, 64, v10
	ds_bpermute_b32 v12, v10, v8
	s_waitcnt vmcnt(5) lgkmcnt(0)
	v_mul_f32_e32 v11, v179, v12
	v_cndmask_b32_e64 v11, v11, -v11, vcc
	v_fmac_f32_e32 v11, v8, v178
	v_mov_b32_e32 v10, v220
	v_cndmask_b32_e64 v8, v8, v11, s[8:9]
	v_lshlrev_b32_e32 v10, 2, v10
	v_xor_b32_e32 v10, 64, v10
	ds_bpermute_b32 v12, v10, v9
	s_waitcnt vmcnt(4) lgkmcnt(0)
	v_mul_f32_e32 v11, v181, v12
	v_cndmask_b32_e64 v11, v11, -v11, vcc
	v_fmac_f32_e32 v11, v9, v180
	v_mov_b32_e32 v10, v220
	v_cndmask_b32_e64 v9, v9, v11, s[8:9]
	v_lshlrev_b32_e32 v10, 2, v10
	v_xor_b32_e32 v10, 64, v10
	ds_bpermute_b32 v12, v10, v2
	s_waitcnt vmcnt(3) lgkmcnt(0)
	v_mul_f32_e32 v11, v183, v12
	v_cndmask_b32_e64 v11, v11, -v11, vcc
	v_fmac_f32_e32 v11, v2, v182
	v_mov_b32_e32 v10, v220
	v_cndmask_b32_e64 v2, v2, v11, s[8:9]
	v_lshlrev_b32_e32 v10, 2, v10
	v_xor_b32_e32 v10, 64, v10
	ds_bpermute_b32 v12, v10, v3
	s_waitcnt vmcnt(2) lgkmcnt(0)
	v_mul_f32_e32 v11, v185, v12
	v_cndmask_b32_e64 v11, v11, -v11, vcc
	v_fmac_f32_e32 v11, v3, v184
	v_mov_b32_e32 v10, v220
	v_cndmask_b32_e64 v3, v3, v11, s[8:9]
	v_lshlrev_b32_e32 v10, 2, v10
	v_xor_b32_e32 v10, 64, v10
	ds_bpermute_b32 v12, v10, v4
	s_waitcnt vmcnt(1) lgkmcnt(0)
	v_mul_f32_e32 v11, v209, v12
	v_cndmask_b32_e64 v11, v11, -v11, vcc
	v_fmac_f32_e32 v11, v4, v208
	v_mov_b32_e32 v10, v220
	v_cndmask_b32_e64 v4, v4, v11, s[8:9]
	v_lshlrev_b32_e32 v10, 2, v10
	v_xor_b32_e32 v10, 64, v10
	ds_bpermute_b32 v12, v10, v5
	s_waitcnt vmcnt(0) lgkmcnt(0)
	v_mul_f32_e32 v11, v211, v12
	v_cndmask_b32_e64 v11, v11, -v11, vcc
	v_fmac_f32_e32 v11, v5, v210
	v_cndmask_b32_e64 v5, v5, v11, s[8:9]
	s_branch .LBB0_295
